# removed the provably redundant second s_waitcnt lgkmcnt(0) after s_setprio in each MMA phase of all six GEMM K-loops
# speedup vs baseline: 1.0088x; 1.0012x over previous
; #define PG8_STAGE(bufoff, gbase, voff) do { _Pragma("unroll") for (int _i = 0; _i < 2; ++_i) \
;         __builtin_amdgcn_global_load_lds((const unsigned*)((const char*)(gbase) + (voff)[_i]), (LAS unsigned*)(lds + (bufoff) + ldsw + _i * 8192), 16, 0, 0); } while (0)
; #define PG8_LDA(dst, b, h) do { _Pragma("unroll") for (int m = 0; m < 4; ++m) _Pragma("unroll") for (int k = 0; k < 2; ++k) dst[m][k] = *(const LAS bf16x8*)(lds + PG8_SA(b, h) + aoff + m * 2048 + k * 1024); } while (0)
; #define PG8_LDB(dst, b, h) do { _Pragma("unroll") for (int n = 0; n < 2; ++n) _Pragma("unroll") for (int k = 0; k < 2; ++k) dst[n][k] = *(const LAS bf16x8*)(lds + PG8_SB(b, h) + boff + n * 2048 + k * 1024); } while (0)
; #define PG8_MMA(ai, bj, At, Bt) do { __builtin_amdgcn_s_setprio(1); _Pragma("unroll") for (int m = 0; m < 4; ++m) _Pragma("unroll") for (int n = 0; n < 2; ++n) _Pragma("unroll") for (int k = 0; k < 2; ++k) \
;         acc[ai][bj][m][n] = __builtin_amdgcn_mfma_f32_16x16x32_bf16(Bt[n][k], At[m][k], acc[ai][bj][m][n], 0, 0, 0); __builtin_amdgcn_s_setprio(0); } while (0)
; #define PG8_WAIT_V(n) asm volatile("s_waitcnt vmcnt(" #n ")" ::: "memory")
; #define PG8_WAIT_L(n) asm volatile("s_waitcnt lgkmcnt(" #n ")" ::: "memory")
; #define PG8_BAR __builtin_amdgcn_s_barrier()
; #define PG8_SCHED __builtin_amdgcn_sched_barrier(0)
; template <class Epi>
; __device__ __forceinline__ void gemm_phase(LAS unsigned char* lds, const Gemm g, const StaticOrder& S, const Epi& E) {
;     ...
;             PG8_LDB(B0, 0, 0); PG8_SCHED; PG8_LDA(At, 0, 0); PG8_STAGE(PG8_SA(1, 1), a1 + hA, voffA);
;             PG8_WAIT_L(8); PG8_BAR; PG8_WAIT_L(0); PG8_MMA(0, 0, At, B0); PG8_BAR; PG8_SCHED;
;             PG8_LDB(B1, 0, 1); PG8_STAGE(PG8_SB(0, 0), b2, voffB);
;             PG8_BAR; PG8_WAIT_L(0); PG8_MMA(0, 1, At, B1); PG8_BAR;
;             PG8_LDA(At, 0, 1); PG8_STAGE(PG8_SA(0, 0), a2, voffA);
;             PG8_BAR; PG8_WAIT_L(0); PG8_MMA(1, 0, At, B0); PG8_BAR; PG8_SCHED;
;             PG8_STAGE(PG8_SB(0, 1), b2 + hB, voffB);
;             PG8_WAIT_V(6); PG8_BAR; PG8_MMA(1, 1, At, B1); PG8_BAR;
;             PG8_LDB(B0, 1, 0); PG8_SCHED; PG8_LDA(At, 1, 0); PG8_STAGE(PG8_SA(0, 1), a2 + hA, voffA);
.LBB0_63:
	s_add_i32 vcc_lo, s66, 2
	s_add_u32 s64, s62, 0x100
	s_addc_u32 s65, s63, 0
	s_add_i32 s22, 0, 0x10000
	v_add_u32_e32 v142, s22, v188
	ds_read_b128 v[130:133], v142
	ds_read_b128 v[134:137], v142 offset:1024
	ds_read_b128 v[138:141], v142 offset:2048
	ds_read_b128 v[142:145], v142 offset:3072
	s_cmp_eq_u32 s59, s66
	s_cselect_b32 s66, s44, s61
	s_cselect_b32 s69, s43, s65
	s_cselect_b32 s68, s42, s64
	s_cselect_b32 s67, s45, s97
	s_add_i32 m0, s52, 0xc000
	ds_read_b128 v[146:149], v189
	ds_read_b128 v[150:153], v189 offset:1024
	ds_read_b128 v[154:157], v189 offset:2048
	ds_read_b128 v[168:171], v189 offset:3072
	ds_read_b128 v[172:175], v189 offset:4096
	ds_read_b128 v[176:179], v189 offset:5120
	ds_read_b128 v[180:183], v189 offset:6144
	ds_read_b128 v[190:193], v189 offset:7168
	global_load_lds_dwordx4 v164, s[62:63]
	s_add_i32 m0, s52, 0xe000
	s_nop 0
	global_load_lds_dwordx4 v166, s[62:63]
	s_waitcnt lgkmcnt(8)
	s_barrier
	s_waitcnt lgkmcnt(0)
	s_setprio 1
	v_mfma_f32_16x16x32_bf16 v[126:129], v[130:133], v[146:149], v[126:129]
	v_mfma_f32_16x16x32_bf16 v[122:125], v[138:141], v[146:149], v[122:125]
	v_mfma_f32_16x16x32_bf16 v[110:113], v[130:133], v[154:157], v[110:113]
	v_mfma_f32_16x16x32_bf16 v[106:109], v[138:141], v[154:157], v[106:109]
	v_mfma_f32_16x16x32_bf16 v[94:97], v[130:133], v[172:175], v[94:97]
	v_mfma_f32_16x16x32_bf16 v[90:93], v[138:141], v[172:175], v[90:93]
	v_mfma_f32_16x16x32_bf16 v[78:81], v[130:133], v[180:183], v[78:81]
	v_mfma_f32_16x16x32_bf16 v[74:77], v[138:141], v[180:183], v[74:77]
	v_mfma_f32_16x16x32_bf16 v[126:129], v[134:137], v[150:153], v[126:129]
	v_mfma_f32_16x16x32_bf16 v[122:125], v[142:145], v[150:153], v[122:125]
	v_mfma_f32_16x16x32_bf16 v[110:113], v[134:137], v[168:171], v[110:113]
	v_mfma_f32_16x16x32_bf16 v[106:109], v[142:145], v[168:171], v[106:109]
	v_mfma_f32_16x16x32_bf16 v[94:97], v[134:137], v[176:179], v[94:97]
	v_mfma_f32_16x16x32_bf16 v[90:93], v[142:145], v[176:179], v[90:93]
	v_mfma_f32_16x16x32_bf16 v[78:81], v[134:137], v[190:193], v[78:81]
	v_mfma_f32_16x16x32_bf16 v[74:77], v[142:145], v[190:193], v[74:77]
	s_setprio 0
	s_barrier
	s_add_i32 s62, 0, 0x14000
	v_add_u32_e32 v184, s62, v188
	s_add_i32 s22, s22, s51
	ds_read_b128 v[202:205], v184
	ds_read_b128 v[206:209], v184 offset:1024
	ds_read_b128 v[210:213], v184 offset:2048
	ds_read_b128 v[214:217], v184 offset:3072
	s_mov_b32 m0, s22
	s_nop 0
	global_load_lds_dwordx4 v0, s[66:67]
	s_add_i32 m0, s22, 0x2000
	s_nop 0
	global_load_lds_dwordx4 v162, s[66:67]
	s_barrier
	s_waitcnt lgkmcnt(0)
	s_setprio 1
	v_mfma_f32_16x16x32_bf16 v[118:121], v[202:205], v[146:149], v[118:121]
	v_mfma_f32_16x16x32_bf16 v[114:117], v[210:213], v[146:149], v[114:117]
	v_mfma_f32_16x16x32_bf16 v[102:105], v[202:205], v[154:157], v[102:105]
	v_mfma_f32_16x16x32_bf16 v[98:101], v[210:213], v[154:157], v[98:101]
	v_mfma_f32_16x16x32_bf16 v[86:89], v[202:205], v[172:175], v[86:89]
	v_mfma_f32_16x16x32_bf16 v[82:85], v[210:213], v[172:175], v[82:85]
	v_mfma_f32_16x16x32_bf16 v[70:73], v[202:205], v[180:183], v[70:73]
	v_mfma_f32_16x16x32_bf16 v[66:69], v[210:213], v[180:183], v[66:69]
	v_mfma_f32_16x16x32_bf16 v[118:121], v[206:209], v[150:153], v[118:121]
	v_mfma_f32_16x16x32_bf16 v[114:117], v[214:217], v[150:153], v[114:117]
	v_mfma_f32_16x16x32_bf16 v[102:105], v[206:209], v[168:171], v[102:105]
	v_mfma_f32_16x16x32_bf16 v[98:101], v[214:217], v[168:171], v[98:101]
	v_mfma_f32_16x16x32_bf16 v[86:89], v[206:209], v[176:179], v[86:89]
	v_mfma_f32_16x16x32_bf16 v[82:85], v[214:217], v[176:179], v[82:85]
	v_mfma_f32_16x16x32_bf16 v[70:73], v[206:209], v[190:193], v[70:73]
	v_mfma_f32_16x16x32_bf16 v[66:69], v[214:217], v[190:193], v[66:69]
	s_setprio 0
	s_mov_b32 m0, s52
	s_barrier
	ds_read_b128 v[146:149], v189 offset:16384
	ds_read_b128 v[150:153], v189 offset:17408
	ds_read_b128 v[154:157], v189 offset:18432
	ds_read_b128 v[168:171], v189 offset:19456
	ds_read_b128 v[172:175], v189 offset:20480
	ds_read_b128 v[176:179], v189 offset:21504
	ds_read_b128 v[180:183], v189 offset:22528
	ds_read_b128 v[190:193], v189 offset:23552
	global_load_lds_dwordx4 v158, s[68:69]
	s_mov_b32 m0, s53
	s_nop 0
	global_load_lds_dwordx4 v160, s[68:69]
	s_barrier
	s_waitcnt lgkmcnt(0)
	s_setprio 1
	v_mfma_f32_16x16x32_bf16 v[62:65], v[130:133], v[146:149], v[62:65]
	v_mfma_f32_16x16x32_bf16 v[58:61], v[138:141], v[146:149], v[58:61]
	v_mfma_f32_16x16x32_bf16 v[46:49], v[130:133], v[154:157], v[46:49]
	v_mfma_f32_16x16x32_bf16 v[42:45], v[138:141], v[154:157], v[42:45]
	v_mfma_f32_16x16x32_bf16 v[30:33], v[130:133], v[172:175], v[30:33]
	v_mfma_f32_16x16x32_bf16 v[26:29], v[138:141], v[172:175], v[26:29]
	v_mfma_f32_16x16x32_bf16 v[14:17], v[130:133], v[180:183], v[14:17]
	v_mfma_f32_16x16x32_bf16 v[10:13], v[138:141], v[180:183], v[10:13]
	v_mfma_f32_16x16x32_bf16 v[62:65], v[134:137], v[150:153], v[62:65]
	v_mfma_f32_16x16x32_bf16 v[58:61], v[142:145], v[150:153], v[58:61]
	v_mfma_f32_16x16x32_bf16 v[46:49], v[134:137], v[168:171], v[46:49]
	v_mfma_f32_16x16x32_bf16 v[42:45], v[142:145], v[168:171], v[42:45]
	v_mfma_f32_16x16x32_bf16 v[30:33], v[134:137], v[176:179], v[30:33]
	v_mfma_f32_16x16x32_bf16 v[26:29], v[142:145], v[176:179], v[26:29]
	v_mfma_f32_16x16x32_bf16 v[14:17], v[134:137], v[190:193], v[14:17]
	v_mfma_f32_16x16x32_bf16 v[10:13], v[142:145], v[190:193], v[10:13]
	s_setprio 0
	s_barrier
	s_add_u32 s22, s66, 0xb0000
	s_addc_u32 s23, s67, 0
	s_add_i32 s62, s62, s51
	s_mov_b32 m0, s62
	s_nop 0
	global_load_lds_dwordx4 v0, s[22:23]
	s_add_i32 m0, s62, 0x2000
	s_nop 0
	global_load_lds_dwordx4 v162, s[22:23]
	s_waitcnt vmcnt(6)
	s_barrier
; #define PG8_STAGE(bufoff, gbase, voff) do { _Pragma("unroll") for (int _i = 0; _i < 2; ++_i) \
;         __builtin_amdgcn_global_load_lds((const unsigned*)((const char*)(gbase) + (voff)[_i]), (LAS unsigned*)(lds + (bufoff) + ldsw + _i * 8192), 16, 0, 0); } while (0)
; #define PG8_LDA(dst, b, h) do { _Pragma("unroll") for (int m = 0; m < 4; ++m) _Pragma("unroll") for (int k = 0; k < 2; ++k) dst[m][k] = *(const LAS bf16x8*)(lds + PG8_SA(b, h) + aoff + m * 2048 + k * 1024); } while (0)
; #define PG8_LDB(dst, b, h) do { _Pragma("unroll") for (int n = 0; n < 2; ++n) _Pragma("unroll") for (int k = 0; k < 2; ++k) dst[n][k] = *(const LAS bf16x8*)(lds + PG8_SB(b, h) + boff + n * 2048 + k * 1024); } while (0)
; #define PG8_MMA(ai, bj, At, Bt) do { __builtin_amdgcn_s_setprio(1); _Pragma("unroll") for (int m = 0; m < 4; ++m) _Pragma("unroll") for (int n = 0; n < 2; ++n) _Pragma("unroll") for (int k = 0; k < 2; ++k) \
;         acc[ai][bj][m][n] = __builtin_amdgcn_mfma_f32_16x16x32_bf16(Bt[n][k], At[m][k], acc[ai][bj][m][n], 0, 0, 0); __builtin_amdgcn_s_setprio(0); } while (0)
; #define PG8_WAIT_V(n) asm volatile("s_waitcnt vmcnt(" #n ")" ::: "memory")
; #define PG8_WAIT_L(n) asm volatile("s_waitcnt lgkmcnt(" #n ")" ::: "memory")
; #define PG8_BAR __builtin_amdgcn_s_barrier()
; #define PG8_SCHED __builtin_amdgcn_sched_barrier(0)
; template <class Epi>
; __device__ __forceinline__ void gemm_phase(LAS unsigned char* lds, const Gemm g, const StaticOrder& S, const Epi& E) {
;     ...
;             PG8_WAIT_V(6); PG8_BAR; PG8_MMA(1, 1, At, B1); PG8_BAR;
;             PG8_LDB(B0, 1, 0); PG8_SCHED; PG8_LDA(At, 1, 0); PG8_STAGE(PG8_SA(0, 1), a2 + hA, voffA);
;             PG8_WAIT_L(8); PG8_BAR; PG8_WAIT_L(0); PG8_MMA(0, 0, At, B0); PG8_BAR; PG8_SCHED;
;             PG8_LDB(B1, 1, 1); PG8_STAGE(PG8_SB(1, 0), b3, voffB);
;             PG8_BAR; PG8_WAIT_L(0); PG8_MMA(0, 1, At, B1); PG8_BAR;
;             PG8_LDA(At, 1, 1); PG8_STAGE(PG8_SA(1, 0), a3, voffA);
;             PG8_BAR; PG8_WAIT_L(0); PG8_MMA(1, 0, At, B0); PG8_BAR; PG8_SCHED;
;             PG8_STAGE(PG8_SB(1, 1), b3 + hB, voffB);
;             PG8_WAIT_V(6); PG8_BAR; PG8_MMA(1, 1, At, B1); PG8_BAR;
	s_setprio 1
	v_mfma_f32_16x16x32_bf16 v[54:57], v[202:205], v[146:149], v[54:57]
	v_mfma_f32_16x16x32_bf16 v[50:53], v[210:213], v[146:149], v[50:53]
	v_mfma_f32_16x16x32_bf16 v[38:41], v[202:205], v[154:157], v[38:41]
	v_mfma_f32_16x16x32_bf16 v[34:37], v[210:213], v[154:157], v[34:37]
	v_mfma_f32_16x16x32_bf16 v[22:25], v[202:205], v[172:175], v[22:25]
	v_mfma_f32_16x16x32_bf16 v[18:21], v[210:213], v[172:175], v[18:21]
	v_mfma_f32_16x16x32_bf16 v[6:9], v[202:205], v[180:183], v[6:9]
	v_mfma_f32_16x16x32_bf16 v[2:5], v[210:213], v[180:183], v[2:5]
	v_mfma_f32_16x16x32_bf16 v[54:57], v[206:209], v[150:153], v[54:57]
	v_mfma_f32_16x16x32_bf16 v[50:53], v[214:217], v[150:153], v[50:53]
	v_mfma_f32_16x16x32_bf16 v[38:41], v[206:209], v[168:171], v[38:41]
	v_mfma_f32_16x16x32_bf16 v[34:37], v[214:217], v[168:171], v[34:37]
	v_mfma_f32_16x16x32_bf16 v[22:25], v[206:209], v[176:179], v[22:25]
	v_mfma_f32_16x16x32_bf16 v[18:21], v[214:217], v[176:179], v[18:21]
	v_mfma_f32_16x16x32_bf16 v[6:9], v[206:209], v[190:193], v[6:9]
	v_mfma_f32_16x16x32_bf16 v[2:5], v[214:217], v[190:193], v[2:5]
	s_setprio 0
	s_add_i32 s62, 0, 0x18000
	v_add_u32_e32 v142, s62, v188
	s_barrier
	ds_read_b128 v[130:133], v142
	ds_read_b128 v[134:137], v142 offset:1024
	ds_read_b128 v[138:141], v142 offset:2048
	ds_read_b128 v[142:145], v142 offset:3072
	s_add_u32 s22, s68, 0xb0000
	s_addc_u32 s23, s69, 0
	s_mov_b32 m0, s56
	ds_read_b128 v[146:149], v189 offset:32768
	ds_read_b128 v[150:153], v189 offset:33792
	ds_read_b128 v[154:157], v189 offset:34816
	ds_read_b128 v[168:171], v189 offset:35840
	ds_read_b128 v[172:175], v189 offset:36864
	ds_read_b128 v[176:179], v189 offset:37888
	ds_read_b128 v[180:183], v189 offset:38912
	ds_read_b128 v[190:193], v189 offset:39936
	global_load_lds_dwordx4 v158, s[22:23]
	s_mov_b32 m0, s57
	s_nop 0
	global_load_lds_dwordx4 v160, s[22:23]
	s_waitcnt lgkmcnt(8)
	s_barrier
	s_waitcnt lgkmcnt(0)
	s_setprio 1
	v_mfma_f32_16x16x32_bf16 v[126:129], v[130:133], v[146:149], v[126:129]
	v_mfma_f32_16x16x32_bf16 v[122:125], v[138:141], v[146:149], v[122:125]
	v_mfma_f32_16x16x32_bf16 v[110:113], v[130:133], v[154:157], v[110:113]
	v_mfma_f32_16x16x32_bf16 v[106:109], v[138:141], v[154:157], v[106:109]
	v_mfma_f32_16x16x32_bf16 v[94:97], v[130:133], v[172:175], v[94:97]
	v_mfma_f32_16x16x32_bf16 v[90:93], v[138:141], v[172:175], v[90:93]
	v_mfma_f32_16x16x32_bf16 v[78:81], v[130:133], v[180:183], v[78:81]
	v_mfma_f32_16x16x32_bf16 v[74:77], v[138:141], v[180:183], v[74:77]
	v_mfma_f32_16x16x32_bf16 v[126:129], v[134:137], v[150:153], v[126:129]
	v_mfma_f32_16x16x32_bf16 v[122:125], v[142:145], v[150:153], v[122:125]
	v_mfma_f32_16x16x32_bf16 v[110:113], v[134:137], v[168:171], v[110:113]
	v_mfma_f32_16x16x32_bf16 v[106:109], v[142:145], v[168:171], v[106:109]
	v_mfma_f32_16x16x32_bf16 v[94:97], v[134:137], v[176:179], v[94:97]
	v_mfma_f32_16x16x32_bf16 v[90:93], v[142:145], v[176:179], v[90:93]
	v_mfma_f32_16x16x32_bf16 v[78:81], v[134:137], v[190:193], v[78:81]
	v_mfma_f32_16x16x32_bf16 v[74:77], v[142:145], v[190:193], v[74:77]
	s_setprio 0
	s_barrier
	s_add_i32 s63, 0, 0x1c000
	s_add_i32 s22, s62, s51
	v_add_u32_e32 v214, s63, v188
	s_mov_b32 m0, s22
	ds_read_b128 v[202:205], v214
	ds_read_b128 v[206:209], v214 offset:1024
	ds_read_b128 v[210:213], v214 offset:2048
	ds_read_b128 v[214:217], v214 offset:3072
	s_add_u32 s100, s66, 0x80
	s_addc_u32 s101, s67, 0
	global_load_lds_dwordx4 v0, s[100:101]
	s_add_i32 m0, s22, 0x2000
	s_nop 0
	global_load_lds_dwordx4 v162, s[100:101]
	s_barrier
	s_waitcnt lgkmcnt(0)
	s_setprio 1
	v_mfma_f32_16x16x32_bf16 v[118:121], v[202:205], v[146:149], v[118:121]
	v_mfma_f32_16x16x32_bf16 v[114:117], v[210:213], v[146:149], v[114:117]
	v_mfma_f32_16x16x32_bf16 v[102:105], v[202:205], v[154:157], v[102:105]
	v_mfma_f32_16x16x32_bf16 v[98:101], v[210:213], v[154:157], v[98:101]
	v_mfma_f32_16x16x32_bf16 v[86:89], v[202:205], v[172:175], v[86:89]
	v_mfma_f32_16x16x32_bf16 v[82:85], v[210:213], v[172:175], v[82:85]
	v_mfma_f32_16x16x32_bf16 v[70:73], v[202:205], v[180:183], v[70:73]
	v_mfma_f32_16x16x32_bf16 v[66:69], v[210:213], v[180:183], v[66:69]
	v_mfma_f32_16x16x32_bf16 v[118:121], v[206:209], v[150:153], v[118:121]
	v_mfma_f32_16x16x32_bf16 v[114:117], v[214:217], v[150:153], v[114:117]
	v_mfma_f32_16x16x32_bf16 v[102:105], v[206:209], v[168:171], v[102:105]
	v_mfma_f32_16x16x32_bf16 v[98:101], v[214:217], v[168:171], v[98:101]
	v_mfma_f32_16x16x32_bf16 v[86:89], v[206:209], v[176:179], v[86:89]
	v_mfma_f32_16x16x32_bf16 v[82:85], v[214:217], v[176:179], v[82:85]
	v_mfma_f32_16x16x32_bf16 v[70:73], v[206:209], v[190:193], v[70:73]
	v_mfma_f32_16x16x32_bf16 v[66:69], v[214:217], v[190:193], v[66:69]
	s_setprio 0
	s_mov_b32 m0, s54
	s_barrier
	ds_read_b128 v[146:149], v189 offset:49152
	ds_read_b128 v[150:153], v189 offset:50176
	ds_read_b128 v[154:157], v189 offset:51200
	ds_read_b128 v[168:171], v189 offset:52224
	ds_read_b128 v[172:175], v189 offset:53248
	ds_read_b128 v[176:179], v189 offset:54272
	ds_read_b128 v[180:183], v189 offset:55296
	ds_read_b128 v[190:193], v189 offset:56320
	s_add_u32 s100, s68, 0x80
	s_addc_u32 s101, s69, 0
	global_load_lds_dwordx4 v158, s[100:101]
	s_mov_b32 m0, s55
	s_nop 0
	global_load_lds_dwordx4 v160, s[100:101]
	s_barrier
; #define PG8_STAGE(bufoff, gbase, voff) do { _Pragma("unroll") for (int _i = 0; _i < 2; ++_i) \
;         __builtin_amdgcn_global_load_lds((const unsigned*)((const char*)(gbase) + (voff)[_i]), (LAS unsigned*)(lds + (bufoff) + ldsw + _i * 8192), 16, 0, 0); } while (0)
; #define PG8_LDA(dst, b, h) do { _Pragma("unroll") for (int m = 0; m < 4; ++m) _Pragma("unroll") for (int k = 0; k < 2; ++k) dst[m][k] = *(const LAS bf16x8*)(lds + PG8_SA(b, h) + aoff + m * 2048 + k * 1024); } while (0)
; #define PG8_LDB(dst, b, h) do { _Pragma("unroll") for (int n = 0; n < 2; ++n) _Pragma("unroll") for (int k = 0; k < 2; ++k) dst[n][k] = *(const LAS bf16x8*)(lds + PG8_SB(b, h) + boff + n * 2048 + k * 1024); } while (0)
; #define PG8_WAIT_V(n) asm volatile("s_waitcnt vmcnt(" #n ")" ::: "memory")
; #define PG8_WAIT_L(n) asm volatile("s_waitcnt lgkmcnt(" #n ")" ::: "memory")
; #define PG8_BAR __builtin_amdgcn_s_barrier()
; template <class Epi>
; __device__ __forceinline__ void gemm_phase(LAS unsigned char* lds, const Gemm g, const StaticOrder& S, const Epi& E) {
;     ...
;             PG8_WAIT_V(6); PG8_BAR; PG8_MMA(1, 1, At, B1); PG8_BAR;
;             PG8_LDB(B0, 1, 0); PG8_SCHED; PG8_LDA(At, 1, 0); PG8_STAGE(PG8_SA(0, 1), a2 + hA, voffA);
;             PG8_WAIT_L(8); PG8_BAR; PG8_WAIT_L(0); PG8_MMA(0, 0, At, B0); PG8_BAR; PG8_SCHED;
;             PG8_LDB(B1, 1, 1); PG8_STAGE(PG8_SB(1, 0), b3, voffB);
;             PG8_BAR; PG8_WAIT_L(0); PG8_MMA(0, 1, At, B1); PG8_BAR;
;             PG8_LDA(At, 1, 1); PG8_STAGE(PG8_SA(1, 0), a3, voffA);
;             PG8_BAR; PG8_WAIT_L(0); PG8_MMA(1, 0, At, B0); PG8_BAR; PG8_SCHED;
;             PG8_STAGE(PG8_SB(1, 1), b3 + hB, voffB);
;             PG8_WAIT_V(6); PG8_BAR; PG8_MMA(1, 1, At, B1); PG8_BAR;
;         }
;     __device__ __forceinline__ void operator()(const Acc& acc, const Unit& u, int wr, int wc, int fr, int fq) const {
;     ...
;         if (u.split) {
;             float* pt = part + (size_t)(u.split - 1) * 256 * DM;
; #pragma unroll
;             for (int ai = 0; ai < 2; ++ai)
; #pragma unroll
;                 for (int m = 0; m < 4; ++m)
; #pragma unroll
;                     for (int bj = 0; bj < 2; ++bj)
; #pragma unroll
;                         for (int n = 0; n < 2; ++n) *(f32x4*)(pt + (size_t)(wr * 64 + fr + ai * 128 + m * 16) * DM + col0 + bj * 128 + n * 4) = acc[ai][bj][m][n] * sc;
;             return; }
	s_waitcnt lgkmcnt(0)
	s_setprio 1
	v_mfma_f32_16x16x32_bf16 v[62:65], v[130:133], v[146:149], v[62:65]
	v_mfma_f32_16x16x32_bf16 v[58:61], v[138:141], v[146:149], v[58:61]
	v_mfma_f32_16x16x32_bf16 v[46:49], v[130:133], v[154:157], v[46:49]
	v_mfma_f32_16x16x32_bf16 v[42:45], v[138:141], v[154:157], v[42:45]
	v_mfma_f32_16x16x32_bf16 v[30:33], v[130:133], v[172:175], v[30:33]
	v_mfma_f32_16x16x32_bf16 v[26:29], v[138:141], v[172:175], v[26:29]
	v_mfma_f32_16x16x32_bf16 v[14:17], v[130:133], v[180:183], v[14:17]
	v_mfma_f32_16x16x32_bf16 v[10:13], v[138:141], v[180:183], v[10:13]
	v_mfma_f32_16x16x32_bf16 v[62:65], v[134:137], v[150:153], v[62:65]
	v_mfma_f32_16x16x32_bf16 v[58:61], v[142:145], v[150:153], v[58:61]
	v_mfma_f32_16x16x32_bf16 v[46:49], v[134:137], v[168:171], v[46:49]
	v_mfma_f32_16x16x32_bf16 v[42:45], v[142:145], v[168:171], v[42:45]
	v_mfma_f32_16x16x32_bf16 v[30:33], v[134:137], v[176:179], v[30:33]
	v_mfma_f32_16x16x32_bf16 v[26:29], v[142:145], v[176:179], v[26:29]
	v_mfma_f32_16x16x32_bf16 v[14:17], v[134:137], v[190:193], v[14:17]
	v_mfma_f32_16x16x32_bf16 v[10:13], v[142:145], v[190:193], v[10:13]
	s_setprio 0
	s_barrier
	s_add_u32 s22, s66, 0xb0080
	s_addc_u32 s23, s67, 0
	s_add_i32 s62, s63, s51
	s_mov_b32 m0, s62
	s_nop 0
	global_load_lds_dwordx4 v0, s[22:23]
	s_add_i32 m0, s62, 0x2000
	s_nop 0
	global_load_lds_dwordx4 v162, s[22:23]
	s_waitcnt vmcnt(6)
	s_barrier
	s_setprio 1
	v_mfma_f32_16x16x32_bf16 v[54:57], v[202:205], v[146:149], v[54:57]
	v_mfma_f32_16x16x32_bf16 v[50:53], v[210:213], v[146:149], v[50:53]
	v_mfma_f32_16x16x32_bf16 v[38:41], v[202:205], v[154:157], v[38:41]
	v_mfma_f32_16x16x32_bf16 v[34:37], v[210:213], v[154:157], v[34:37]
	v_mfma_f32_16x16x32_bf16 v[22:25], v[202:205], v[172:175], v[22:25]
	v_mfma_f32_16x16x32_bf16 v[18:21], v[210:213], v[172:175], v[18:21]
	v_mfma_f32_16x16x32_bf16 v[6:9], v[202:205], v[180:183], v[6:9]
	v_mfma_f32_16x16x32_bf16 v[2:5], v[210:213], v[180:183], v[2:5]
	v_mfma_f32_16x16x32_bf16 v[54:57], v[206:209], v[150:153], v[54:57]
	v_mfma_f32_16x16x32_bf16 v[50:53], v[214:217], v[150:153], v[50:53]
	v_mfma_f32_16x16x32_bf16 v[38:41], v[206:209], v[168:171], v[38:41]
	v_mfma_f32_16x16x32_bf16 v[34:37], v[214:217], v[168:171], v[34:37]
	v_mfma_f32_16x16x32_bf16 v[22:25], v[206:209], v[176:179], v[22:25]
	v_mfma_f32_16x16x32_bf16 v[18:21], v[214:217], v[176:179], v[18:21]
	v_mfma_f32_16x16x32_bf16 v[6:9], v[206:209], v[190:193], v[6:9]
	v_mfma_f32_16x16x32_bf16 v[2:5], v[214:217], v[190:193], v[2:5]
	s_setprio 0
	s_add_u32 s61, s61, 0x100
	s_addc_u32 s97, s97, 0
	s_cmp_ge_i32 vcc_lo, s33
	s_mov_b64 s[62:63], s[64:65]
	s_mov_b32 s66, vcc_lo
	s_barrier
	s_cbranch_scc0 .LBB0_63
	s_lshl_b32 s22, s46, 8
	v_mov_b32_e32 v133, v186
	v_mov_b32_e32 v132, v187
	s_or_b32 s22, s22, s76
	s_cmp_lg_u32 s60, 0
	v_lshl_add_u32 v168, v132, 3, s22
	v_add_u32_e32 v130, s75, v133
	v_ashrrev_i32_e32 v169, 31, v168
	s_cbranch_scc0 .LBB0_66
	s_ashr_i32 s61, s60, 31
	s_lshl_b64 s[22:23], s[60:61], 20
	s_add_u32 s22, s15, s22
	s_addc_u32 s23, s18, s23
	v_ashrrev_i32_e32 v131, 31, v130
	v_lshl_add_u64 v[134:135], v[168:169], 2, s[22:23]
	v_lshlrev_b64 v[136:137], 12, v[130:131]
	s_mov_b32 s22, 0xfff00000
	v_lshl_add_u64 v[134:135], v[134:135], 0, v[136:137]
	s_mov_b32 s23, -1
	v_lshl_add_u64 v[136:137], v[134:135], 0, s[22:23]
	v_add_co_u32_e32 v138, vcc, s0, v134
	s_mov_b32 s22, 0xfff10000
	s_nop 0
	v_addc_co_u32_e32 v139, vcc, -1, v135, vcc
	s_mov_b32 s23, -1
	global_store_dwordx4 v[138:139], v[126:129], off
	global_store_dwordx4 v[136:137], v[122:125], off offset:16
	global_store_dwordx4 v[136:137], v[118:121], off offset:512
	global_store_dwordx4 v[136:137], v[114:117], off offset:528
	v_lshl_add_u64 v[136:137], v[134:135], 0, s[22:23]
	v_add_co_u32_e32 v138, vcc, s1, v134
	s_mov_b32 s22, 0xfff20000
	s_nop 0
	v_addc_co_u32_e32 v139, vcc, -1, v135, vcc
	s_mov_b32 s23, -1
	global_store_dwordx4 v[138:139], v[110:113], off
	global_store_dwordx4 v[136:137], v[106:109], off offset:16
	global_store_dwordx4 v[136:137], v[102:105], off offset:512
	global_store_dwordx4 v[136:137], v[98:101], off offset:528
	v_lshl_add_u64 v[136:137], v[134:135], 0, s[22:23]
	s_mov_b32 s22, 0xfff20000
	v_add_co_u32_e32 v138, vcc, s22, v134
	s_mov_b32 s22, 0xfff30000
	s_nop 0
	v_addc_co_u32_e32 v139, vcc, -1, v135, vcc
	s_mov_b32 s23, -1
	global_store_dwordx4 v[138:139], v[94:97], off
	global_store_dwordx4 v[136:137], v[90:93], off offset:16
	global_store_dwordx4 v[136:137], v[86:89], off offset:512
	global_store_dwordx4 v[136:137], v[82:85], off offset:528
	v_lshl_add_u64 v[136:137], v[134:135], 0, s[22:23]
	s_mov_b32 s22, 0xfff30000
	v_add_co_u32_e32 v138, vcc, s22, v134
	s_mov_b32 s22, 0xfff80000
	s_nop 0
	v_addc_co_u32_e32 v139, vcc, -1, v135, vcc
	s_mov_b32 s23, -1
	global_store_dwordx4 v[138:139], v[78:81], off
	global_store_dwordx4 v[136:137], v[74:77], off offset:16
	global_store_dwordx4 v[136:137], v[70:73], off offset:512
	global_store_dwordx4 v[136:137], v[66:69], off offset:528
	v_lshl_add_u64 v[136:137], v[134:135], 0, s[22:23]
	s_mov_b32 s22, 0xfff80000
	v_add_co_u32_e32 v138, vcc, s22, v134
	s_mov_b32 s22, 0xfff90000
	s_nop 0
	v_addc_co_u32_e32 v139, vcc, -1, v135, vcc
	s_mov_b32 s23, -1
	global_store_dwordx4 v[138:139], v[62:65], off
	global_store_dwordx4 v[136:137], v[58:61], off offset:16
	global_store_dwordx4 v[136:137], v[54:57], off offset:512
	global_store_dwordx4 v[136:137], v[50:53], off offset:528
	v_lshl_add_u64 v[136:137], v[134:135], 0, s[22:23]
	s_mov_b32 s22, 0xfff90000
	v_add_co_u32_e32 v138, vcc, s22, v134
	s_mov_b32 s22, 0xfffa0000
	s_nop 0
	v_addc_co_u32_e32 v139, vcc, -1, v135, vcc
	s_mov_b32 s23, -1
	global_store_dwordx4 v[138:139], v[46:49], off
	global_store_dwordx4 v[136:137], v[42:45], off offset:16
	global_store_dwordx4 v[136:137], v[38:41], off offset:512
	global_store_dwordx4 v[136:137], v[34:37], off offset:528
	v_lshl_add_u64 v[136:137], v[134:135], 0, s[22:23]
	s_mov_b32 s22, 0xfffa0000
	v_add_co_u32_e32 v138, vcc, s22, v134
	s_mov_b32 s22, 0xfffb0000
	s_nop 0
	v_addc_co_u32_e32 v139, vcc, -1, v135, vcc
	s_mov_b32 s23, -1
	global_store_dwordx4 v[138:139], v[30:33], off
	global_store_dwordx4 v[136:137], v[26:29], off offset:16
	global_store_dwordx4 v[136:137], v[22:25], off offset:512
	global_store_dwordx4 v[136:137], v[18:21], off offset:528
	v_lshl_add_u64 v[136:137], v[134:135], 0, s[22:23]
	v_add_co_u32_e32 v134, vcc, 0xfffb0000, v134
	s_nop 1
	v_addc_co_u32_e32 v135, vcc, -1, v135, vcc
	global_store_dwordx4 v[134:135], v[14:17], off
	global_store_dwordx4 v[136:137], v[10:13], off offset:16
	global_store_dwordx4 v[136:137], v[6:9], off offset:512
	global_store_dwordx4 v[136:137], v[2:5], off offset:528
	s_cbranch_execnz .LBB0_47
	s_branch .LBB0_67

; #define PG8_STAGE(bufoff, gbase, voff) do { _Pragma("unroll") for (int _i = 0; _i < 2; ++_i) \
;         __builtin_amdgcn_global_load_lds((const unsigned*)((const char*)(gbase) + (voff)[_i]), (LAS unsigned*)(lds + (bufoff) + ldsw + _i * 8192), 16, 0, 0); } while (0)
; #define PG8_LDA(dst, b, h) do { _Pragma("unroll") for (int m = 0; m < 4; ++m) _Pragma("unroll") for (int k = 0; k < 2; ++k) dst[m][k] = *(const LAS bf16x8*)(lds + PG8_SA(b, h) + aoff + m * 2048 + k * 1024); } while (0)
; #define PG8_LDB(dst, b, h) do { _Pragma("unroll") for (int n = 0; n < 2; ++n) _Pragma("unroll") for (int k = 0; k < 2; ++k) dst[n][k] = *(const LAS bf16x8*)(lds + PG8_SB(b, h) + boff + n * 2048 + k * 1024); } while (0)
; #define PG8_MMA(ai, bj, At, Bt) do { __builtin_amdgcn_s_setprio(1); _Pragma("unroll") for (int m = 0; m < 4; ++m) _Pragma("unroll") for (int n = 0; n < 2; ++n) _Pragma("unroll") for (int k = 0; k < 2; ++k) \
;         acc[ai][bj][m][n] = __builtin_amdgcn_mfma_f32_16x16x32_bf16(Bt[n][k], At[m][k], acc[ai][bj][m][n], 0, 0, 0); __builtin_amdgcn_s_setprio(0); } while (0)
; #define PG8_WAIT_V(n) asm volatile("s_waitcnt vmcnt(" #n ")" ::: "memory")
; #define PG8_WAIT_L(n) asm volatile("s_waitcnt lgkmcnt(" #n ")" ::: "memory")
; #define PG8_BAR __builtin_amdgcn_s_barrier()
; #define PG8_SCHED __builtin_amdgcn_sched_barrier(0)
; template <class Epi>
; __device__ __forceinline__ void gemm_phase(LAS unsigned char* lds, const Gemm g, const StaticOrder& S, const Epi& E) {
;     ...
;             PG8_LDB(B0, 0, 0); PG8_SCHED; PG8_LDA(At, 0, 0); PG8_STAGE(PG8_SA(1, 1), a1 + hA, voffA);
;             PG8_WAIT_L(8); PG8_BAR; PG8_WAIT_L(0); PG8_MMA(0, 0, At, B0); PG8_BAR; PG8_SCHED;
;             PG8_LDB(B1, 0, 1); PG8_STAGE(PG8_SB(0, 0), b2, voffB);
;             PG8_BAR; PG8_WAIT_L(0); PG8_MMA(0, 1, At, B1); PG8_BAR;
;             PG8_LDA(At, 0, 1); PG8_STAGE(PG8_SA(0, 0), a2, voffA);
;             PG8_BAR; PG8_WAIT_L(0); PG8_MMA(1, 0, At, B0); PG8_BAR; PG8_SCHED;
;             PG8_STAGE(PG8_SB(0, 1), b2 + hB, voffB);
;             PG8_WAIT_V(6); PG8_BAR; PG8_MMA(1, 1, At, B1); PG8_BAR;
;             PG8_LDB(B0, 1, 0); PG8_SCHED; PG8_LDA(At, 1, 0); PG8_STAGE(PG8_SA(0, 1), a2 + hA, voffA);
.LBB0_104:
	s_add_u32 s22, s62, 0xfffc0080
	s_addc_u32 s23, s63, -1
	s_add_i32 s75, 0, 0x10000
	v_add_u32_e32 v151, s75, v147
	ds_read_b128 v[156:159], v151
	ds_read_b128 v[160:163], v151 offset:1024
	ds_read_b128 v[164:167], v151 offset:2048
	ds_read_b128 v[168:171], v151 offset:3072
	s_cmp_eq_u32 s74, 12
	s_cselect_b32 s67, s43, s23
	s_cselect_b32 s66, s61, s22
	s_cselect_b32 s65, s41, s71
	s_cselect_b32 s64, s69, s70
	s_add_i32 m0, s50, 0xc000
	ds_read_b128 v[172:175], v149
	ds_read_b128 v[176:179], v149 offset:1024
	ds_read_b128 v[180:183], v149 offset:2048
	ds_read_b128 v[184:187], v149 offset:3072
	ds_read_b128 v[188:191], v149 offset:4096
	ds_read_b128 v[192:195], v149 offset:5120
	ds_read_b128 v[202:205], v149 offset:6144
	ds_read_b128 v[206:209], v149 offset:7168
	global_load_lds_dwordx4 v138, s[62:63]
	s_add_i32 m0, s50, 0xe000
	s_nop 0
	global_load_lds_dwordx4 v140, s[62:63]
	s_waitcnt lgkmcnt(8)
	s_barrier
	s_waitcnt lgkmcnt(0)
	s_setprio 1
	v_mfma_f32_16x16x32_bf16 v[126:129], v[156:159], v[172:175], v[126:129]
	v_mfma_f32_16x16x32_bf16 v[118:121], v[164:167], v[172:175], v[118:121]
	v_mfma_f32_16x16x32_bf16 v[110:113], v[156:159], v[180:183], v[110:113]
	v_mfma_f32_16x16x32_bf16 v[102:105], v[164:167], v[180:183], v[102:105]
	v_mfma_f32_16x16x32_bf16 v[94:97], v[156:159], v[188:191], v[94:97]
	v_mfma_f32_16x16x32_bf16 v[86:89], v[164:167], v[188:191], v[86:89]
	v_mfma_f32_16x16x32_bf16 v[78:81], v[156:159], v[202:205], v[78:81]
	v_mfma_f32_16x16x32_bf16 v[70:73], v[164:167], v[202:205], v[70:73]
	v_mfma_f32_16x16x32_bf16 v[126:129], v[160:163], v[176:179], v[126:129]
	v_mfma_f32_16x16x32_bf16 v[118:121], v[168:171], v[176:179], v[118:121]
	v_mfma_f32_16x16x32_bf16 v[110:113], v[160:163], v[184:187], v[110:113]
	v_mfma_f32_16x16x32_bf16 v[102:105], v[168:171], v[184:187], v[102:105]
	v_mfma_f32_16x16x32_bf16 v[94:97], v[160:163], v[192:195], v[94:97]
	v_mfma_f32_16x16x32_bf16 v[86:89], v[168:171], v[192:195], v[86:89]
	v_mfma_f32_16x16x32_bf16 v[78:81], v[160:163], v[206:209], v[78:81]
	v_mfma_f32_16x16x32_bf16 v[70:73], v[168:171], v[206:209], v[70:73]
	s_setprio 0
	s_barrier
	s_add_i32 s76, 0, 0x14000
	s_add_i32 s22, s75, s48
	v_add_u32_e32 v151, s76, v147
	s_mov_b32 m0, s22
	ds_read_b128 v[210:213], v151
	ds_read_b128 v[214:217], v151 offset:1024
	ds_read_b128 v[218:221], v151 offset:2048
	ds_read_b128 v[222:225], v151 offset:3072
	global_load_lds_dwordx4 v0, s[64:65]
	s_add_i32 m0, s22, 0x2000
	s_nop 0
	global_load_lds_dwordx4 v134, s[64:65]
	s_barrier
	s_waitcnt lgkmcnt(0)
	s_setprio 1
	v_mfma_f32_16x16x32_bf16 v[122:125], v[210:213], v[172:175], v[122:125]
	v_mfma_f32_16x16x32_bf16 v[114:117], v[218:221], v[172:175], v[114:117]
	v_mfma_f32_16x16x32_bf16 v[106:109], v[210:213], v[180:183], v[106:109]
	v_mfma_f32_16x16x32_bf16 v[98:101], v[218:221], v[180:183], v[98:101]
	v_mfma_f32_16x16x32_bf16 v[90:93], v[210:213], v[188:191], v[90:93]
	v_mfma_f32_16x16x32_bf16 v[82:85], v[218:221], v[188:191], v[82:85]
	v_mfma_f32_16x16x32_bf16 v[74:77], v[210:213], v[202:205], v[74:77]
	v_mfma_f32_16x16x32_bf16 v[66:69], v[218:221], v[202:205], v[66:69]
	v_mfma_f32_16x16x32_bf16 v[122:125], v[214:217], v[176:179], v[122:125]
	v_mfma_f32_16x16x32_bf16 v[114:117], v[222:225], v[176:179], v[114:117]
	v_mfma_f32_16x16x32_bf16 v[106:109], v[214:217], v[184:187], v[106:109]
	v_mfma_f32_16x16x32_bf16 v[98:101], v[222:225], v[184:187], v[98:101]
	v_mfma_f32_16x16x32_bf16 v[90:93], v[214:217], v[192:195], v[90:93]
	v_mfma_f32_16x16x32_bf16 v[82:85], v[222:225], v[192:195], v[82:85]
	v_mfma_f32_16x16x32_bf16 v[74:77], v[214:217], v[206:209], v[74:77]
	v_mfma_f32_16x16x32_bf16 v[66:69], v[222:225], v[206:209], v[66:69]
	s_setprio 0
	s_mov_b32 m0, s50
	s_barrier
	ds_read_b128 v[172:175], v149 offset:16384
	ds_read_b128 v[176:179], v149 offset:17408
	ds_read_b128 v[180:183], v149 offset:18432
	ds_read_b128 v[184:187], v149 offset:19456
	ds_read_b128 v[188:191], v149 offset:20480
	ds_read_b128 v[192:195], v149 offset:21504
	ds_read_b128 v[202:205], v149 offset:22528
	ds_read_b128 v[206:209], v149 offset:23552
	global_load_lds_dwordx4 v130, s[66:67]
	s_mov_b32 m0, s51
	s_nop 0
	global_load_lds_dwordx4 v132, s[66:67]
	s_barrier
	s_waitcnt lgkmcnt(0)
	s_setprio 1
	v_mfma_f32_16x16x32_bf16 v[62:65], v[156:159], v[172:175], v[62:65]
	v_mfma_f32_16x16x32_bf16 v[54:57], v[164:167], v[172:175], v[54:57]
	v_mfma_f32_16x16x32_bf16 v[46:49], v[156:159], v[180:183], v[46:49]
	v_mfma_f32_16x16x32_bf16 v[38:41], v[164:167], v[180:183], v[38:41]
	v_mfma_f32_16x16x32_bf16 v[30:33], v[156:159], v[188:191], v[30:33]
	v_mfma_f32_16x16x32_bf16 v[22:25], v[164:167], v[188:191], v[22:25]
	v_mfma_f32_16x16x32_bf16 v[14:17], v[156:159], v[202:205], v[14:17]
	v_mfma_f32_16x16x32_bf16 v[6:9], v[164:167], v[202:205], v[6:9]
	v_mfma_f32_16x16x32_bf16 v[62:65], v[160:163], v[176:179], v[62:65]
	v_mfma_f32_16x16x32_bf16 v[54:57], v[168:171], v[176:179], v[54:57]
	v_mfma_f32_16x16x32_bf16 v[46:49], v[160:163], v[184:187], v[46:49]
	v_mfma_f32_16x16x32_bf16 v[38:41], v[168:171], v[184:187], v[38:41]
	v_mfma_f32_16x16x32_bf16 v[30:33], v[160:163], v[192:195], v[30:33]
	v_mfma_f32_16x16x32_bf16 v[22:25], v[168:171], v[192:195], v[22:25]
	v_mfma_f32_16x16x32_bf16 v[14:17], v[160:163], v[206:209], v[14:17]
	v_mfma_f32_16x16x32_bf16 v[6:9], v[168:171], v[206:209], v[6:9]
	s_setprio 0
	s_barrier
	s_add_u32 s22, s64, 0x40000
	s_addc_u32 s23, s65, 0
	s_add_i32 s75, s76, s48
	s_mov_b32 m0, s75
	s_nop 0
	global_load_lds_dwordx4 v0, s[22:23]
	s_add_i32 m0, s75, 0x2000
	s_nop 0
	global_load_lds_dwordx4 v134, s[22:23]
	s_waitcnt vmcnt(6)
	s_barrier
; #define PG8_STAGE(bufoff, gbase, voff) do { _Pragma("unroll") for (int _i = 0; _i < 2; ++_i) \
;         __builtin_amdgcn_global_load_lds((const unsigned*)((const char*)(gbase) + (voff)[_i]), (LAS unsigned*)(lds + (bufoff) + ldsw + _i * 8192), 16, 0, 0); } while (0)
; #define PG8_LDA(dst, b, h) do { _Pragma("unroll") for (int m = 0; m < 4; ++m) _Pragma("unroll") for (int k = 0; k < 2; ++k) dst[m][k] = *(const LAS bf16x8*)(lds + PG8_SA(b, h) + aoff + m * 2048 + k * 1024); } while (0)
; #define PG8_LDB(dst, b, h) do { _Pragma("unroll") for (int n = 0; n < 2; ++n) _Pragma("unroll") for (int k = 0; k < 2; ++k) dst[n][k] = *(const LAS bf16x8*)(lds + PG8_SB(b, h) + boff + n * 2048 + k * 1024); } while (0)
; #define PG8_MMA(ai, bj, At, Bt) do { __builtin_amdgcn_s_setprio(1); _Pragma("unroll") for (int m = 0; m < 4; ++m) _Pragma("unroll") for (int n = 0; n < 2; ++n) _Pragma("unroll") for (int k = 0; k < 2; ++k) \
;         acc[ai][bj][m][n] = __builtin_amdgcn_mfma_f32_16x16x32_bf16(Bt[n][k], At[m][k], acc[ai][bj][m][n], 0, 0, 0); __builtin_amdgcn_s_setprio(0); } while (0)
; #define PG8_WAIT_V(n) asm volatile("s_waitcnt vmcnt(" #n ")" ::: "memory")
; #define PG8_WAIT_L(n) asm volatile("s_waitcnt lgkmcnt(" #n ")" ::: "memory")
; #define PG8_BAR __builtin_amdgcn_s_barrier()
; #define PG8_SCHED __builtin_amdgcn_sched_barrier(0)
; template <class Epi>
; __device__ __forceinline__ void gemm_phase(LAS unsigned char* lds, const Gemm g, const StaticOrder& S, const Epi& E) {
;     ...
;             PG8_WAIT_V(6); PG8_BAR; PG8_MMA(1, 1, At, B1); PG8_BAR;
;             PG8_LDB(B0, 1, 0); PG8_SCHED; PG8_LDA(At, 1, 0); PG8_STAGE(PG8_SA(0, 1), a2 + hA, voffA);
;             PG8_WAIT_L(8); PG8_BAR; PG8_WAIT_L(0); PG8_MMA(0, 0, At, B0); PG8_BAR; PG8_SCHED;
;             PG8_LDB(B1, 1, 1); PG8_STAGE(PG8_SB(1, 0), b3, voffB);
;             PG8_BAR; PG8_WAIT_L(0); PG8_MMA(0, 1, At, B1); PG8_BAR;
;             PG8_LDA(At, 1, 1); PG8_STAGE(PG8_SA(1, 0), a3, voffA);
;             PG8_BAR; PG8_WAIT_L(0); PG8_MMA(1, 0, At, B0); PG8_BAR; PG8_SCHED;
	s_setprio 1
	v_mfma_f32_16x16x32_bf16 v[58:61], v[210:213], v[172:175], v[58:61]
	v_mfma_f32_16x16x32_bf16 v[50:53], v[218:221], v[172:175], v[50:53]
	v_mfma_f32_16x16x32_bf16 v[42:45], v[210:213], v[180:183], v[42:45]
	v_mfma_f32_16x16x32_bf16 v[34:37], v[218:221], v[180:183], v[34:37]
	v_mfma_f32_16x16x32_bf16 v[26:29], v[210:213], v[188:191], v[26:29]
	v_mfma_f32_16x16x32_bf16 v[18:21], v[218:221], v[188:191], v[18:21]
	v_mfma_f32_16x16x32_bf16 v[10:13], v[210:213], v[202:205], v[10:13]
	v_mfma_f32_16x16x32_bf16 v[2:5], v[218:221], v[202:205], v[2:5]
	v_mfma_f32_16x16x32_bf16 v[58:61], v[214:217], v[176:179], v[58:61]
	v_mfma_f32_16x16x32_bf16 v[50:53], v[222:225], v[176:179], v[50:53]
	v_mfma_f32_16x16x32_bf16 v[42:45], v[214:217], v[184:187], v[42:45]
	v_mfma_f32_16x16x32_bf16 v[34:37], v[222:225], v[184:187], v[34:37]
	v_mfma_f32_16x16x32_bf16 v[26:29], v[214:217], v[192:195], v[26:29]
	v_mfma_f32_16x16x32_bf16 v[18:21], v[222:225], v[192:195], v[18:21]
	v_mfma_f32_16x16x32_bf16 v[10:13], v[214:217], v[206:209], v[10:13]
	v_mfma_f32_16x16x32_bf16 v[2:5], v[222:225], v[206:209], v[2:5]
	s_setprio 0
	s_add_i32 s75, 0, 0x18000
	v_add_u32_e32 v151, s75, v147
	s_barrier
	ds_read_b128 v[156:159], v151
	ds_read_b128 v[160:163], v151 offset:1024
	ds_read_b128 v[164:167], v151 offset:2048
	ds_read_b128 v[168:171], v151 offset:3072
	s_add_u32 s22, s66, 0x40000
	s_addc_u32 s23, s67, 0
	s_mov_b32 m0, s53
	ds_read_b128 v[172:175], v149 offset:32768
	ds_read_b128 v[176:179], v149 offset:33792
	ds_read_b128 v[180:183], v149 offset:34816
	ds_read_b128 v[184:187], v149 offset:35840
	ds_read_b128 v[188:191], v149 offset:36864
	ds_read_b128 v[192:195], v149 offset:37888
	ds_read_b128 v[202:205], v149 offset:38912
	ds_read_b128 v[206:209], v149 offset:39936
	global_load_lds_dwordx4 v130, s[22:23]
	s_mov_b32 m0, s54
	s_nop 0
	global_load_lds_dwordx4 v132, s[22:23]
	s_waitcnt lgkmcnt(8)
	s_barrier
	s_waitcnt lgkmcnt(0)
	s_setprio 1
	v_mfma_f32_16x16x32_bf16 v[126:129], v[156:159], v[172:175], v[126:129]
	v_mfma_f32_16x16x32_bf16 v[118:121], v[164:167], v[172:175], v[118:121]
	v_mfma_f32_16x16x32_bf16 v[110:113], v[156:159], v[180:183], v[110:113]
	v_mfma_f32_16x16x32_bf16 v[102:105], v[164:167], v[180:183], v[102:105]
	v_mfma_f32_16x16x32_bf16 v[94:97], v[156:159], v[188:191], v[94:97]
	v_mfma_f32_16x16x32_bf16 v[86:89], v[164:167], v[188:191], v[86:89]
	v_mfma_f32_16x16x32_bf16 v[78:81], v[156:159], v[202:205], v[78:81]
	v_mfma_f32_16x16x32_bf16 v[70:73], v[164:167], v[202:205], v[70:73]
	v_mfma_f32_16x16x32_bf16 v[126:129], v[160:163], v[176:179], v[126:129]
	v_mfma_f32_16x16x32_bf16 v[118:121], v[168:171], v[176:179], v[118:121]
	v_mfma_f32_16x16x32_bf16 v[110:113], v[160:163], v[184:187], v[110:113]
	v_mfma_f32_16x16x32_bf16 v[102:105], v[168:171], v[184:187], v[102:105]
	v_mfma_f32_16x16x32_bf16 v[94:97], v[160:163], v[192:195], v[94:97]
	v_mfma_f32_16x16x32_bf16 v[86:89], v[168:171], v[192:195], v[86:89]
	v_mfma_f32_16x16x32_bf16 v[78:81], v[160:163], v[206:209], v[78:81]
	v_mfma_f32_16x16x32_bf16 v[70:73], v[168:171], v[206:209], v[70:73]
	s_setprio 0
	s_barrier
	s_add_i32 s22, s75, s48
	v_add_u32_e32 v151, 0x1c000, v147
	s_add_u32 s100, s64, 0x80
	s_addc_u32 s101, s65, 0
	s_mov_b32 m0, s22
	ds_read_b128 v[210:213], v151
	ds_read_b128 v[214:217], v151 offset:1024
	ds_read_b128 v[218:221], v151 offset:2048
	ds_read_b128 v[222:225], v151 offset:3072
	global_load_lds_dwordx4 v0, s[100:101]
	s_add_i32 m0, s22, 0x2000
	s_nop 0
	global_load_lds_dwordx4 v134, s[100:101]
	s_barrier
	s_waitcnt lgkmcnt(0)
	s_setprio 1
	v_mfma_f32_16x16x32_bf16 v[122:125], v[210:213], v[172:175], v[122:125]
	v_mfma_f32_16x16x32_bf16 v[114:117], v[218:221], v[172:175], v[114:117]
	v_mfma_f32_16x16x32_bf16 v[106:109], v[210:213], v[180:183], v[106:109]
	v_mfma_f32_16x16x32_bf16 v[98:101], v[218:221], v[180:183], v[98:101]
	v_mfma_f32_16x16x32_bf16 v[90:93], v[210:213], v[188:191], v[90:93]
	v_mfma_f32_16x16x32_bf16 v[82:85], v[218:221], v[188:191], v[82:85]
	v_mfma_f32_16x16x32_bf16 v[74:77], v[210:213], v[202:205], v[74:77]
	v_mfma_f32_16x16x32_bf16 v[66:69], v[218:221], v[202:205], v[66:69]
	v_mfma_f32_16x16x32_bf16 v[122:125], v[214:217], v[176:179], v[122:125]
	v_mfma_f32_16x16x32_bf16 v[114:117], v[222:225], v[176:179], v[114:117]
	v_mfma_f32_16x16x32_bf16 v[106:109], v[214:217], v[184:187], v[106:109]
	v_mfma_f32_16x16x32_bf16 v[98:101], v[222:225], v[184:187], v[98:101]
	v_mfma_f32_16x16x32_bf16 v[90:93], v[214:217], v[192:195], v[90:93]
	v_mfma_f32_16x16x32_bf16 v[82:85], v[222:225], v[192:195], v[82:85]
	v_mfma_f32_16x16x32_bf16 v[74:77], v[214:217], v[206:209], v[74:77]
	v_mfma_f32_16x16x32_bf16 v[66:69], v[222:225], v[206:209], v[66:69]
	s_setprio 0
	s_mov_b32 m0, s56
	s_add_u32 s100, s66, 0x80
	s_addc_u32 s101, s67, 0
	s_barrier
	ds_read_b128 v[172:175], v149 offset:49152
	ds_read_b128 v[176:179], v149 offset:50176
	ds_read_b128 v[180:183], v149 offset:51200
	ds_read_b128 v[184:187], v149 offset:52224
	ds_read_b128 v[188:191], v149 offset:53248
	ds_read_b128 v[192:195], v149 offset:54272
	ds_read_b128 v[202:205], v149 offset:55296
	ds_read_b128 v[206:209], v149 offset:56320
	global_load_lds_dwordx4 v130, s[100:101]
	s_mov_b32 m0, s57
	s_nop 0
	global_load_lds_dwordx4 v132, s[100:101]
	s_barrier
; __device__ __forceinline__ float siluf_(float x) { return x * sigmoidf_(x); }
; #define PG8_STAGE(bufoff, gbase, voff) do { _Pragma("unroll") for (int _i = 0; _i < 2; ++_i) \
;         __builtin_amdgcn_global_load_lds((const unsigned*)((const char*)(gbase) + (voff)[_i]), (LAS unsigned*)(lds + (bufoff) + ldsw + _i * 8192), 16, 0, 0); } while (0)
; #define PG8_LDA(dst, b, h) do { _Pragma("unroll") for (int m = 0; m < 4; ++m) _Pragma("unroll") for (int k = 0; k < 2; ++k) dst[m][k] = *(const LAS bf16x8*)(lds + PG8_SA(b, h) + aoff + m * 2048 + k * 1024); } while (0)
; #define PG8_MMA(ai, bj, At, Bt) do { __builtin_amdgcn_s_setprio(1); _Pragma("unroll") for (int m = 0; m < 4; ++m) _Pragma("unroll") for (int n = 0; n < 2; ++n) _Pragma("unroll") for (int k = 0; k < 2; ++k) \
;         acc[ai][bj][m][n] = __builtin_amdgcn_mfma_f32_16x16x32_bf16(Bt[n][k], At[m][k], acc[ai][bj][m][n], 0, 0, 0); __builtin_amdgcn_s_setprio(0); } while (0)
; #define PG8_WAIT_V(n) asm volatile("s_waitcnt vmcnt(" #n ")" ::: "memory")
; template <class Epi>
; __device__ __forceinline__ void gemm_phase(LAS unsigned char* lds, const Gemm g, const StaticOrder& S, const Epi& E) {
;     ...
;             PG8_BAR; PG8_WAIT_L(0); PG8_MMA(0, 1, At, B1); PG8_BAR;
;             PG8_LDA(At, 1, 1); PG8_STAGE(PG8_SA(1, 0), a3, voffA);
;             PG8_BAR; PG8_WAIT_L(0); PG8_MMA(1, 0, At, B0); PG8_BAR; PG8_SCHED;
;             PG8_STAGE(PG8_SB(1, 1), b3 + hB, voffB);
;             PG8_WAIT_V(6); PG8_BAR; PG8_MMA(1, 1, At, B1); PG8_BAR;
;         }
;     __device__ __forceinline__ void operator()(const Acc& acc, const Unit& u, int wr, int wc, int fr, int fq, const RsPre& pr) const {
;         asm volatile("" : "+v"(fr), "+v"(fq));
;         const int row0 = u.pm * 256 + wr * 64 + fr, col0 = u.pn * 128 + wc * 32 + 8 * fq;
;         const float (&rs)[2][4] = pr.rs;
; #pragma unroll
;         for (int ai = 0; ai < 2; ++ai)
; #pragma unroll
;             for (int m = 0; m < 4; ++m) { f32x4 o[2];
; #pragma unroll
;                 for (int n = 0; n < 2; ++n) { const f32x4 a1 = acc[ai][0][m][n] * rs[ai][m], a3 = acc[ai][1][m][n] * rs[ai][m];
;                     o[n] = (f32x4){siluf_(a1[0]) * a3[0], siluf_(a1[1]) * a3[1], siluf_(a1[2]) * a3[2], siluf_(a1[3]) * a3[3]}; }
;                 *(u32x4*)(ff + (size_t)(row0 + ai * 128 + m * 16) * DFF + col0) = pack8(o[0], o[1]); }
	s_waitcnt lgkmcnt(0)
	s_setprio 1
	v_mfma_f32_16x16x32_bf16 v[62:65], v[156:159], v[172:175], v[62:65]
	v_mfma_f32_16x16x32_bf16 v[54:57], v[164:167], v[172:175], v[54:57]
	v_mfma_f32_16x16x32_bf16 v[46:49], v[156:159], v[180:183], v[46:49]
	v_mfma_f32_16x16x32_bf16 v[38:41], v[164:167], v[180:183], v[38:41]
	v_mfma_f32_16x16x32_bf16 v[30:33], v[156:159], v[188:191], v[30:33]
	v_mfma_f32_16x16x32_bf16 v[22:25], v[164:167], v[188:191], v[22:25]
	v_mfma_f32_16x16x32_bf16 v[14:17], v[156:159], v[202:205], v[14:17]
	v_mfma_f32_16x16x32_bf16 v[6:9], v[164:167], v[202:205], v[6:9]
	v_mfma_f32_16x16x32_bf16 v[62:65], v[160:163], v[176:179], v[62:65]
	v_mfma_f32_16x16x32_bf16 v[54:57], v[168:171], v[176:179], v[54:57]
	v_mfma_f32_16x16x32_bf16 v[46:49], v[160:163], v[184:187], v[46:49]
	v_mfma_f32_16x16x32_bf16 v[38:41], v[168:171], v[184:187], v[38:41]
	v_mfma_f32_16x16x32_bf16 v[30:33], v[160:163], v[192:195], v[30:33]
	v_mfma_f32_16x16x32_bf16 v[22:25], v[168:171], v[192:195], v[22:25]
	v_mfma_f32_16x16x32_bf16 v[14:17], v[160:163], v[206:209], v[14:17]
	v_mfma_f32_16x16x32_bf16 v[6:9], v[168:171], v[206:209], v[6:9]
	s_setprio 0
	s_barrier
	s_add_u32 s22, s64, 0x40080
	s_addc_u32 s23, s65, 0
	s_add_i32 s64, s48, 0x1c000
	s_mov_b32 m0, s64
	s_nop 0
	global_load_lds_dwordx4 v0, s[22:23]
	s_add_i32 m0, s64, 0x2000
	s_nop 0
	global_load_lds_dwordx4 v134, s[22:23]
	s_waitcnt vmcnt(6)
	s_barrier
	s_setprio 1
	v_mfma_f32_16x16x32_bf16 v[58:61], v[210:213], v[172:175], v[58:61]
	v_mfma_f32_16x16x32_bf16 v[50:53], v[218:221], v[172:175], v[50:53]
	v_mfma_f32_16x16x32_bf16 v[42:45], v[210:213], v[180:183], v[42:45]
	v_mfma_f32_16x16x32_bf16 v[34:37], v[218:221], v[180:183], v[34:37]
	v_mfma_f32_16x16x32_bf16 v[26:29], v[210:213], v[188:191], v[26:29]
	v_mfma_f32_16x16x32_bf16 v[18:21], v[218:221], v[188:191], v[18:21]
	v_mfma_f32_16x16x32_bf16 v[10:13], v[210:213], v[202:205], v[10:13]
	v_mfma_f32_16x16x32_bf16 v[2:5], v[218:221], v[202:205], v[2:5]
	v_mfma_f32_16x16x32_bf16 v[58:61], v[214:217], v[176:179], v[58:61]
	v_mfma_f32_16x16x32_bf16 v[50:53], v[222:225], v[176:179], v[50:53]
	v_mfma_f32_16x16x32_bf16 v[42:45], v[214:217], v[184:187], v[42:45]
	v_mfma_f32_16x16x32_bf16 v[34:37], v[222:225], v[184:187], v[34:37]
	v_mfma_f32_16x16x32_bf16 v[26:29], v[214:217], v[192:195], v[26:29]
	v_mfma_f32_16x16x32_bf16 v[18:21], v[222:225], v[192:195], v[18:21]
	v_mfma_f32_16x16x32_bf16 v[10:13], v[214:217], v[206:209], v[10:13]
	v_mfma_f32_16x16x32_bf16 v[2:5], v[222:225], v[206:209], v[2:5]
	s_setprio 0
	s_add_i32 s74, s74, 2
	s_add_u32 s62, s62, 0x100
	s_addc_u32 s63, s63, 0
	s_add_u32 s70, s70, 0x100
	s_addc_u32 s71, s71, 0
	s_cmp_gt_u32 s74, 13
	s_barrier
	s_cbranch_scc0 .LBB0_104
	v_mov_b32_e32 v151, v137
	v_mov_b32_e32 v153, v143
	s_lshl_b32 s22, s60, 8
	s_add_i32 s22, s22, s49
	v_add_u32_e32 v151, s22, v151
	s_lshl_b32 s22, s33, 7
	s_or_b32 s22, s22, s55
	s_waitcnt vmcnt(0)
	v_pk_mul_f32 v[126:127], v[154:155], v[126:127] op_sel_hi:[0,1]
	v_lshl_add_u32 v156, v153, 3, s22
	v_mul_f32_e32 v153, 0xbfb8aa3b, v126
	v_exp_f32_e32 v153, v153
	v_pk_mul_f32 v[128:129], v[154:155], v[128:129] op_sel_hi:[0,1]
	v_pk_mul_f32 v[122:123], v[154:155], v[122:123] op_sel_hi:[0,1]
	v_pk_mul_f32 v[124:125], v[154:155], v[124:125] op_sel_hi:[0,1]
	v_add_f32_e32 v153, 1.0, v153
	v_rcp_f32_e32 v158, v153
	v_mul_f32_e32 v153, 0xbfb8aa3b, v127
	v_exp_f32_e32 v153, v153
	v_pk_mul_f32 v[118:119], v[154:155], v[118:119] op_sel_hi:[0,1]
	v_pk_mul_f32 v[120:121], v[154:155], v[120:121] op_sel_hi:[0,1]
	v_pk_mul_f32 v[114:115], v[154:155], v[114:115] op_sel_hi:[0,1]
	v_add_f32_e32 v153, 1.0, v153
	v_rcp_f32_e32 v159, v153
	v_pk_mul_f32 v[116:117], v[154:155], v[116:117] op_sel_hi:[0,1]
	s_movk_i32 s0, 0x1600
	v_pk_mul_f32 v[126:127], v[126:127], v[158:159]
	v_pk_mul_f32 v[110:111], v[152:153], v[110:111] op_sel_hi:[0,1]
	v_pk_mul_f32 v[122:123], v[126:127], v[122:123]
	v_mul_f32_e32 v126, 0xbfb8aa3b, v128
	v_mul_f32_e32 v127, 0xbfb8aa3b, v129
	v_exp_f32_e32 v126, v126
	v_exp_f32_e32 v127, v127
	v_pk_mul_f32 v[112:113], v[152:153], v[112:113] op_sel_hi:[0,1]
	v_pk_mul_f32 v[106:107], v[152:153], v[106:107] op_sel_hi:[0,1]
	v_add_f32_e32 v126, 1.0, v126
	v_add_f32_e32 v127, 1.0, v127
	v_rcp_f32_e32 v126, v126
	v_rcp_f32_e32 v127, v127
	v_pk_mul_f32 v[108:109], v[152:153], v[108:109] op_sel_hi:[0,1]
	v_pk_mul_f32 v[102:103], v[152:153], v[102:103] op_sel_hi:[0,1]
	v_pk_mul_f32 v[104:105], v[152:153], v[104:105] op_sel_hi:[0,1]
	v_pk_mul_f32 v[126:127], v[128:129], v[126:127]
	v_pk_mul_f32 v[98:99], v[152:153], v[98:99] op_sel_hi:[0,1]
	v_pk_mul_f32 v[124:125], v[126:127], v[124:125]
	v_mul_f32_e32 v126, 0xbfb8aa3b, v118
	v_mul_f32_e32 v127, 0xbfb8aa3b, v119
	v_exp_f32_e32 v126, v126
	v_exp_f32_e32 v127, v127
	v_pk_mul_f32 v[100:101], v[152:153], v[100:101] op_sel_hi:[0,1]
	v_pk_mul_f32 v[94:95], v[150:151], v[94:95] op_sel_hi:[0,1]
	v_add_f32_e32 v126, 1.0, v126
	v_add_f32_e32 v127, 1.0, v127
	v_rcp_f32_e32 v126, v126
	v_rcp_f32_e32 v127, v127
	v_pk_mul_f32 v[96:97], v[150:151], v[96:97] op_sel_hi:[0,1]
	v_pk_mul_f32 v[90:91], v[150:151], v[90:91] op_sel_hi:[0,1]
	v_pk_mul_f32 v[92:93], v[150:151], v[92:93] op_sel_hi:[0,1]
	v_pk_mul_f32 v[118:119], v[118:119], v[126:127]
	v_pk_mul_f32 v[86:87], v[150:151], v[86:87] op_sel_hi:[0,1]
	v_pk_mul_f32 v[114:115], v[118:119], v[114:115]
	v_mul_f32_e32 v118, 0xbfb8aa3b, v120
	v_mul_f32_e32 v119, 0xbfb8aa3b, v121
	v_exp_f32_e32 v118, v118
	v_exp_f32_e32 v119, v119
	v_pk_mul_f32 v[88:89], v[150:151], v[88:89] op_sel_hi:[0,1]
	v_pk_mul_f32 v[82:83], v[150:151], v[82:83] op_sel_hi:[0,1]
	v_add_f32_e32 v118, 1.0, v118
	v_add_f32_e32 v119, 1.0, v119
; __device__ __forceinline__ float siluf_(float x) { return x * sigmoidf_(x); }
; __device__ __forceinline__ u32x4 pack8(const f32x4 a, const f32x4 b) { u32x4 w; w.x = cvt_pk_bf16(a[0], a[1]); w.y = cvt_pk_bf16(a[2], a[3]); w.z = cvt_pk_bf16(b[0], b[1]); w.w = cvt_pk_bf16(b[2], b[3]); return w; }
;     __device__ __forceinline__ void operator()(const Acc& acc, const Unit& u, int wr, int wc, int fr, int fq, const RsPre& pr) const {
;         asm volatile("" : "+v"(fr), "+v"(fq));
;         const int row0 = u.pm * 256 + wr * 64 + fr, col0 = u.pn * 128 + wc * 32 + 8 * fq;
;         const float (&rs)[2][4] = pr.rs;
; #pragma unroll
;         for (int ai = 0; ai < 2; ++ai)
; #pragma unroll
;             for (int m = 0; m < 4; ++m) { f32x4 o[2];
; #pragma unroll
;                 for (int n = 0; n < 2; ++n) { const f32x4 a1 = acc[ai][0][m][n] * rs[ai][m], a3 = acc[ai][1][m][n] * rs[ai][m];
;                     o[n] = (f32x4){siluf_(a1[0]) * a3[0], siluf_(a1[1]) * a3[1], siluf_(a1[2]) * a3[2], siluf_(a1[3]) * a3[3]}; }
;                 *(u32x4*)(ff + (size_t)(row0 + ai * 128 + m * 16) * DFF + col0) = pack8(o[0], o[1]); }
	v_rcp_f32_e32 v118, v118
	v_rcp_f32_e32 v119, v119
	v_pk_mul_f32 v[84:85], v[150:151], v[84:85] op_sel_hi:[0,1]
	v_pk_mul_f32 v[78:79], v[148:149], v[78:79] op_sel_hi:[0,1]
	v_pk_mul_f32 v[80:81], v[148:149], v[80:81] op_sel_hi:[0,1]
	v_pk_mul_f32 v[118:119], v[120:121], v[118:119]
	v_cvt_pk_bf16_f32 v120, v114, v115
	v_pk_mul_f32 v[116:117], v[118:119], v[116:117]
	v_cvt_pk_bf16_f32 v118, v122, v123
	v_cvt_pk_bf16_f32 v121, v116, v117
	v_lshlrev_b32_e32 v116, 1, v156
	v_mad_u32_u24 v114, v151, s0, v116
	v_cvt_pk_bf16_f32 v119, v124, v125
	global_store_dwordx4 v114, v[118:121], s[20:21]
	v_pk_mul_f32 v[74:75], v[148:149], v[74:75] op_sel_hi:[0,1]
	v_pk_mul_f32 v[76:77], v[148:149], v[76:77] op_sel_hi:[0,1]
	v_mul_f32_e32 v118, 0xbfb8aa3b, v110
	v_mul_f32_e32 v119, 0xbfb8aa3b, v111
	v_exp_f32_e32 v118, v118
	v_exp_f32_e32 v119, v119
	v_pk_mul_f32 v[70:71], v[148:149], v[70:71] op_sel_hi:[0,1]
	v_pk_mul_f32 v[72:73], v[148:149], v[72:73] op_sel_hi:[0,1]
	v_add_f32_e32 v118, 1.0, v118
	v_add_f32_e32 v119, 1.0, v119
	v_rcp_f32_e32 v118, v118
	v_rcp_f32_e32 v119, v119
	v_pk_mul_f32 v[66:67], v[148:149], v[66:67] op_sel_hi:[0,1]
	v_pk_mul_f32 v[68:69], v[148:149], v[68:69] op_sel_hi:[0,1]
	v_pk_mul_f32 v[62:63], v[146:147], v[62:63] op_sel_hi:[0,1]
	v_pk_mul_f32 v[110:111], v[110:111], v[118:119]
	v_pk_mul_f32 v[64:65], v[146:147], v[64:65] op_sel_hi:[0,1]
	v_pk_mul_f32 v[106:107], v[110:111], v[106:107]
	v_mul_f32_e32 v110, 0xbfb8aa3b, v112
	v_mul_f32_e32 v111, 0xbfb8aa3b, v113
	v_exp_f32_e32 v110, v110
	v_exp_f32_e32 v111, v111
	v_pk_mul_f32 v[58:59], v[146:147], v[58:59] op_sel_hi:[0,1]
	v_pk_mul_f32 v[60:61], v[146:147], v[60:61] op_sel_hi:[0,1]
	v_add_f32_e32 v110, 1.0, v110
	v_add_f32_e32 v111, 1.0, v111
	v_rcp_f32_e32 v110, v110
	v_rcp_f32_e32 v111, v111
	v_pk_mul_f32 v[54:55], v[146:147], v[54:55] op_sel_hi:[0,1]
	v_pk_mul_f32 v[56:57], v[146:147], v[56:57] op_sel_hi:[0,1]
	v_pk_mul_f32 v[50:51], v[146:147], v[50:51] op_sel_hi:[0,1]
	v_pk_mul_f32 v[110:111], v[112:113], v[110:111]
	v_pk_mul_f32 v[52:53], v[146:147], v[52:53] op_sel_hi:[0,1]
	v_pk_mul_f32 v[108:109], v[110:111], v[108:109]
	v_mul_f32_e32 v110, 0xbfb8aa3b, v102
	v_mul_f32_e32 v111, 0xbfb8aa3b, v103
	v_exp_f32_e32 v110, v110
	v_exp_f32_e32 v111, v111
	v_pk_mul_f32 v[46:47], v[144:145], v[46:47] op_sel_hi:[0,1]
	v_pk_mul_f32 v[48:49], v[144:145], v[48:49] op_sel_hi:[0,1]
	v_add_f32_e32 v110, 1.0, v110
	v_add_f32_e32 v111, 1.0, v111
	v_rcp_f32_e32 v110, v110
	v_rcp_f32_e32 v111, v111
	v_pk_mul_f32 v[42:43], v[144:145], v[42:43] op_sel_hi:[0,1]
	v_pk_mul_f32 v[44:45], v[144:145], v[44:45] op_sel_hi:[0,1]
	v_pk_mul_f32 v[38:39], v[144:145], v[38:39] op_sel_hi:[0,1]
	v_pk_mul_f32 v[102:103], v[102:103], v[110:111]
	v_pk_mul_f32 v[40:41], v[144:145], v[40:41] op_sel_hi:[0,1]
	v_pk_mul_f32 v[102:103], v[102:103], v[98:99]
	v_mul_f32_e32 v98, 0xbfb8aa3b, v104
	v_mul_f32_e32 v99, 0xbfb8aa3b, v105
	v_exp_f32_e32 v98, v98
	v_exp_f32_e32 v99, v99
	v_pk_mul_f32 v[34:35], v[144:145], v[34:35] op_sel_hi:[0,1]
	v_pk_mul_f32 v[36:37], v[144:145], v[36:37] op_sel_hi:[0,1]
	v_add_f32_e32 v98, 1.0, v98
	v_add_f32_e32 v99, 1.0, v99
	v_rcp_f32_e32 v98, v98
	v_rcp_f32_e32 v99, v99
	v_pk_mul_f32 v[30:31], v[142:143], v[30:31] op_sel_hi:[0,1]
	v_pk_mul_f32 v[32:33], v[142:143], v[32:33] op_sel_hi:[0,1]
	v_pk_mul_f32 v[26:27], v[142:143], v[26:27] op_sel_hi:[0,1]
	v_pk_mul_f32 v[98:99], v[104:105], v[98:99]
	v_pk_mul_f32 v[28:29], v[142:143], v[28:29] op_sel_hi:[0,1]
	v_pk_mul_f32 v[104:105], v[98:99], v[100:101]
	v_cvt_pk_bf16_f32 v100, v102, v103
	v_cvt_pk_bf16_f32 v98, v106, v107
	v_cvt_pk_bf16_f32 v99, v108, v109
	v_cvt_pk_bf16_f32 v101, v104, v105
	v_add_u32_e32 v102, 0x16000, v114
	global_store_dwordx4 v102, v[98:101], s[20:21]
	v_pk_mul_f32 v[22:23], v[142:143], v[22:23] op_sel_hi:[0,1]
	v_pk_mul_f32 v[24:25], v[142:143], v[24:25] op_sel_hi:[0,1]
	v_mul_f32_e32 v98, 0xbfb8aa3b, v94
	v_mul_f32_e32 v99, 0xbfb8aa3b, v95
	v_exp_f32_e32 v98, v98
	v_exp_f32_e32 v99, v99
	v_pk_mul_f32 v[18:19], v[142:143], v[18:19] op_sel_hi:[0,1]
	v_pk_mul_f32 v[20:21], v[142:143], v[20:21] op_sel_hi:[0,1]
	v_add_f32_e32 v98, 1.0, v98
	v_add_f32_e32 v99, 1.0, v99
	v_rcp_f32_e32 v98, v98
	v_rcp_f32_e32 v99, v99
	v_pk_mul_f32 v[14:15], v[136:137], v[14:15] op_sel_hi:[0,1]
	v_pk_mul_f32 v[16:17], v[136:137], v[16:17] op_sel_hi:[0,1]
	v_pk_mul_f32 v[10:11], v[136:137], v[10:11] op_sel_hi:[0,1]
	v_pk_mul_f32 v[94:95], v[94:95], v[98:99]
	v_pk_mul_f32 v[12:13], v[136:137], v[12:13] op_sel_hi:[0,1]
	v_pk_mul_f32 v[90:91], v[94:95], v[90:91]
	v_mul_f32_e32 v94, 0xbfb8aa3b, v96
	v_mul_f32_e32 v95, 0xbfb8aa3b, v97
	v_exp_f32_e32 v94, v94
	v_exp_f32_e32 v95, v95
	v_pk_mul_f32 v[6:7], v[136:137], v[6:7] op_sel_hi:[0,1]
	v_pk_mul_f32 v[8:9], v[136:137], v[8:9] op_sel_hi:[0,1]
	v_add_f32_e32 v94, 1.0, v94
	v_add_f32_e32 v95, 1.0, v95
	v_rcp_f32_e32 v94, v94
	v_rcp_f32_e32 v95, v95
	v_pk_mul_f32 v[2:3], v[136:137], v[2:3] op_sel_hi:[0,1]
	v_pk_mul_f32 v[4:5], v[136:137], v[4:5] op_sel_hi:[0,1]
	s_mov_b64 s[60:61], -1
	v_pk_mul_f32 v[94:95], v[96:97], v[94:95]
	s_and_b64 vcc, vcc, exec
	v_pk_mul_f32 v[92:93], v[94:95], v[92:93]
	v_mul_f32_e32 v94, 0xbfb8aa3b, v86
	v_mul_f32_e32 v95, 0xbfb8aa3b, v87
	v_exp_f32_e32 v94, v94
	v_exp_f32_e32 v95, v95
	v_add_f32_e32 v94, 1.0, v94
	v_add_f32_e32 v95, 1.0, v95
	v_rcp_f32_e32 v94, v94
	v_rcp_f32_e32 v95, v95
	s_nop 0
	v_pk_mul_f32 v[86:87], v[86:87], v[94:95]
	s_nop 0
	v_pk_mul_f32 v[86:87], v[86:87], v[82:83]
	v_mul_f32_e32 v82, 0xbfb8aa3b, v88
	v_mul_f32_e32 v83, 0xbfb8aa3b, v89
	v_exp_f32_e32 v82, v82
	v_exp_f32_e32 v83, v83
	v_add_f32_e32 v82, 1.0, v82
	v_add_f32_e32 v83, 1.0, v83
; __device__ __forceinline__ float siluf_(float x) { return x * sigmoidf_(x); }
; __device__ __forceinline__ u32x4 pack8(const f32x4 a, const f32x4 b) { u32x4 w; w.x = cvt_pk_bf16(a[0], a[1]); w.y = cvt_pk_bf16(a[2], a[3]); w.z = cvt_pk_bf16(b[0], b[1]); w.w = cvt_pk_bf16(b[2], b[3]); return w; }
;     __device__ __forceinline__ void operator()(const Acc& acc, const Unit& u, int wr, int wc, int fr, int fq, const RsPre& pr) const {
;         asm volatile("" : "+v"(fr), "+v"(fq));
;         const int row0 = u.pm * 256 + wr * 64 + fr, col0 = u.pn * 128 + wc * 32 + 8 * fq;
;         const float (&rs)[2][4] = pr.rs;
; #pragma unroll
;         for (int ai = 0; ai < 2; ++ai)
; #pragma unroll
;             for (int m = 0; m < 4; ++m) { f32x4 o[2];
; #pragma unroll
;                 for (int n = 0; n < 2; ++n) { const f32x4 a1 = acc[ai][0][m][n] * rs[ai][m], a3 = acc[ai][1][m][n] * rs[ai][m];
;                     o[n] = (f32x4){siluf_(a1[0]) * a3[0], siluf_(a1[1]) * a3[1], siluf_(a1[2]) * a3[2], siluf_(a1[3]) * a3[3]}; }
;                 *(u32x4*)(ff + (size_t)(row0 + ai * 128 + m * 16) * DFF + col0) = pack8(o[0], o[1]); }
	v_rcp_f32_e32 v82, v82
	v_rcp_f32_e32 v83, v83
	s_nop 0
	v_pk_mul_f32 v[82:83], v[88:89], v[82:83]
	s_nop 0
	v_pk_mul_f32 v[88:89], v[82:83], v[84:85]
	v_cvt_pk_bf16_f32 v84, v86, v87
	v_cvt_pk_bf16_f32 v82, v90, v91
	v_cvt_pk_bf16_f32 v83, v92, v93
	v_cvt_pk_bf16_f32 v85, v88, v89
	v_add_u32_e32 v86, 0x2c000, v114
	global_store_dwordx4 v86, v[82:85], s[20:21]
	s_nop 1
	v_mul_f32_e32 v82, 0xbfb8aa3b, v78
	v_mul_f32_e32 v83, 0xbfb8aa3b, v79
	v_exp_f32_e32 v82, v82
	v_exp_f32_e32 v83, v83
	v_add_f32_e32 v82, 1.0, v82
	v_add_f32_e32 v83, 1.0, v83
	v_rcp_f32_e32 v82, v82
	v_rcp_f32_e32 v83, v83
	s_nop 0
	v_pk_mul_f32 v[78:79], v[78:79], v[82:83]
	s_nop 0
	v_pk_mul_f32 v[74:75], v[78:79], v[74:75]
	v_mul_f32_e32 v78, 0xbfb8aa3b, v80
	v_mul_f32_e32 v79, 0xbfb8aa3b, v81
	v_exp_f32_e32 v78, v78
	v_exp_f32_e32 v79, v79
	v_add_f32_e32 v78, 1.0, v78
	v_add_f32_e32 v79, 1.0, v79
	v_rcp_f32_e32 v78, v78
	v_rcp_f32_e32 v79, v79
	s_nop 0
	v_pk_mul_f32 v[78:79], v[80:81], v[78:79]
	s_nop 0
	v_pk_mul_f32 v[76:77], v[78:79], v[76:77]
	v_mul_f32_e32 v78, 0xbfb8aa3b, v70
	v_mul_f32_e32 v79, 0xbfb8aa3b, v71
	v_exp_f32_e32 v78, v78
	v_exp_f32_e32 v79, v79
	v_add_f32_e32 v78, 1.0, v78
	v_add_f32_e32 v79, 1.0, v79
	v_rcp_f32_e32 v78, v78
	v_rcp_f32_e32 v79, v79
	s_nop 0
	v_pk_mul_f32 v[70:71], v[70:71], v[78:79]
	s_nop 0
	v_pk_mul_f32 v[70:71], v[70:71], v[66:67]
	v_mul_f32_e32 v66, 0xbfb8aa3b, v72
	v_mul_f32_e32 v67, 0xbfb8aa3b, v73
	v_exp_f32_e32 v66, v66
	v_exp_f32_e32 v67, v67
	v_add_f32_e32 v66, 1.0, v66
	v_add_f32_e32 v67, 1.0, v67
	v_rcp_f32_e32 v66, v66
	v_rcp_f32_e32 v67, v67
	s_nop 0
	v_pk_mul_f32 v[66:67], v[72:73], v[66:67]
	s_nop 0
	v_pk_mul_f32 v[72:73], v[66:67], v[68:69]
	v_cvt_pk_bf16_f32 v68, v70, v71
	v_cvt_pk_bf16_f32 v66, v74, v75
	v_cvt_pk_bf16_f32 v67, v76, v77
	v_cvt_pk_bf16_f32 v69, v72, v73
	v_add_u32_e32 v70, 0x42000, v114
	global_store_dwordx4 v70, v[66:69], s[20:21]
	s_nop 1
	v_mul_f32_e32 v66, 0xbfb8aa3b, v62
	v_mul_f32_e32 v67, 0xbfb8aa3b, v63
	v_exp_f32_e32 v66, v66
	v_exp_f32_e32 v67, v67
	v_add_f32_e32 v66, 1.0, v66
	v_add_f32_e32 v67, 1.0, v67
	v_rcp_f32_e32 v66, v66
	v_rcp_f32_e32 v67, v67
	s_nop 0
	v_pk_mul_f32 v[62:63], v[62:63], v[66:67]
	s_nop 0
	v_pk_mul_f32 v[58:59], v[62:63], v[58:59]
	v_mul_f32_e32 v62, 0xbfb8aa3b, v64
	v_mul_f32_e32 v63, 0xbfb8aa3b, v65
	v_exp_f32_e32 v62, v62
	v_exp_f32_e32 v63, v63
	v_add_f32_e32 v62, 1.0, v62
	v_add_f32_e32 v63, 1.0, v63
	v_rcp_f32_e32 v62, v62
	v_rcp_f32_e32 v63, v63
	s_nop 0
	v_pk_mul_f32 v[62:63], v[64:65], v[62:63]
	s_nop 0
	v_pk_mul_f32 v[60:61], v[62:63], v[60:61]
	v_mul_f32_e32 v62, 0xbfb8aa3b, v54
	v_mul_f32_e32 v63, 0xbfb8aa3b, v55
	v_exp_f32_e32 v62, v62
	v_exp_f32_e32 v63, v63
	v_add_f32_e32 v62, 1.0, v62
	v_add_f32_e32 v63, 1.0, v63
	v_rcp_f32_e32 v62, v62
	v_rcp_f32_e32 v63, v63
	s_nop 0
	v_pk_mul_f32 v[54:55], v[54:55], v[62:63]
	s_nop 0
	v_pk_mul_f32 v[54:55], v[54:55], v[50:51]
	v_mul_f32_e32 v50, 0xbfb8aa3b, v56
	v_mul_f32_e32 v51, 0xbfb8aa3b, v57
	v_exp_f32_e32 v50, v50
	v_exp_f32_e32 v51, v51
	v_add_f32_e32 v50, 1.0, v50
	v_add_f32_e32 v51, 1.0, v51
	v_rcp_f32_e32 v50, v50
	v_rcp_f32_e32 v51, v51
	s_nop 0
	v_pk_mul_f32 v[50:51], v[56:57], v[50:51]
	s_nop 0
	v_pk_mul_f32 v[56:57], v[50:51], v[52:53]
	v_cvt_pk_bf16_f32 v52, v54, v55
	v_cvt_pk_bf16_f32 v50, v58, v59
	v_cvt_pk_bf16_f32 v51, v60, v61
	v_cvt_pk_bf16_f32 v53, v56, v57
	v_add_u32_e32 v54, 0xb0000, v114
	global_store_dwordx4 v54, v[50:53], s[20:21]
	s_nop 1
	v_mul_f32_e32 v50, 0xbfb8aa3b, v46
	v_mul_f32_e32 v51, 0xbfb8aa3b, v47
	v_exp_f32_e32 v50, v50
	v_exp_f32_e32 v51, v51
	v_add_f32_e32 v50, 1.0, v50
	v_add_f32_e32 v51, 1.0, v51
	v_rcp_f32_e32 v50, v50
	v_rcp_f32_e32 v51, v51
	s_nop 0
	v_pk_mul_f32 v[46:47], v[46:47], v[50:51]
	s_nop 0
	v_pk_mul_f32 v[42:43], v[46:47], v[42:43]
	v_mul_f32_e32 v46, 0xbfb8aa3b, v48
	v_mul_f32_e32 v47, 0xbfb8aa3b, v49
	v_exp_f32_e32 v46, v46
	v_exp_f32_e32 v47, v47
	v_add_f32_e32 v46, 1.0, v46
	v_add_f32_e32 v47, 1.0, v47
	v_rcp_f32_e32 v46, v46
	v_rcp_f32_e32 v47, v47
	s_nop 0
	v_pk_mul_f32 v[46:47], v[48:49], v[46:47]
	s_nop 0
	v_pk_mul_f32 v[44:45], v[46:47], v[44:45]
	v_mul_f32_e32 v46, 0xbfb8aa3b, v38
	v_mul_f32_e32 v47, 0xbfb8aa3b, v39
	v_exp_f32_e32 v46, v46
	v_exp_f32_e32 v47, v47
	v_add_f32_e32 v46, 1.0, v46
	v_add_f32_e32 v47, 1.0, v47
; __device__ __forceinline__ float siluf_(float x) { return x * sigmoidf_(x); }
; __device__ __forceinline__ u32x4 pack8(const f32x4 a, const f32x4 b) { u32x4 w; w.x = cvt_pk_bf16(a[0], a[1]); w.y = cvt_pk_bf16(a[2], a[3]); w.z = cvt_pk_bf16(b[0], b[1]); w.w = cvt_pk_bf16(b[2], b[3]); return w; }
;     __device__ __forceinline__ void pre(RsPre& r, const Unit& u, int wr, int fr) const {
; #pragma unroll
;         for (int ai = 0; ai < 2; ++ai)
; #pragma unroll
;             for (int m = 0; m < 4; ++m) r.rs[ai][m] = rsv[u.pm * 256 + wr * 64 + fr + ai * 128 + m * 16]; }
;     __device__ __forceinline__ void operator()(const Acc& acc, const Unit& u, int wr, int wc, int fr, int fq, const RsPre& pr) const {
;     ...
; #pragma unroll
;         for (int ai = 0; ai < 2; ++ai)
; #pragma unroll
;             for (int m = 0; m < 4; ++m) { f32x4 o[2];
; #pragma unroll
;                 for (int n = 0; n < 2; ++n) { const f32x4 a1 = acc[ai][0][m][n] * rs[ai][m], a3 = acc[ai][1][m][n] * rs[ai][m];
;                     o[n] = (f32x4){siluf_(a1[0]) * a3[0], siluf_(a1[1]) * a3[1], siluf_(a1[2]) * a3[2], siluf_(a1[3]) * a3[3]}; }
;                 *(u32x4*)(ff + (size_t)(row0 + ai * 128 + m * 16) * DFF + col0) = pack8(o[0], o[1]); }
	v_rcp_f32_e32 v46, v46
	v_rcp_f32_e32 v47, v47
	s_nop 0
	v_pk_mul_f32 v[38:39], v[38:39], v[46:47]
	s_nop 0
	v_pk_mul_f32 v[38:39], v[38:39], v[34:35]
	v_mul_f32_e32 v34, 0xbfb8aa3b, v40
	v_mul_f32_e32 v35, 0xbfb8aa3b, v41
	v_exp_f32_e32 v34, v34
	v_exp_f32_e32 v35, v35
	v_add_f32_e32 v34, 1.0, v34
	v_add_f32_e32 v35, 1.0, v35
	v_rcp_f32_e32 v34, v34
	v_rcp_f32_e32 v35, v35
	s_nop 0
	v_pk_mul_f32 v[34:35], v[40:41], v[34:35]
	s_nop 0
	v_pk_mul_f32 v[40:41], v[34:35], v[36:37]
	v_cvt_pk_bf16_f32 v36, v38, v39
	v_cvt_pk_bf16_f32 v34, v42, v43
	v_cvt_pk_bf16_f32 v35, v44, v45
	v_cvt_pk_bf16_f32 v37, v40, v41
	v_add_u32_e32 v38, 0xc6000, v114
	global_store_dwordx4 v38, v[34:37], s[20:21]
	s_nop 1
	v_mul_f32_e32 v34, 0xbfb8aa3b, v30
	v_mul_f32_e32 v35, 0xbfb8aa3b, v31
	v_exp_f32_e32 v34, v34
	v_exp_f32_e32 v35, v35
	v_add_f32_e32 v34, 1.0, v34
	v_add_f32_e32 v35, 1.0, v35
	v_rcp_f32_e32 v34, v34
	v_rcp_f32_e32 v35, v35
	s_nop 0
	v_pk_mul_f32 v[30:31], v[30:31], v[34:35]
	s_nop 0
	v_pk_mul_f32 v[26:27], v[30:31], v[26:27]
	v_mul_f32_e32 v30, 0xbfb8aa3b, v32
	v_mul_f32_e32 v31, 0xbfb8aa3b, v33
	v_exp_f32_e32 v30, v30
	v_exp_f32_e32 v31, v31
	v_add_f32_e32 v30, 1.0, v30
	v_add_f32_e32 v31, 1.0, v31
	v_rcp_f32_e32 v30, v30
	v_rcp_f32_e32 v31, v31
	s_nop 0
	v_pk_mul_f32 v[30:31], v[32:33], v[30:31]
	s_nop 0
	v_pk_mul_f32 v[28:29], v[30:31], v[28:29]
	v_mul_f32_e32 v30, 0xbfb8aa3b, v22
	v_mul_f32_e32 v31, 0xbfb8aa3b, v23
	v_exp_f32_e32 v30, v30
	v_exp_f32_e32 v31, v31
	v_add_f32_e32 v30, 1.0, v30
	v_add_f32_e32 v31, 1.0, v31
	v_rcp_f32_e32 v30, v30
	v_rcp_f32_e32 v31, v31
	s_nop 0
	v_pk_mul_f32 v[22:23], v[22:23], v[30:31]
	s_nop 0
	v_pk_mul_f32 v[22:23], v[22:23], v[18:19]
	v_mul_f32_e32 v18, 0xbfb8aa3b, v24
	v_mul_f32_e32 v19, 0xbfb8aa3b, v25
	v_exp_f32_e32 v18, v18
	v_exp_f32_e32 v19, v19
	v_add_f32_e32 v18, 1.0, v18
	v_add_f32_e32 v19, 1.0, v19
	v_rcp_f32_e32 v18, v18
	v_rcp_f32_e32 v19, v19
	s_nop 0
	v_pk_mul_f32 v[18:19], v[24:25], v[18:19]
	s_nop 0
	v_pk_mul_f32 v[24:25], v[18:19], v[20:21]
	v_cvt_pk_bf16_f32 v20, v22, v23
	v_cvt_pk_bf16_f32 v18, v26, v27
	v_cvt_pk_bf16_f32 v19, v28, v29
	v_cvt_pk_bf16_f32 v21, v24, v25
	v_add_u32_e32 v22, 0xdc000, v114
	global_store_dwordx4 v22, v[18:21], s[20:21]
	s_nop 1
	v_mul_f32_e32 v18, 0xbfb8aa3b, v14
	v_mul_f32_e32 v19, 0xbfb8aa3b, v15
	v_exp_f32_e32 v18, v18
	v_exp_f32_e32 v19, v19
	v_add_f32_e32 v18, 1.0, v18
	v_add_f32_e32 v19, 1.0, v19
	v_rcp_f32_e32 v18, v18
	v_rcp_f32_e32 v19, v19
	s_nop 0
	v_pk_mul_f32 v[14:15], v[14:15], v[18:19]
	s_nop 0
	v_pk_mul_f32 v[10:11], v[14:15], v[10:11]
	v_mul_f32_e32 v14, 0xbfb8aa3b, v16
	v_mul_f32_e32 v15, 0xbfb8aa3b, v17
	v_exp_f32_e32 v14, v14
	v_exp_f32_e32 v15, v15
	v_add_f32_e32 v14, 1.0, v14
	v_add_f32_e32 v15, 1.0, v15
	v_rcp_f32_e32 v14, v14
	v_rcp_f32_e32 v15, v15
	s_nop 0
	v_pk_mul_f32 v[14:15], v[16:17], v[14:15]
	s_nop 0
	v_pk_mul_f32 v[12:13], v[14:15], v[12:13]
	v_mul_f32_e32 v14, 0xbfb8aa3b, v6
	v_mul_f32_e32 v15, 0xbfb8aa3b, v7
	v_exp_f32_e32 v14, v14
	v_exp_f32_e32 v15, v15
	v_add_f32_e32 v14, 1.0, v14
	v_add_f32_e32 v15, 1.0, v15
	v_rcp_f32_e32 v14, v14
	v_rcp_f32_e32 v15, v15
	s_nop 0
	v_pk_mul_f32 v[6:7], v[6:7], v[14:15]
	s_nop 0
	v_pk_mul_f32 v[6:7], v[6:7], v[2:3]
	v_mul_f32_e32 v2, 0xbfb8aa3b, v8
	v_mul_f32_e32 v3, 0xbfb8aa3b, v9
	v_exp_f32_e32 v2, v2
	v_exp_f32_e32 v3, v3
	v_add_f32_e32 v2, 1.0, v2
	v_add_f32_e32 v3, 1.0, v3
	v_rcp_f32_e32 v2, v2
	v_rcp_f32_e32 v3, v3
	s_nop 0
	v_pk_mul_f32 v[2:3], v[8:9], v[2:3]
	s_nop 0
	v_pk_mul_f32 v[8:9], v[2:3], v[4:5]
	v_cvt_pk_bf16_f32 v4, v6, v7
	v_cvt_pk_bf16_f32 v2, v10, v11
	v_cvt_pk_bf16_f32 v3, v12, v13
	v_cvt_pk_bf16_f32 v5, v8, v9
	v_add_u32_e32 v6, 0xf2000, v114
	global_store_dwordx4 v6, v[2:5], s[20:21]
	s_cbranch_vccz .LBB0_96
	s_nop 0
	v_lshl_add_u32 v2, s42, 8, v145
	v_ashrrev_i32_e32 v3, 31, v2
	v_lshl_add_u64 v[2:3], v[2:3], 2, s[4:5]
	global_load_dword v154, v[2:3], off
	global_load_dword v152, v[2:3], off offset:64
	global_load_dword v150, v[2:3], off offset:128
	global_load_dword v148, v[2:3], off offset:192
	global_load_dword v146, v[2:3], off offset:512
	global_load_dword v144, v[2:3], off offset:576
	global_load_dword v142, v[2:3], off offset:640
	global_load_dword v136, v[2:3], off offset:704
	s_mov_b64 s[60:61], 0
	s_branch .LBB0_96

; #define PG8_STAGE(bufoff, gbase, voff) do { _Pragma("unroll") for (int _i = 0; _i < 2; ++_i) \
;         __builtin_amdgcn_global_load_lds((const unsigned*)((const char*)(gbase) + (voff)[_i]), (LAS unsigned*)(lds + (bufoff) + ldsw + _i * 8192), 16, 0, 0); } while (0)
; #define PG8_LDA(dst, b, h) do { _Pragma("unroll") for (int m = 0; m < 4; ++m) _Pragma("unroll") for (int k = 0; k < 2; ++k) dst[m][k] = *(const LAS bf16x8*)(lds + PG8_SA(b, h) + aoff + m * 2048 + k * 1024); } while (0)
; #define PG8_LDB(dst, b, h) do { _Pragma("unroll") for (int n = 0; n < 2; ++n) _Pragma("unroll") for (int k = 0; k < 2; ++k) dst[n][k] = *(const LAS bf16x8*)(lds + PG8_SB(b, h) + boff + n * 2048 + k * 1024); } while (0)
; #define PG8_WAIT_V(n) asm volatile("s_waitcnt vmcnt(" #n ")" ::: "memory")
; #define PG8_WAIT_L(n) asm volatile("s_waitcnt lgkmcnt(" #n ")" ::: "memory")
; #define PG8_BAR __builtin_amdgcn_s_barrier()
; template <class Epi>
; __device__ __forceinline__ void gemm_phase(LAS unsigned char* lds, const Gemm g, const StaticOrder& S, const Epi& E) {
;     ...
;         for (int t = 0; t < nt; t += 2) {
;             const bool last = (t == nt - 2);
;             const char* a1 = cA + (size_t)(t + 1) * kstep;
;             const char* a2 = last ? nA : cA + (size_t)(t + 2) * kstep; const char* b2 = last ? nB : cB + (size_t)(t + 2) * kstep;
;             const char* a3 = a2 + kstep; const char* b3 = b2 + kstep;
;             PG8_LDB(B0, 0, 0); PG8_SCHED; PG8_LDA(At, 0, 0); PG8_STAGE(PG8_SA(1, 1), a1 + hA, voffA);
;             PG8_WAIT_L(8); PG8_BAR; PG8_WAIT_L(0); PG8_MMA(0, 0, At, B0); PG8_BAR; PG8_SCHED;
;             PG8_LDB(B1, 0, 1); PG8_STAGE(PG8_SB(0, 0), b2, voffB);
;             PG8_BAR; PG8_WAIT_L(0); PG8_MMA(0, 1, At, B1); PG8_BAR;
;             PG8_LDA(At, 0, 1); PG8_STAGE(PG8_SA(0, 0), a2, voffA);
;             PG8_BAR; PG8_WAIT_L(0); PG8_MMA(1, 0, At, B0); PG8_BAR; PG8_SCHED;
;             PG8_STAGE(PG8_SB(0, 1), b2 + hB, voffB);
;             PG8_WAIT_V(6); PG8_BAR; PG8_MMA(1, 1, At, B1); PG8_BAR;
;             PG8_LDB(B0, 1, 0); PG8_SCHED; PG8_LDA(At, 1, 0); PG8_STAGE(PG8_SA(0, 1), a2 + hA, voffA);
;             PG8_WAIT_L(8); PG8_BAR; PG8_WAIT_L(0); PG8_MMA(0, 0, At, B0); PG8_BAR; PG8_SCHED;
;             PG8_LDB(B1, 1, 1); PG8_STAGE(PG8_SB(1, 0), b3, voffB);
;             PG8_BAR; PG8_WAIT_L(0); PG8_MMA(0, 1, At, B1); PG8_BAR;
.LBB0_209:
	s_add_i32 vcc_lo, s70, 2
	s_add_u32 s22, s68, 0xfffc0080
	s_addc_u32 s23, s69, -1
	s_add_i32 vcc_hi, 0, 0x10000
	v_add_u32_e32 v142, vcc_hi, v188
	ds_read_b128 v[130:133], v142
	ds_read_b128 v[134:137], v142 offset:1024
	ds_read_b128 v[138:141], v142 offset:2048
	ds_read_b128 v[142:145], v142 offset:3072
	s_cmp_eq_u32 s65, s70
	s_cselect_b32 s70, s59, s67
	s_cselect_b32 s75, s33, s23
	s_cselect_b32 s74, s45, s22
	s_cselect_b32 s71, s57, s97
	s_add_i32 m0, s43, 0xc000
	ds_read_b128 v[146:149], v189
	ds_read_b128 v[150:153], v189 offset:1024
	ds_read_b128 v[154:157], v189 offset:2048
	ds_read_b128 v[168:171], v189 offset:3072
	ds_read_b128 v[172:175], v189 offset:4096
	ds_read_b128 v[176:179], v189 offset:5120
	ds_read_b128 v[180:183], v189 offset:6144
	ds_read_b128 v[190:193], v189 offset:7168
	global_load_lds_dwordx4 v164, s[68:69]
	s_add_i32 m0, s43, 0xe000
	s_nop 0
	global_load_lds_dwordx4 v166, s[68:69]
	s_waitcnt lgkmcnt(8)
	s_barrier
	s_waitcnt lgkmcnt(0)
	s_setprio 1
	v_mfma_f32_16x16x32_bf16 v[126:129], v[130:133], v[146:149], v[126:129]
	v_mfma_f32_16x16x32_bf16 v[122:125], v[138:141], v[146:149], v[122:125]
	v_mfma_f32_16x16x32_bf16 v[110:113], v[130:133], v[154:157], v[110:113]
	v_mfma_f32_16x16x32_bf16 v[106:109], v[138:141], v[154:157], v[106:109]
	v_mfma_f32_16x16x32_bf16 v[94:97], v[130:133], v[172:175], v[94:97]
	v_mfma_f32_16x16x32_bf16 v[90:93], v[138:141], v[172:175], v[90:93]
	v_mfma_f32_16x16x32_bf16 v[78:81], v[130:133], v[180:183], v[78:81]
	v_mfma_f32_16x16x32_bf16 v[74:77], v[138:141], v[180:183], v[74:77]
	v_mfma_f32_16x16x32_bf16 v[126:129], v[134:137], v[150:153], v[126:129]
	v_mfma_f32_16x16x32_bf16 v[122:125], v[142:145], v[150:153], v[122:125]
	v_mfma_f32_16x16x32_bf16 v[110:113], v[134:137], v[168:171], v[110:113]
	v_mfma_f32_16x16x32_bf16 v[106:109], v[142:145], v[168:171], v[106:109]
	v_mfma_f32_16x16x32_bf16 v[94:97], v[134:137], v[176:179], v[94:97]
	v_mfma_f32_16x16x32_bf16 v[90:93], v[142:145], v[176:179], v[90:93]
	v_mfma_f32_16x16x32_bf16 v[78:81], v[134:137], v[190:193], v[78:81]
	v_mfma_f32_16x16x32_bf16 v[74:77], v[142:145], v[190:193], v[74:77]
	s_setprio 0
	s_barrier
	s_add_i32 s77, 0, 0x14000
	v_add_u32_e32 v184, s77, v188
	s_add_i32 s22, vcc_hi, s50
	ds_read_b128 v[202:205], v184
	ds_read_b128 v[206:209], v184 offset:1024
	ds_read_b128 v[210:213], v184 offset:2048
	ds_read_b128 v[214:217], v184 offset:3072
	s_mov_b32 m0, s22
	s_nop 0
	global_load_lds_dwordx4 v0, s[70:71]
	s_add_i32 m0, s22, 0x2000
	s_nop 0
	global_load_lds_dwordx4 v162, s[70:71]
	s_barrier
	s_waitcnt lgkmcnt(0)
	s_setprio 1
	v_mfma_f32_16x16x32_bf16 v[118:121], v[202:205], v[146:149], v[118:121]
	v_mfma_f32_16x16x32_bf16 v[114:117], v[210:213], v[146:149], v[114:117]
	v_mfma_f32_16x16x32_bf16 v[102:105], v[202:205], v[154:157], v[102:105]
	v_mfma_f32_16x16x32_bf16 v[98:101], v[210:213], v[154:157], v[98:101]
	v_mfma_f32_16x16x32_bf16 v[86:89], v[202:205], v[172:175], v[86:89]
	v_mfma_f32_16x16x32_bf16 v[82:85], v[210:213], v[172:175], v[82:85]
	v_mfma_f32_16x16x32_bf16 v[70:73], v[202:205], v[180:183], v[70:73]
	v_mfma_f32_16x16x32_bf16 v[66:69], v[210:213], v[180:183], v[66:69]
	v_mfma_f32_16x16x32_bf16 v[118:121], v[206:209], v[150:153], v[118:121]
	v_mfma_f32_16x16x32_bf16 v[114:117], v[214:217], v[150:153], v[114:117]
	v_mfma_f32_16x16x32_bf16 v[102:105], v[206:209], v[168:171], v[102:105]
	v_mfma_f32_16x16x32_bf16 v[98:101], v[214:217], v[168:171], v[98:101]
	v_mfma_f32_16x16x32_bf16 v[86:89], v[206:209], v[176:179], v[86:89]
	v_mfma_f32_16x16x32_bf16 v[82:85], v[214:217], v[176:179], v[82:85]
	v_mfma_f32_16x16x32_bf16 v[70:73], v[206:209], v[190:193], v[70:73]
	v_mfma_f32_16x16x32_bf16 v[66:69], v[214:217], v[190:193], v[66:69]
	s_setprio 0
	s_mov_b32 m0, s43
	s_barrier
	ds_read_b128 v[146:149], v189 offset:16384
	ds_read_b128 v[150:153], v189 offset:17408
	ds_read_b128 v[154:157], v189 offset:18432
	ds_read_b128 v[168:171], v189 offset:19456
	ds_read_b128 v[172:175], v189 offset:20480
	ds_read_b128 v[176:179], v189 offset:21504
	ds_read_b128 v[180:183], v189 offset:22528
	ds_read_b128 v[190:193], v189 offset:23552
	global_load_lds_dwordx4 v158, s[74:75]
	s_mov_b32 m0, s51
	s_nop 0
	global_load_lds_dwordx4 v160, s[74:75]
	s_barrier
	s_waitcnt lgkmcnt(0)
	s_setprio 1
	v_mfma_f32_16x16x32_bf16 v[62:65], v[130:133], v[146:149], v[62:65]
	v_mfma_f32_16x16x32_bf16 v[58:61], v[138:141], v[146:149], v[58:61]
	v_mfma_f32_16x16x32_bf16 v[46:49], v[130:133], v[154:157], v[46:49]
	v_mfma_f32_16x16x32_bf16 v[42:45], v[138:141], v[154:157], v[42:45]
	v_mfma_f32_16x16x32_bf16 v[30:33], v[130:133], v[172:175], v[30:33]
	v_mfma_f32_16x16x32_bf16 v[26:29], v[138:141], v[172:175], v[26:29]
	v_mfma_f32_16x16x32_bf16 v[14:17], v[130:133], v[180:183], v[14:17]
	v_mfma_f32_16x16x32_bf16 v[10:13], v[138:141], v[180:183], v[10:13]
	v_mfma_f32_16x16x32_bf16 v[62:65], v[134:137], v[150:153], v[62:65]
	v_mfma_f32_16x16x32_bf16 v[58:61], v[142:145], v[150:153], v[58:61]
	v_mfma_f32_16x16x32_bf16 v[46:49], v[134:137], v[168:171], v[46:49]
	v_mfma_f32_16x16x32_bf16 v[42:45], v[142:145], v[168:171], v[42:45]
	v_mfma_f32_16x16x32_bf16 v[30:33], v[134:137], v[176:179], v[30:33]
	v_mfma_f32_16x16x32_bf16 v[26:29], v[142:145], v[176:179], v[26:29]
	v_mfma_f32_16x16x32_bf16 v[14:17], v[134:137], v[190:193], v[14:17]
	v_mfma_f32_16x16x32_bf16 v[10:13], v[142:145], v[190:193], v[10:13]
	s_setprio 0
	s_barrier
	s_add_u32 s22, s70, 0x40000
	s_addc_u32 s23, s71, 0
	s_add_i32 s77, s77, s50
	s_mov_b32 m0, s77
	s_nop 0
	global_load_lds_dwordx4 v0, s[22:23]
	s_add_i32 m0, s77, 0x2000
	s_nop 0
	global_load_lds_dwordx4 v162, s[22:23]
	s_waitcnt vmcnt(6)
	s_barrier
; #define PG8_STAGE(bufoff, gbase, voff) do { _Pragma("unroll") for (int _i = 0; _i < 2; ++_i) \
;         __builtin_amdgcn_global_load_lds((const unsigned*)((const char*)(gbase) + (voff)[_i]), (LAS unsigned*)(lds + (bufoff) + ldsw + _i * 8192), 16, 0, 0); } while (0)
; #define PG8_LDA(dst, b, h) do { _Pragma("unroll") for (int m = 0; m < 4; ++m) _Pragma("unroll") for (int k = 0; k < 2; ++k) dst[m][k] = *(const LAS bf16x8*)(lds + PG8_SA(b, h) + aoff + m * 2048 + k * 1024); } while (0)
; #define PG8_LDB(dst, b, h) do { _Pragma("unroll") for (int n = 0; n < 2; ++n) _Pragma("unroll") for (int k = 0; k < 2; ++k) dst[n][k] = *(const LAS bf16x8*)(lds + PG8_SB(b, h) + boff + n * 2048 + k * 1024); } while (0)
; #define PG8_MMA(ai, bj, At, Bt) do { __builtin_amdgcn_s_setprio(1); _Pragma("unroll") for (int m = 0; m < 4; ++m) _Pragma("unroll") for (int n = 0; n < 2; ++n) _Pragma("unroll") for (int k = 0; k < 2; ++k) \
;         acc[ai][bj][m][n] = __builtin_amdgcn_mfma_f32_16x16x32_bf16(Bt[n][k], At[m][k], acc[ai][bj][m][n], 0, 0, 0); __builtin_amdgcn_s_setprio(0); } while (0)
; #define PG8_WAIT_V(n) asm volatile("s_waitcnt vmcnt(" #n ")" ::: "memory")
; #define PG8_WAIT_L(n) asm volatile("s_waitcnt lgkmcnt(" #n ")" ::: "memory")
; #define PG8_BAR __builtin_amdgcn_s_barrier()
; #define PG8_SCHED __builtin_amdgcn_sched_barrier(0)
; template <class Epi>
; __device__ __forceinline__ void gemm_phase(LAS unsigned char* lds, const Gemm g, const StaticOrder& S, const Epi& E) {
;     ...
;             PG8_WAIT_V(6); PG8_BAR; PG8_MMA(1, 1, At, B1); PG8_BAR;
;             PG8_LDB(B0, 1, 0); PG8_SCHED; PG8_LDA(At, 1, 0); PG8_STAGE(PG8_SA(0, 1), a2 + hA, voffA);
;             PG8_WAIT_L(8); PG8_BAR; PG8_WAIT_L(0); PG8_MMA(0, 0, At, B0); PG8_BAR; PG8_SCHED;
;             PG8_LDB(B1, 1, 1); PG8_STAGE(PG8_SB(1, 0), b3, voffB);
;             PG8_BAR; PG8_WAIT_L(0); PG8_MMA(0, 1, At, B1); PG8_BAR;
;             PG8_LDA(At, 1, 1); PG8_STAGE(PG8_SA(1, 0), a3, voffA);
;             PG8_BAR; PG8_WAIT_L(0); PG8_MMA(1, 0, At, B0); PG8_BAR; PG8_SCHED;
	s_setprio 1
	v_mfma_f32_16x16x32_bf16 v[54:57], v[202:205], v[146:149], v[54:57]
	v_mfma_f32_16x16x32_bf16 v[50:53], v[210:213], v[146:149], v[50:53]
	v_mfma_f32_16x16x32_bf16 v[38:41], v[202:205], v[154:157], v[38:41]
	v_mfma_f32_16x16x32_bf16 v[34:37], v[210:213], v[154:157], v[34:37]
	v_mfma_f32_16x16x32_bf16 v[22:25], v[202:205], v[172:175], v[22:25]
	v_mfma_f32_16x16x32_bf16 v[18:21], v[210:213], v[172:175], v[18:21]
	v_mfma_f32_16x16x32_bf16 v[6:9], v[202:205], v[180:183], v[6:9]
	v_mfma_f32_16x16x32_bf16 v[2:5], v[210:213], v[180:183], v[2:5]
	v_mfma_f32_16x16x32_bf16 v[54:57], v[206:209], v[150:153], v[54:57]
	v_mfma_f32_16x16x32_bf16 v[50:53], v[214:217], v[150:153], v[50:53]
	v_mfma_f32_16x16x32_bf16 v[38:41], v[206:209], v[168:171], v[38:41]
	v_mfma_f32_16x16x32_bf16 v[34:37], v[214:217], v[168:171], v[34:37]
	v_mfma_f32_16x16x32_bf16 v[22:25], v[206:209], v[176:179], v[22:25]
	v_mfma_f32_16x16x32_bf16 v[18:21], v[214:217], v[176:179], v[18:21]
	v_mfma_f32_16x16x32_bf16 v[6:9], v[206:209], v[190:193], v[6:9]
	v_mfma_f32_16x16x32_bf16 v[2:5], v[214:217], v[190:193], v[2:5]
	s_setprio 0
	s_add_i32 s77, 0, 0x18000
	v_add_u32_e32 v142, s77, v188
	s_barrier
	ds_read_b128 v[130:133], v142
	ds_read_b128 v[134:137], v142 offset:1024
	ds_read_b128 v[138:141], v142 offset:2048
	ds_read_b128 v[142:145], v142 offset:3072
	s_add_u32 s22, s74, 0x40000
	s_addc_u32 s23, s75, 0
	s_mov_b32 m0, s52
	ds_read_b128 v[146:149], v189 offset:32768
	ds_read_b128 v[150:153], v189 offset:33792
	ds_read_b128 v[154:157], v189 offset:34816
	ds_read_b128 v[168:171], v189 offset:35840
	ds_read_b128 v[172:175], v189 offset:36864
	ds_read_b128 v[176:179], v189 offset:37888
	ds_read_b128 v[180:183], v189 offset:38912
	ds_read_b128 v[190:193], v189 offset:39936
	global_load_lds_dwordx4 v158, s[22:23]
	s_mov_b32 m0, s53
	s_nop 0
	global_load_lds_dwordx4 v160, s[22:23]
	s_waitcnt lgkmcnt(8)
	s_barrier
	s_waitcnt lgkmcnt(0)
	s_setprio 1
	v_mfma_f32_16x16x32_bf16 v[126:129], v[130:133], v[146:149], v[126:129]
	v_mfma_f32_16x16x32_bf16 v[122:125], v[138:141], v[146:149], v[122:125]
	v_mfma_f32_16x16x32_bf16 v[110:113], v[130:133], v[154:157], v[110:113]
	v_mfma_f32_16x16x32_bf16 v[106:109], v[138:141], v[154:157], v[106:109]
	v_mfma_f32_16x16x32_bf16 v[94:97], v[130:133], v[172:175], v[94:97]
	v_mfma_f32_16x16x32_bf16 v[90:93], v[138:141], v[172:175], v[90:93]
	v_mfma_f32_16x16x32_bf16 v[78:81], v[130:133], v[180:183], v[78:81]
	v_mfma_f32_16x16x32_bf16 v[74:77], v[138:141], v[180:183], v[74:77]
	v_mfma_f32_16x16x32_bf16 v[126:129], v[134:137], v[150:153], v[126:129]
	v_mfma_f32_16x16x32_bf16 v[122:125], v[142:145], v[150:153], v[122:125]
	v_mfma_f32_16x16x32_bf16 v[110:113], v[134:137], v[168:171], v[110:113]
	v_mfma_f32_16x16x32_bf16 v[106:109], v[142:145], v[168:171], v[106:109]
	v_mfma_f32_16x16x32_bf16 v[94:97], v[134:137], v[176:179], v[94:97]
	v_mfma_f32_16x16x32_bf16 v[90:93], v[142:145], v[176:179], v[90:93]
	v_mfma_f32_16x16x32_bf16 v[78:81], v[134:137], v[190:193], v[78:81]
	v_mfma_f32_16x16x32_bf16 v[74:77], v[142:145], v[190:193], v[74:77]
	s_setprio 0
	s_barrier
	s_add_i32 s22, s77, s50
	v_add_u32_e32 v214, 0x1c000, v188
	s_mov_b32 m0, s22
	ds_read_b128 v[202:205], v214
	ds_read_b128 v[206:209], v214 offset:1024
	ds_read_b128 v[210:213], v214 offset:2048
	ds_read_b128 v[214:217], v214 offset:3072
	s_add_u32 s100, s70, 0x80
	s_addc_u32 s101, s71, 0
	global_load_lds_dwordx4 v0, s[100:101]
	s_add_i32 m0, s22, 0x2000
	s_nop 0
	global_load_lds_dwordx4 v162, s[100:101]
	s_barrier
	s_waitcnt lgkmcnt(0)
	s_setprio 1
	v_mfma_f32_16x16x32_bf16 v[118:121], v[202:205], v[146:149], v[118:121]
	v_mfma_f32_16x16x32_bf16 v[114:117], v[210:213], v[146:149], v[114:117]
	v_mfma_f32_16x16x32_bf16 v[102:105], v[202:205], v[154:157], v[102:105]
	v_mfma_f32_16x16x32_bf16 v[98:101], v[210:213], v[154:157], v[98:101]
	v_mfma_f32_16x16x32_bf16 v[86:89], v[202:205], v[172:175], v[86:89]
	v_mfma_f32_16x16x32_bf16 v[82:85], v[210:213], v[172:175], v[82:85]
	v_mfma_f32_16x16x32_bf16 v[70:73], v[202:205], v[180:183], v[70:73]
	v_mfma_f32_16x16x32_bf16 v[66:69], v[210:213], v[180:183], v[66:69]
	v_mfma_f32_16x16x32_bf16 v[118:121], v[206:209], v[150:153], v[118:121]
	v_mfma_f32_16x16x32_bf16 v[114:117], v[214:217], v[150:153], v[114:117]
	v_mfma_f32_16x16x32_bf16 v[102:105], v[206:209], v[168:171], v[102:105]
	v_mfma_f32_16x16x32_bf16 v[98:101], v[214:217], v[168:171], v[98:101]
	v_mfma_f32_16x16x32_bf16 v[86:89], v[206:209], v[176:179], v[86:89]
	v_mfma_f32_16x16x32_bf16 v[82:85], v[214:217], v[176:179], v[82:85]
	v_mfma_f32_16x16x32_bf16 v[70:73], v[206:209], v[190:193], v[70:73]
	v_mfma_f32_16x16x32_bf16 v[66:69], v[214:217], v[190:193], v[66:69]
	s_setprio 0
	s_mov_b32 m0, s55
	s_barrier
	ds_read_b128 v[146:149], v189 offset:49152
	ds_read_b128 v[150:153], v189 offset:50176
	ds_read_b128 v[154:157], v189 offset:51200
	ds_read_b128 v[168:171], v189 offset:52224
	ds_read_b128 v[172:175], v189 offset:53248
	ds_read_b128 v[176:179], v189 offset:54272
	ds_read_b128 v[180:183], v189 offset:55296
	ds_read_b128 v[190:193], v189 offset:56320
	s_add_u32 s100, s74, 0x80
	s_addc_u32 s101, s75, 0
	global_load_lds_dwordx4 v158, s[100:101]
	s_mov_b32 m0, s48
	s_nop 0
	global_load_lds_dwordx4 v160, s[100:101]
	s_barrier
; #define PG8_STAGE(bufoff, gbase, voff) do { _Pragma("unroll") for (int _i = 0; _i < 2; ++_i) \
;         __builtin_amdgcn_global_load_lds((const unsigned*)((const char*)(gbase) + (voff)[_i]), (LAS unsigned*)(lds + (bufoff) + ldsw + _i * 8192), 16, 0, 0); } while (0)
; #define PG8_MMA(ai, bj, At, Bt) do { __builtin_amdgcn_s_setprio(1); _Pragma("unroll") for (int m = 0; m < 4; ++m) _Pragma("unroll") for (int n = 0; n < 2; ++n) _Pragma("unroll") for (int k = 0; k < 2; ++k) \
;         acc[ai][bj][m][n] = __builtin_amdgcn_mfma_f32_16x16x32_bf16(Bt[n][k], At[m][k], acc[ai][bj][m][n], 0, 0, 0); __builtin_amdgcn_s_setprio(0); } while (0)
; #define PG8_WAIT_V(n) asm volatile("s_waitcnt vmcnt(" #n ")" ::: "memory")
; #define PG8_WAIT_L(n) asm volatile("s_waitcnt lgkmcnt(" #n ")" ::: "memory")
; #define PG8_BAR __builtin_amdgcn_s_barrier()
; #define PG8_SCHED __builtin_amdgcn_sched_barrier(0)
; template <class Epi>
; __device__ __forceinline__ void gemm_phase(LAS unsigned char* lds, const Gemm g, const StaticOrder& S, const Epi& E) {
;     ...
;             PG8_BAR; PG8_WAIT_L(0); PG8_MMA(1, 0, At, B0); PG8_BAR; PG8_SCHED;
;             PG8_STAGE(PG8_SB(1, 1), b3 + hB, voffB);
;             PG8_WAIT_V(6); PG8_BAR; PG8_MMA(1, 1, At, B1); PG8_BAR;
;         }
;     __device__ __forceinline__ void operator()(const Acc& acc, const Unit& u, int wr, int wc, int fr, int fq) const {
;     ...
;         if (u.split) {
;             float* pt = part + (size_t)(u.split - 1) * 256 * DM;
; #pragma unroll
;             for (int ai = 0; ai < 2; ++ai)
; #pragma unroll
;                 for (int m = 0; m < 4; ++m)
; #pragma unroll
;                     for (int bj = 0; bj < 2; ++bj)
; #pragma unroll
;                         for (int n = 0; n < 2; ++n) *(f32x4*)(pt + (size_t)(wr * 64 + fr + ai * 128 + m * 16) * DM + col0 + bj * 128 + n * 4) = acc[ai][bj][m][n] * sc;
;             return; }
	s_waitcnt lgkmcnt(0)
	s_setprio 1
	v_mfma_f32_16x16x32_bf16 v[62:65], v[130:133], v[146:149], v[62:65]
	v_mfma_f32_16x16x32_bf16 v[58:61], v[138:141], v[146:149], v[58:61]
	v_mfma_f32_16x16x32_bf16 v[46:49], v[130:133], v[154:157], v[46:49]
	v_mfma_f32_16x16x32_bf16 v[42:45], v[138:141], v[154:157], v[42:45]
	v_mfma_f32_16x16x32_bf16 v[30:33], v[130:133], v[172:175], v[30:33]
	v_mfma_f32_16x16x32_bf16 v[26:29], v[138:141], v[172:175], v[26:29]
	v_mfma_f32_16x16x32_bf16 v[14:17], v[130:133], v[180:183], v[14:17]
	v_mfma_f32_16x16x32_bf16 v[10:13], v[138:141], v[180:183], v[10:13]
	v_mfma_f32_16x16x32_bf16 v[62:65], v[134:137], v[150:153], v[62:65]
	v_mfma_f32_16x16x32_bf16 v[58:61], v[142:145], v[150:153], v[58:61]
	v_mfma_f32_16x16x32_bf16 v[46:49], v[134:137], v[168:171], v[46:49]
	v_mfma_f32_16x16x32_bf16 v[42:45], v[142:145], v[168:171], v[42:45]
	v_mfma_f32_16x16x32_bf16 v[30:33], v[134:137], v[176:179], v[30:33]
	v_mfma_f32_16x16x32_bf16 v[26:29], v[142:145], v[176:179], v[26:29]
	v_mfma_f32_16x16x32_bf16 v[14:17], v[134:137], v[190:193], v[14:17]
	v_mfma_f32_16x16x32_bf16 v[10:13], v[142:145], v[190:193], v[10:13]
	s_setprio 0
	s_barrier
	s_add_u32 s22, s70, 0x40080
	s_addc_u32 s23, s71, 0
	s_add_i32 s70, s50, 0x1c000
	s_mov_b32 m0, s70
	s_nop 0
	global_load_lds_dwordx4 v0, s[22:23]
	s_add_i32 m0, s70, 0x2000
	s_nop 0
	global_load_lds_dwordx4 v162, s[22:23]
	s_waitcnt vmcnt(6)
	s_barrier
	s_setprio 1
	v_mfma_f32_16x16x32_bf16 v[54:57], v[202:205], v[146:149], v[54:57]
	v_mfma_f32_16x16x32_bf16 v[50:53], v[210:213], v[146:149], v[50:53]
	v_mfma_f32_16x16x32_bf16 v[38:41], v[202:205], v[154:157], v[38:41]
	v_mfma_f32_16x16x32_bf16 v[34:37], v[210:213], v[154:157], v[34:37]
	v_mfma_f32_16x16x32_bf16 v[22:25], v[202:205], v[172:175], v[22:25]
	v_mfma_f32_16x16x32_bf16 v[18:21], v[210:213], v[172:175], v[18:21]
	v_mfma_f32_16x16x32_bf16 v[6:9], v[202:205], v[180:183], v[6:9]
	v_mfma_f32_16x16x32_bf16 v[2:5], v[210:213], v[180:183], v[2:5]
	v_mfma_f32_16x16x32_bf16 v[54:57], v[206:209], v[150:153], v[54:57]
	v_mfma_f32_16x16x32_bf16 v[50:53], v[214:217], v[150:153], v[50:53]
	v_mfma_f32_16x16x32_bf16 v[38:41], v[206:209], v[168:171], v[38:41]
	v_mfma_f32_16x16x32_bf16 v[34:37], v[214:217], v[168:171], v[34:37]
	v_mfma_f32_16x16x32_bf16 v[22:25], v[206:209], v[176:179], v[22:25]
	v_mfma_f32_16x16x32_bf16 v[18:21], v[214:217], v[176:179], v[18:21]
	v_mfma_f32_16x16x32_bf16 v[6:9], v[206:209], v[190:193], v[6:9]
	v_mfma_f32_16x16x32_bf16 v[2:5], v[214:217], v[190:193], v[2:5]
	s_setprio 0
	s_add_u32 s68, s68, 0x100
	s_addc_u32 s69, s69, 0
	s_add_u32 s67, s67, 0x100
	s_addc_u32 s97, s97, 0
	s_cmp_ge_i32 vcc_lo, s30
	s_mov_b32 s70, vcc_lo
	s_barrier
	s_cbranch_scc0 .LBB0_209
	s_lshl_b32 s22, s42, 8
	v_mov_b32_e32 v133, v186
	v_mov_b32_e32 v132, v187
	s_or_b32 s22, s22, s82
	s_cmp_lg_u32 s66, 0
	v_lshl_add_u32 v168, v132, 3, s22
	v_add_u32_e32 v130, s81, v133
	v_ashrrev_i32_e32 v169, 31, v168
	s_cbranch_scc0 .LBB0_212
	s_ashr_i32 s67, s66, 31
	s_lshl_b64 s[66:67], s[66:67], 20
	s_add_u32 s66, s19, s66
	s_addc_u32 s67, s80, s67
	v_ashrrev_i32_e32 v131, 31, v130
	v_lshl_add_u64 v[134:135], v[168:169], 2, s[66:67]
	v_lshlrev_b64 v[136:137], 12, v[130:131]
	s_mov_b32 s22, 0xfff00000
	v_lshl_add_u64 v[134:135], v[134:135], 0, v[136:137]
	s_mov_b32 s23, -1
	v_lshl_add_u64 v[136:137], v[134:135], 0, s[22:23]
	v_add_co_u32_e32 v138, vcc, s83, v134
	s_mov_b32 s22, 0xfff10000
	s_nop 0
	v_addc_co_u32_e32 v139, vcc, -1, v135, vcc
	s_mov_b32 s23, -1
	global_store_dwordx4 v[138:139], v[126:129], off
	global_store_dwordx4 v[136:137], v[122:125], off offset:16
	global_store_dwordx4 v[136:137], v[118:121], off offset:512
	global_store_dwordx4 v[136:137], v[114:117], off offset:528
	v_lshl_add_u64 v[136:137], v[134:135], 0, s[22:23]
	v_add_co_u32_e32 v138, vcc, s1, v134
	s_mov_b32 s22, 0xfff20000
	s_nop 0
	v_addc_co_u32_e32 v139, vcc, -1, v135, vcc
	s_mov_b32 s23, -1
	global_store_dwordx4 v[138:139], v[110:113], off
	global_store_dwordx4 v[136:137], v[106:109], off offset:16
	global_store_dwordx4 v[136:137], v[102:105], off offset:512
	global_store_dwordx4 v[136:137], v[98:101], off offset:528
	v_lshl_add_u64 v[136:137], v[134:135], 0, s[22:23]
	s_mov_b32 s22, 0xfff20000
	v_add_co_u32_e32 v138, vcc, s22, v134
	s_mov_b32 s22, 0xfff30000
	s_nop 0
	v_addc_co_u32_e32 v139, vcc, -1, v135, vcc
	s_mov_b32 s23, -1
	global_store_dwordx4 v[138:139], v[94:97], off
	global_store_dwordx4 v[136:137], v[90:93], off offset:16
	global_store_dwordx4 v[136:137], v[86:89], off offset:512
	global_store_dwordx4 v[136:137], v[82:85], off offset:528
	v_lshl_add_u64 v[136:137], v[134:135], 0, s[22:23]
	s_mov_b32 s22, 0xfff30000
	v_add_co_u32_e32 v138, vcc, s22, v134
	s_mov_b32 s22, 0xfff80000
	s_nop 0
	v_addc_co_u32_e32 v139, vcc, -1, v135, vcc
	s_mov_b32 s23, -1
	global_store_dwordx4 v[138:139], v[78:81], off
	global_store_dwordx4 v[136:137], v[74:77], off offset:16
	global_store_dwordx4 v[136:137], v[70:73], off offset:512
	global_store_dwordx4 v[136:137], v[66:69], off offset:528
	v_lshl_add_u64 v[136:137], v[134:135], 0, s[22:23]
	s_mov_b32 s22, 0xfff80000
	v_add_co_u32_e32 v138, vcc, s22, v134
	s_mov_b32 s22, 0xfff90000
	s_nop 0
	v_addc_co_u32_e32 v139, vcc, -1, v135, vcc
	s_mov_b32 s23, -1
	global_store_dwordx4 v[138:139], v[62:65], off
	global_store_dwordx4 v[136:137], v[58:61], off offset:16
	global_store_dwordx4 v[136:137], v[54:57], off offset:512
	global_store_dwordx4 v[136:137], v[50:53], off offset:528
	v_lshl_add_u64 v[136:137], v[134:135], 0, s[22:23]
	s_mov_b32 s22, 0xfff90000
	v_add_co_u32_e32 v138, vcc, s22, v134
	s_mov_b32 s22, 0xfffa0000
	s_nop 0
	v_addc_co_u32_e32 v139, vcc, -1, v135, vcc
	s_mov_b32 s23, -1
	global_store_dwordx4 v[138:139], v[46:49], off
	global_store_dwordx4 v[136:137], v[42:45], off offset:16
	global_store_dwordx4 v[136:137], v[38:41], off offset:512
	global_store_dwordx4 v[136:137], v[34:37], off offset:528
	v_lshl_add_u64 v[136:137], v[134:135], 0, s[22:23]
	s_mov_b32 s22, 0xfffa0000
	v_add_co_u32_e32 v138, vcc, s22, v134
	s_mov_b32 s22, 0xfffb0000
	s_nop 0
	v_addc_co_u32_e32 v139, vcc, -1, v135, vcc
	s_mov_b32 s23, -1
	global_store_dwordx4 v[138:139], v[30:33], off
	global_store_dwordx4 v[136:137], v[26:29], off offset:16
	global_store_dwordx4 v[136:137], v[22:25], off offset:512
	global_store_dwordx4 v[136:137], v[18:21], off offset:528
	v_lshl_add_u64 v[136:137], v[134:135], 0, s[22:23]
	v_add_co_u32_e32 v134, vcc, 0xfffb0000, v134
	s_mov_b64 s[66:67], 0
	s_nop 0
	v_addc_co_u32_e32 v135, vcc, -1, v135, vcc
	global_store_dwordx4 v[134:135], v[14:17], off
	global_store_dwordx4 v[136:137], v[10:13], off offset:16
	global_store_dwordx4 v[136:137], v[6:9], off offset:512
	global_store_dwordx4 v[136:137], v[2:5], off offset:528
	s_branch .LBB0_213

; #define PG8_STAGE(bufoff, gbase, voff) do { _Pragma("unroll") for (int _i = 0; _i < 2; ++_i) \
;         __builtin_amdgcn_global_load_lds((const unsigned*)((const char*)(gbase) + (voff)[_i]), (LAS unsigned*)(lds + (bufoff) + ldsw + _i * 8192), 16, 0, 0); } while (0)
; #define PG8_LDA(dst, b, h) do { _Pragma("unroll") for (int m = 0; m < 4; ++m) _Pragma("unroll") for (int k = 0; k < 2; ++k) dst[m][k] = *(const LAS bf16x8*)(lds + PG8_SA(b, h) + aoff + m * 2048 + k * 1024); } while (0)
; #define PG8_LDB(dst, b, h) do { _Pragma("unroll") for (int n = 0; n < 2; ++n) _Pragma("unroll") for (int k = 0; k < 2; ++k) dst[n][k] = *(const LAS bf16x8*)(lds + PG8_SB(b, h) + boff + n * 2048 + k * 1024); } while (0)
; #define PG8_MMA(ai, bj, At, Bt) do { __builtin_amdgcn_s_setprio(1); _Pragma("unroll") for (int m = 0; m < 4; ++m) _Pragma("unroll") for (int n = 0; n < 2; ++n) _Pragma("unroll") for (int k = 0; k < 2; ++k) \
;         acc[ai][bj][m][n] = __builtin_amdgcn_mfma_f32_16x16x32_bf16(Bt[n][k], At[m][k], acc[ai][bj][m][n], 0, 0, 0); __builtin_amdgcn_s_setprio(0); } while (0)
; #define PG8_WAIT_V(n) asm volatile("s_waitcnt vmcnt(" #n ")" ::: "memory")
; #define PG8_WAIT_L(n) asm volatile("s_waitcnt lgkmcnt(" #n ")" ::: "memory")
; #define PG8_BAR __builtin_amdgcn_s_barrier()
; template <class Epi>
; __device__ __forceinline__ void gemm_phase(LAS unsigned char* lds, const Gemm g, const StaticOrder& S, const Epi& E) {
;     ...
;         for (int t = 0; t < nt; t += 2) {
;             const bool last = (t == nt - 2);
;             const char* a1 = cA + (size_t)(t + 1) * kstep;
;             const char* a2 = last ? nA : cA + (size_t)(t + 2) * kstep; const char* b2 = last ? nB : cB + (size_t)(t + 2) * kstep;
;             const char* a3 = a2 + kstep; const char* b3 = b2 + kstep;
;             PG8_LDB(B0, 0, 0); PG8_SCHED; PG8_LDA(At, 0, 0); PG8_STAGE(PG8_SA(1, 1), a1 + hA, voffA);
;             PG8_WAIT_L(8); PG8_BAR; PG8_WAIT_L(0); PG8_MMA(0, 0, At, B0); PG8_BAR; PG8_SCHED;
;             PG8_LDB(B1, 0, 1); PG8_STAGE(PG8_SB(0, 0), b2, voffB);
;             PG8_BAR; PG8_WAIT_L(0); PG8_MMA(0, 1, At, B1); PG8_BAR;
;             PG8_LDA(At, 0, 1); PG8_STAGE(PG8_SA(0, 0), a2, voffA);
;             PG8_BAR; PG8_WAIT_L(0); PG8_MMA(1, 0, At, B0); PG8_BAR; PG8_SCHED;
;             PG8_STAGE(PG8_SB(0, 1), b2 + hB, voffB);
;             PG8_WAIT_V(6); PG8_BAR; PG8_MMA(1, 1, At, B1); PG8_BAR;
.LBB0_263:
	s_add_u32 s64, s44, 0x100
	s_addc_u32 s65, s45, 0
	s_add_i32 s22, 0, 0x10000
	v_add_u32_e32 v0, s22, v241
	ds_read_b128 v[132:135], v0
	ds_read_b128 v[136:139], v0 offset:1024
	ds_read_b128 v[140:143], v0 offset:2048
	ds_read_b128 v[144:147], v0 offset:3072
	s_cmp_eq_u32 vcc_lo, 4
	s_cselect_b32 s69, s61, s65
	s_cselect_b32 s68, s60, s64
	s_cselect_b32 s67, s43, s97
	s_cselect_b32 s66, s49, s59
	s_add_i32 m0, s70, 0xc000
	ds_read_b128 v[148:151], v242
	ds_read_b128 v[152:155], v242 offset:1024
	ds_read_b128 v[156:159], v242 offset:2048
	ds_read_b128 v[160:163], v242 offset:3072
	ds_read_b128 v[164:167], v242 offset:4096
	ds_read_b128 v[168:171], v242 offset:5120
	ds_read_b128 v[172:175], v242 offset:6144
	ds_read_b128 v[176:179], v242 offset:7168
	global_load_lds_dwordx4 v210, s[44:45]
	s_add_i32 m0, s70, 0xe000
	s_nop 0
	global_load_lds_dwordx4 v212, s[44:45]
	s_waitcnt lgkmcnt(8)
	s_barrier
	s_waitcnt lgkmcnt(0)
	s_setprio 1
	v_mfma_f32_16x16x32_bf16 v[2:5], v[132:135], v[148:151], v[4:7]
	v_mfma_f32_16x16x32_bf16 v[6:9], v[140:143], v[148:151], v[8:11]
	v_mfma_f32_16x16x32_bf16 v[128:131], v[132:135], v[156:159], v[128:131]
	v_mfma_f32_16x16x32_bf16 v[124:127], v[140:143], v[156:159], v[124:127]
	v_mfma_f32_16x16x32_bf16 v[120:123], v[132:135], v[164:167], v[120:123]
	v_mfma_f32_16x16x32_bf16 v[116:119], v[140:143], v[164:167], v[116:119]
	v_mfma_f32_16x16x32_bf16 v[112:115], v[132:135], v[172:175], v[112:115]
	v_mfma_f32_16x16x32_bf16 v[108:111], v[140:143], v[172:175], v[108:111]
	v_mfma_f32_16x16x32_bf16 v[2:5], v[136:139], v[152:155], v[2:5]
	v_mfma_f32_16x16x32_bf16 v[8:11], v[144:147], v[152:155], v[6:9]
	v_mfma_f32_16x16x32_bf16 v[128:131], v[136:139], v[160:163], v[128:131]
	v_mfma_f32_16x16x32_bf16 v[124:127], v[144:147], v[160:163], v[124:127]
	v_mfma_f32_16x16x32_bf16 v[120:123], v[136:139], v[168:171], v[120:123]
	v_mfma_f32_16x16x32_bf16 v[116:119], v[144:147], v[168:171], v[116:119]
	v_mfma_f32_16x16x32_bf16 v[112:115], v[136:139], v[176:179], v[112:115]
	v_mfma_f32_16x16x32_bf16 v[108:111], v[144:147], v[176:179], v[108:111]
	s_setprio 0
	s_barrier
	s_add_i32 s23, 0, 0x14000
	s_add_i32 s22, s22, s53
	v_add_u32_e32 v0, s23, v241
	s_mov_b32 m0, s22
	ds_read_b128 v[180:183], v0
	ds_read_b128 v[184:187], v0 offset:1024
	ds_read_b128 v[188:191], v0 offset:2048
	ds_read_b128 v[192:195], v0 offset:3072
	global_load_lds_dwordx4 v204, s[66:67]
	s_add_i32 m0, s22, 0x2000
	s_nop 0
	global_load_lds_dwordx4 v208, s[66:67]
	s_barrier
	s_waitcnt lgkmcnt(0)
	s_setprio 1
	v_mfma_f32_16x16x32_bf16 v[104:107], v[180:183], v[148:151], v[104:107]
	v_mfma_f32_16x16x32_bf16 v[100:103], v[188:191], v[148:151], v[100:103]
	v_mfma_f32_16x16x32_bf16 v[96:99], v[180:183], v[156:159], v[96:99]
	v_mfma_f32_16x16x32_bf16 v[92:95], v[188:191], v[156:159], v[92:95]
	v_mfma_f32_16x16x32_bf16 v[88:91], v[180:183], v[164:167], v[88:91]
	v_mfma_f32_16x16x32_bf16 v[84:87], v[188:191], v[164:167], v[84:87]
	v_mfma_f32_16x16x32_bf16 v[80:83], v[180:183], v[172:175], v[80:83]
	v_mfma_f32_16x16x32_bf16 v[76:79], v[188:191], v[172:175], v[76:79]
	v_mfma_f32_16x16x32_bf16 v[104:107], v[184:187], v[152:155], v[104:107]
	v_mfma_f32_16x16x32_bf16 v[100:103], v[192:195], v[152:155], v[100:103]
	v_mfma_f32_16x16x32_bf16 v[96:99], v[184:187], v[160:163], v[96:99]
	v_mfma_f32_16x16x32_bf16 v[92:95], v[192:195], v[160:163], v[92:95]
	v_mfma_f32_16x16x32_bf16 v[88:91], v[184:187], v[168:171], v[88:91]
	v_mfma_f32_16x16x32_bf16 v[84:87], v[192:195], v[168:171], v[84:87]
	v_mfma_f32_16x16x32_bf16 v[80:83], v[184:187], v[176:179], v[80:83]
	v_mfma_f32_16x16x32_bf16 v[76:79], v[192:195], v[176:179], v[76:79]
	s_setprio 0
	s_mov_b32 m0, s70
	s_barrier
	ds_read_b128 v[148:151], v242 offset:16384
	ds_read_b128 v[152:155], v242 offset:17408
	ds_read_b128 v[156:159], v242 offset:18432
	ds_read_b128 v[160:163], v242 offset:19456
	ds_read_b128 v[164:167], v242 offset:20480
	ds_read_b128 v[168:171], v242 offset:21504
	ds_read_b128 v[172:175], v242 offset:22528
	ds_read_b128 v[176:179], v242 offset:23552
	global_load_lds_dwordx4 v202, s[68:69]
	s_mov_b32 m0, s71
	s_nop 0
	global_load_lds_dwordx4 v206, s[68:69]
	s_barrier
	s_waitcnt lgkmcnt(0)
	s_setprio 1
	v_mfma_f32_16x16x32_bf16 v[72:75], v[132:135], v[148:151], v[72:75]
	v_mfma_f32_16x16x32_bf16 v[68:71], v[140:143], v[148:151], v[68:71]
	v_mfma_f32_16x16x32_bf16 v[64:67], v[132:135], v[156:159], v[64:67]
	v_mfma_f32_16x16x32_bf16 v[60:63], v[140:143], v[156:159], v[60:63]
	v_mfma_f32_16x16x32_bf16 v[56:59], v[132:135], v[164:167], v[56:59]
	v_mfma_f32_16x16x32_bf16 v[52:55], v[140:143], v[164:167], v[52:55]
	v_mfma_f32_16x16x32_bf16 v[48:51], v[132:135], v[172:175], v[48:51]
	v_mfma_f32_16x16x32_bf16 v[44:47], v[140:143], v[172:175], v[44:47]
	v_mfma_f32_16x16x32_bf16 v[72:75], v[136:139], v[152:155], v[72:75]
	v_mfma_f32_16x16x32_bf16 v[68:71], v[144:147], v[152:155], v[68:71]
	v_mfma_f32_16x16x32_bf16 v[64:67], v[136:139], v[160:163], v[64:67]
	v_mfma_f32_16x16x32_bf16 v[60:63], v[144:147], v[160:163], v[60:63]
	v_mfma_f32_16x16x32_bf16 v[56:59], v[136:139], v[168:171], v[56:59]
	v_mfma_f32_16x16x32_bf16 v[52:55], v[144:147], v[168:171], v[52:55]
	v_mfma_f32_16x16x32_bf16 v[48:51], v[136:139], v[176:179], v[48:51]
	v_mfma_f32_16x16x32_bf16 v[44:47], v[144:147], v[176:179], v[44:47]
	s_setprio 0
	s_barrier
	s_add_u32 s44, s66, 0x20000
	s_addc_u32 s45, s67, 0
	s_add_i32 s22, s23, s53
	s_mov_b32 m0, s22
	s_nop 0
	global_load_lds_dwordx4 v204, s[44:45]
	s_add_i32 m0, s22, 0x2000
	s_nop 0
	global_load_lds_dwordx4 v208, s[44:45]
	s_waitcnt vmcnt(6)
	s_barrier
; #define PG8_STAGE(bufoff, gbase, voff) do { _Pragma("unroll") for (int _i = 0; _i < 2; ++_i) \
;         __builtin_amdgcn_global_load_lds((const unsigned*)((const char*)(gbase) + (voff)[_i]), (LAS unsigned*)(lds + (bufoff) + ldsw + _i * 8192), 16, 0, 0); } while (0)
; #define PG8_LDA(dst, b, h) do { _Pragma("unroll") for (int m = 0; m < 4; ++m) _Pragma("unroll") for (int k = 0; k < 2; ++k) dst[m][k] = *(const LAS bf16x8*)(lds + PG8_SA(b, h) + aoff + m * 2048 + k * 1024); } while (0)
; #define PG8_LDB(dst, b, h) do { _Pragma("unroll") for (int n = 0; n < 2; ++n) _Pragma("unroll") for (int k = 0; k < 2; ++k) dst[n][k] = *(const LAS bf16x8*)(lds + PG8_SB(b, h) + boff + n * 2048 + k * 1024); } while (0)
; #define PG8_MMA(ai, bj, At, Bt) do { __builtin_amdgcn_s_setprio(1); _Pragma("unroll") for (int m = 0; m < 4; ++m) _Pragma("unroll") for (int n = 0; n < 2; ++n) _Pragma("unroll") for (int k = 0; k < 2; ++k) \
;         acc[ai][bj][m][n] = __builtin_amdgcn_mfma_f32_16x16x32_bf16(Bt[n][k], At[m][k], acc[ai][bj][m][n], 0, 0, 0); __builtin_amdgcn_s_setprio(0); } while (0)
; #define PG8_WAIT_V(n) asm volatile("s_waitcnt vmcnt(" #n ")" ::: "memory")
; #define PG8_WAIT_L(n) asm volatile("s_waitcnt lgkmcnt(" #n ")" ::: "memory")
; #define PG8_BAR __builtin_amdgcn_s_barrier()
; #define PG8_SCHED __builtin_amdgcn_sched_barrier(0)
; template <class Epi>
; __device__ __forceinline__ void gemm_phase(LAS unsigned char* lds, const Gemm g, const StaticOrder& S, const Epi& E) {
;     ...
;             PG8_WAIT_V(6); PG8_BAR; PG8_MMA(1, 1, At, B1); PG8_BAR;
;             PG8_LDB(B0, 1, 0); PG8_SCHED; PG8_LDA(At, 1, 0); PG8_STAGE(PG8_SA(0, 1), a2 + hA, voffA);
;             PG8_WAIT_L(8); PG8_BAR; PG8_WAIT_L(0); PG8_MMA(0, 0, At, B0); PG8_BAR; PG8_SCHED;
;             PG8_LDB(B1, 1, 1); PG8_STAGE(PG8_SB(1, 0), b3, voffB);
;             PG8_BAR; PG8_WAIT_L(0); PG8_MMA(0, 1, At, B1); PG8_BAR;
;             PG8_LDA(At, 1, 1); PG8_STAGE(PG8_SA(1, 0), a3, voffA);
;             PG8_BAR; PG8_WAIT_L(0); PG8_MMA(1, 0, At, B0); PG8_BAR; PG8_SCHED;
	s_setprio 1
	v_mfma_f32_16x16x32_bf16 v[40:43], v[180:183], v[148:151], v[40:43]
	v_mfma_f32_16x16x32_bf16 v[36:39], v[188:191], v[148:151], v[36:39]
	v_mfma_f32_16x16x32_bf16 v[32:35], v[180:183], v[156:159], v[32:35]
	v_mfma_f32_16x16x32_bf16 v[28:31], v[188:191], v[156:159], v[28:31]
	v_mfma_f32_16x16x32_bf16 v[24:27], v[180:183], v[164:167], v[24:27]
	v_mfma_f32_16x16x32_bf16 v[20:23], v[188:191], v[164:167], v[20:23]
	v_mfma_f32_16x16x32_bf16 v[16:19], v[180:183], v[172:175], v[16:19]
	v_mfma_f32_16x16x32_bf16 v[12:15], v[188:191], v[172:175], v[12:15]
	v_mfma_f32_16x16x32_bf16 v[40:43], v[184:187], v[152:155], v[40:43]
	v_mfma_f32_16x16x32_bf16 v[36:39], v[192:195], v[152:155], v[36:39]
	v_mfma_f32_16x16x32_bf16 v[32:35], v[184:187], v[160:163], v[32:35]
	v_mfma_f32_16x16x32_bf16 v[28:31], v[192:195], v[160:163], v[28:31]
	v_mfma_f32_16x16x32_bf16 v[24:27], v[184:187], v[168:171], v[24:27]
	v_mfma_f32_16x16x32_bf16 v[20:23], v[192:195], v[168:171], v[20:23]
	v_mfma_f32_16x16x32_bf16 v[16:19], v[184:187], v[176:179], v[16:19]
	v_mfma_f32_16x16x32_bf16 v[12:15], v[192:195], v[176:179], v[12:15]
	s_setprio 0
	s_add_i32 s22, 0, 0x18000
	v_add_u32_e32 v0, s22, v241
	s_barrier
	ds_read_b128 v[132:135], v0
	ds_read_b128 v[136:139], v0 offset:1024
	ds_read_b128 v[140:143], v0 offset:2048
	ds_read_b128 v[144:147], v0 offset:3072
	s_add_u32 s44, s68, 0x110000
	s_addc_u32 s45, s69, 0
	s_mov_b32 m0, s74
	ds_read_b128 v[148:151], v242 offset:32768
	ds_read_b128 v[152:155], v242 offset:33792
	ds_read_b128 v[156:159], v242 offset:34816
	ds_read_b128 v[160:163], v242 offset:35840
	ds_read_b128 v[164:167], v242 offset:36864
	ds_read_b128 v[168:171], v242 offset:37888
	ds_read_b128 v[172:175], v242 offset:38912
	ds_read_b128 v[176:179], v242 offset:39936
	global_load_lds_dwordx4 v202, s[44:45]
	s_mov_b32 m0, s75
	s_nop 0
	global_load_lds_dwordx4 v206, s[44:45]
	s_waitcnt lgkmcnt(8)
	s_barrier
	s_waitcnt lgkmcnt(0)
	s_setprio 1
	v_mfma_f32_16x16x32_bf16 v[2:5], v[132:135], v[148:151], v[2:5]
	v_mfma_f32_16x16x32_bf16 v[8:11], v[140:143], v[148:151], v[8:11]
	v_mfma_f32_16x16x32_bf16 v[128:131], v[132:135], v[156:159], v[128:131]
	v_mfma_f32_16x16x32_bf16 v[124:127], v[140:143], v[156:159], v[124:127]
	v_mfma_f32_16x16x32_bf16 v[120:123], v[132:135], v[164:167], v[120:123]
	v_mfma_f32_16x16x32_bf16 v[116:119], v[140:143], v[164:167], v[116:119]
	v_mfma_f32_16x16x32_bf16 v[112:115], v[132:135], v[172:175], v[112:115]
	v_mfma_f32_16x16x32_bf16 v[108:111], v[140:143], v[172:175], v[108:111]
	v_mfma_f32_16x16x32_bf16 v[4:7], v[136:139], v[152:155], v[2:5]
	v_mfma_f32_16x16x32_bf16 v[8:11], v[144:147], v[152:155], v[8:11]
	v_mfma_f32_16x16x32_bf16 v[128:131], v[136:139], v[160:163], v[128:131]
	v_mfma_f32_16x16x32_bf16 v[124:127], v[144:147], v[160:163], v[124:127]
	v_mfma_f32_16x16x32_bf16 v[120:123], v[136:139], v[168:171], v[120:123]
	v_mfma_f32_16x16x32_bf16 v[116:119], v[144:147], v[168:171], v[116:119]
	v_mfma_f32_16x16x32_bf16 v[112:115], v[136:139], v[176:179], v[112:115]
	v_mfma_f32_16x16x32_bf16 v[108:111], v[144:147], v[176:179], v[108:111]
	s_setprio 0
	s_barrier
	s_add_i32 s23, 0, 0x1c000
	s_add_i32 s22, s22, s53
	v_add_u32_e32 v0, s23, v241
	s_mov_b32 m0, s22
	ds_read_b128 v[180:183], v0
	ds_read_b128 v[184:187], v0 offset:1024
	ds_read_b128 v[188:191], v0 offset:2048
	ds_read_b128 v[192:195], v0 offset:3072
	s_add_u32 s100, s66, 0x80
	s_addc_u32 s101, s67, 0
	global_load_lds_dwordx4 v204, s[100:101]
	s_add_i32 m0, s22, 0x2000
	s_nop 0
	global_load_lds_dwordx4 v208, s[100:101]
	s_barrier
	s_waitcnt lgkmcnt(0)
	s_setprio 1
	v_mfma_f32_16x16x32_bf16 v[104:107], v[180:183], v[148:151], v[104:107]
	v_mfma_f32_16x16x32_bf16 v[100:103], v[188:191], v[148:151], v[100:103]
	v_mfma_f32_16x16x32_bf16 v[96:99], v[180:183], v[156:159], v[96:99]
	v_mfma_f32_16x16x32_bf16 v[92:95], v[188:191], v[156:159], v[92:95]
	v_mfma_f32_16x16x32_bf16 v[88:91], v[180:183], v[164:167], v[88:91]
	v_mfma_f32_16x16x32_bf16 v[84:87], v[188:191], v[164:167], v[84:87]
	v_mfma_f32_16x16x32_bf16 v[80:83], v[180:183], v[172:175], v[80:83]
	v_mfma_f32_16x16x32_bf16 v[76:79], v[188:191], v[172:175], v[76:79]
	v_mfma_f32_16x16x32_bf16 v[104:107], v[184:187], v[152:155], v[104:107]
	v_mfma_f32_16x16x32_bf16 v[100:103], v[192:195], v[152:155], v[100:103]
	v_mfma_f32_16x16x32_bf16 v[96:99], v[184:187], v[160:163], v[96:99]
	v_mfma_f32_16x16x32_bf16 v[92:95], v[192:195], v[160:163], v[92:95]
	v_mfma_f32_16x16x32_bf16 v[88:91], v[184:187], v[168:171], v[88:91]
	v_mfma_f32_16x16x32_bf16 v[84:87], v[192:195], v[168:171], v[84:87]
	v_mfma_f32_16x16x32_bf16 v[80:83], v[184:187], v[176:179], v[80:83]
	v_mfma_f32_16x16x32_bf16 v[76:79], v[192:195], v[176:179], v[76:79]
	s_setprio 0
	s_mov_b32 m0, s30
	s_barrier
; #define PG8_STAGE(bufoff, gbase, voff) do { _Pragma("unroll") for (int _i = 0; _i < 2; ++_i) \
;         __builtin_amdgcn_global_load_lds((const unsigned*)((const char*)(gbase) + (voff)[_i]), (LAS unsigned*)(lds + (bufoff) + ldsw + _i * 8192), 16, 0, 0); } while (0)
; #define PG8_LDA(dst, b, h) do { _Pragma("unroll") for (int m = 0; m < 4; ++m) _Pragma("unroll") for (int k = 0; k < 2; ++k) dst[m][k] = *(const LAS bf16x8*)(lds + PG8_SA(b, h) + aoff + m * 2048 + k * 1024); } while (0)
; #define PG8_MMA(ai, bj, At, Bt) do { __builtin_amdgcn_s_setprio(1); _Pragma("unroll") for (int m = 0; m < 4; ++m) _Pragma("unroll") for (int n = 0; n < 2; ++n) _Pragma("unroll") for (int k = 0; k < 2; ++k) \
;         acc[ai][bj][m][n] = __builtin_amdgcn_mfma_f32_16x16x32_bf16(Bt[n][k], At[m][k], acc[ai][bj][m][n], 0, 0, 0); __builtin_amdgcn_s_setprio(0); } while (0)
; #define PG8_WAIT_V(n) asm volatile("s_waitcnt vmcnt(" #n ")" ::: "memory")
; #define PG8_WAIT_L(n) asm volatile("s_waitcnt lgkmcnt(" #n ")" ::: "memory")
; #define PG8_BAR __builtin_amdgcn_s_barrier()
; #define PG8_SCHED __builtin_amdgcn_sched_barrier(0)
; template <class Epi>
; __device__ __forceinline__ void gemm_phase(LAS unsigned char* lds, const Gemm g, const StaticOrder& S, const Epi& E) {
;     ...
;             PG8_LDA(At, 1, 1); PG8_STAGE(PG8_SA(1, 0), a3, voffA);
;             PG8_BAR; PG8_WAIT_L(0); PG8_MMA(1, 0, At, B0); PG8_BAR; PG8_SCHED;
;             PG8_STAGE(PG8_SB(1, 1), b3 + hB, voffB);
;             PG8_WAIT_V(6); PG8_BAR; PG8_MMA(1, 1, At, B1); PG8_BAR;
;         }
;     __device__ __forceinline__ void operator()(Acc& acc, const Unit& u, int wr, int wc, int fr, int fq) const {
;         asm volatile("" : "+v"(fr), "+v"(fq));
;         const int row0 = u.pm * 256 + wr * 64 + fr, col0 = u.pn * 256 + wc * 32 + 8 * fq;
; #pragma unroll
;         for (int ai = 0; ai < 2; ++ai) {
;             u32x4 av[4][2], bv[4][2];
; #pragma unroll
;             for (int m = 0; m < 4; ++m)
; #pragma unroll
;                 for (int bj = 0; bj < 2; ++bj) { const size_t off = (size_t)(row0 + ai * 128 + m * 16) * NPROJ + col0 + bj * 128;
;                     bv[m][bj] = *(const u32x4*)(gb + off); if (u.alt == 0) av[m][bj] = *(const u32x4*)(ga + off); }
	ds_read_b128 v[148:151], v242 offset:49152
	ds_read_b128 v[152:155], v242 offset:50176
	ds_read_b128 v[156:159], v242 offset:51200
	ds_read_b128 v[160:163], v242 offset:52224
	ds_read_b128 v[164:167], v242 offset:53248
	ds_read_b128 v[168:171], v242 offset:54272
	ds_read_b128 v[172:175], v242 offset:55296
	ds_read_b128 v[176:179], v242 offset:56320
	s_add_u32 s100, s68, 0x80
	s_addc_u32 s101, s69, 0
	global_load_lds_dwordx4 v202, s[100:101]
	s_mov_b32 m0, s46
	s_nop 0
	global_load_lds_dwordx4 v206, s[100:101]
	s_barrier
	s_waitcnt lgkmcnt(0)
	s_setprio 1
	v_mfma_f32_16x16x32_bf16 v[72:75], v[132:135], v[148:151], v[72:75]
	v_mfma_f32_16x16x32_bf16 v[68:71], v[140:143], v[148:151], v[68:71]
	v_mfma_f32_16x16x32_bf16 v[64:67], v[132:135], v[156:159], v[64:67]
	v_mfma_f32_16x16x32_bf16 v[60:63], v[140:143], v[156:159], v[60:63]
	v_mfma_f32_16x16x32_bf16 v[56:59], v[132:135], v[164:167], v[56:59]
	v_mfma_f32_16x16x32_bf16 v[52:55], v[140:143], v[164:167], v[52:55]
	v_mfma_f32_16x16x32_bf16 v[48:51], v[132:135], v[172:175], v[48:51]
	v_mfma_f32_16x16x32_bf16 v[44:47], v[140:143], v[172:175], v[44:47]
	v_mfma_f32_16x16x32_bf16 v[72:75], v[136:139], v[152:155], v[72:75]
	v_mfma_f32_16x16x32_bf16 v[68:71], v[144:147], v[152:155], v[68:71]
	v_mfma_f32_16x16x32_bf16 v[64:67], v[136:139], v[160:163], v[64:67]
	v_mfma_f32_16x16x32_bf16 v[60:63], v[144:147], v[160:163], v[60:63]
	v_mfma_f32_16x16x32_bf16 v[56:59], v[136:139], v[168:171], v[56:59]
	v_mfma_f32_16x16x32_bf16 v[52:55], v[144:147], v[168:171], v[52:55]
	v_mfma_f32_16x16x32_bf16 v[48:51], v[136:139], v[176:179], v[48:51]
	v_mfma_f32_16x16x32_bf16 v[44:47], v[144:147], v[176:179], v[44:47]
	s_setprio 0
	s_barrier
	s_add_u32 s44, s66, 0x20080
	s_addc_u32 s45, s67, 0
	s_add_i32 s22, s23, s53
	s_mov_b32 m0, s22
	s_nop 0
	global_load_lds_dwordx4 v204, s[44:45]
	s_add_i32 m0, s22, 0x2000
	s_nop 0
	global_load_lds_dwordx4 v208, s[44:45]
	s_waitcnt vmcnt(6)
	s_barrier
	s_setprio 1
	v_mfma_f32_16x16x32_bf16 v[40:43], v[180:183], v[148:151], v[40:43]
	v_mfma_f32_16x16x32_bf16 v[36:39], v[188:191], v[148:151], v[36:39]
	v_mfma_f32_16x16x32_bf16 v[32:35], v[180:183], v[156:159], v[32:35]
	v_mfma_f32_16x16x32_bf16 v[28:31], v[188:191], v[156:159], v[28:31]
	v_mfma_f32_16x16x32_bf16 v[24:27], v[180:183], v[164:167], v[24:27]
	v_mfma_f32_16x16x32_bf16 v[20:23], v[188:191], v[164:167], v[20:23]
	v_mfma_f32_16x16x32_bf16 v[16:19], v[180:183], v[172:175], v[16:19]
	v_mfma_f32_16x16x32_bf16 v[12:15], v[188:191], v[172:175], v[12:15]
	v_mfma_f32_16x16x32_bf16 v[40:43], v[184:187], v[152:155], v[40:43]
	v_mfma_f32_16x16x32_bf16 v[36:39], v[192:195], v[152:155], v[36:39]
	v_mfma_f32_16x16x32_bf16 v[32:35], v[184:187], v[160:163], v[32:35]
	v_mfma_f32_16x16x32_bf16 v[28:31], v[192:195], v[160:163], v[28:31]
	v_mfma_f32_16x16x32_bf16 v[24:27], v[184:187], v[168:171], v[24:27]
	v_mfma_f32_16x16x32_bf16 v[20:23], v[192:195], v[168:171], v[20:23]
	v_mfma_f32_16x16x32_bf16 v[16:19], v[184:187], v[176:179], v[16:19]
	v_mfma_f32_16x16x32_bf16 v[12:15], v[192:195], v[176:179], v[12:15]
	s_setprio 0
	s_add_i32 vcc_lo, vcc_lo, 2
	s_add_u32 s59, s59, 0x100
	s_addc_u32 s97, s97, 0
	s_cmp_gt_u32 vcc_lo, 5
	s_mov_b64 s[44:45], s[64:65]
	s_barrier
	s_cbranch_scc0 .LBB0_263
	s_lshl_b32 s22, s33, 8
	v_mov_b32_e32 v0, v240
	v_mov_b32_e32 v2, v239
	s_add_i32 s22, s22, s51
	s_nop 0
	v_add_u32_e32 v214, s22, v2
	s_lshl_b32 s22, s42, 8
	s_or_b32 s22, s22, s76
	v_lshl_add_u32 v2, v0, 3, s22
	v_ashrrev_i32_e32 v3, 31, v2
	v_mad_i64_i32 v[132:133], s[42:43], v214, s1, v[2:3]
	v_lshl_add_u64 v[134:135], v[132:133], 1, s[56:57]
	global_load_dwordx4 v[192:195], v[134:135], off
	s_cmp_eq_u32 s48, 0
	s_cselect_b64 s[42:43], -1, 0
	s_cmp_lg_u32 s48, 0
	s_cselect_b64 s[64:65], -1, 0
	s_and_b64 vcc, exec, s[64:65]
	s_cbranch_vccnz .LBB0_266
	v_lshl_add_u64 v[136:137], v[132:133], 1, s[54:55]
	global_load_dwordx4 v[160:163], v[136:137], off

; #define PG8_STAGE(bufoff, gbase, voff) do { _Pragma("unroll") for (int _i = 0; _i < 2; ++_i) \
;         __builtin_amdgcn_global_load_lds((const unsigned*)((const char*)(gbase) + (voff)[_i]), (LAS unsigned*)(lds + (bufoff) + ldsw + _i * 8192), 16, 0, 0); } while (0)
; #define PG8_LDA(dst, b, h) do { _Pragma("unroll") for (int m = 0; m < 4; ++m) _Pragma("unroll") for (int k = 0; k < 2; ++k) dst[m][k] = *(const LAS bf16x8*)(lds + PG8_SA(b, h) + aoff + m * 2048 + k * 1024); } while (0)
; #define PG8_LDB(dst, b, h) do { _Pragma("unroll") for (int n = 0; n < 2; ++n) _Pragma("unroll") for (int k = 0; k < 2; ++k) dst[n][k] = *(const LAS bf16x8*)(lds + PG8_SB(b, h) + boff + n * 2048 + k * 1024); } while (0)
; #define PG8_MMA(ai, bj, At, Bt) do { __builtin_amdgcn_s_setprio(1); _Pragma("unroll") for (int m = 0; m < 4; ++m) _Pragma("unroll") for (int n = 0; n < 2; ++n) _Pragma("unroll") for (int k = 0; k < 2; ++k) \
;         acc[ai][bj][m][n] = __builtin_amdgcn_mfma_f32_16x16x32_bf16(Bt[n][k], At[m][k], acc[ai][bj][m][n], 0, 0, 0); __builtin_amdgcn_s_setprio(0); } while (0)
; #define PG8_WAIT_V(n) asm volatile("s_waitcnt vmcnt(" #n ")" ::: "memory")
; #define PG8_WAIT_L(n) asm volatile("s_waitcnt lgkmcnt(" #n ")" ::: "memory")
; #define PG8_BAR __builtin_amdgcn_s_barrier()
; template <class Epi>
; __device__ __forceinline__ void gemm_phase(LAS unsigned char* lds, const Gemm g, const StaticOrder& S, const Epi& E) {
;     ...
;         for (int t = 0; t < nt; t += 2) {
;             const bool last = (t == nt - 2);
;             const char* a1 = cA + (size_t)(t + 1) * kstep;
;             const char* a2 = last ? nA : cA + (size_t)(t + 2) * kstep; const char* b2 = last ? nB : cB + (size_t)(t + 2) * kstep;
;             const char* a3 = a2 + kstep; const char* b3 = b2 + kstep;
;             PG8_LDB(B0, 0, 0); PG8_SCHED; PG8_LDA(At, 0, 0); PG8_STAGE(PG8_SA(1, 1), a1 + hA, voffA);
;             PG8_WAIT_L(8); PG8_BAR; PG8_WAIT_L(0); PG8_MMA(0, 0, At, B0); PG8_BAR; PG8_SCHED;
;             PG8_LDB(B1, 0, 1); PG8_STAGE(PG8_SB(0, 0), b2, voffB);
;             PG8_BAR; PG8_WAIT_L(0); PG8_MMA(0, 1, At, B1); PG8_BAR;
;             PG8_LDA(At, 0, 1); PG8_STAGE(PG8_SA(0, 0), a2, voffA);
;             PG8_BAR; PG8_WAIT_L(0); PG8_MMA(1, 0, At, B0); PG8_BAR; PG8_SCHED;
;             PG8_STAGE(PG8_SB(0, 1), b2 + hB, voffB);
;             PG8_WAIT_V(6); PG8_BAR; PG8_MMA(1, 1, At, B1); PG8_BAR;
.LBB0_387:
	s_add_u32 s42, s60, 0x100
	s_addc_u32 s43, s61, 0
	s_add_i32 s22, 0, 0x10000
	v_add_u32_e32 v62, s22, v204
	ds_read_b128 v[38:41], v62
	ds_read_b128 v[46:49], v62 offset:1024
	ds_read_b128 v[54:57], v62 offset:2048
	ds_read_b128 v[62:65], v62 offset:3072
	s_cmp_eq_u32 s97, 4
	s_cselect_b32 s65, s57, s43
	s_cselect_b32 s64, s56, s42
	s_cselect_b32 s63, s49, s55
	s_cselect_b32 s62, s50, s51
	s_add_i32 m0, s68, 0xc000
	ds_read_b128 v[122:125], v205
	ds_read_b128 v[130:133], v205 offset:1024
	ds_read_b128 v[146:149], v205 offset:2048
	ds_read_b128 v[150:153], v205 offset:3072
	ds_read_b128 v[158:161], v205 offset:4096
	ds_read_b128 v[166:169], v205 offset:5120
	ds_read_b128 v[170:173], v205 offset:6144
	ds_read_b128 v[184:187], v205 offset:7168
	global_load_lds_dwordx4 v180, s[60:61]
	s_add_i32 m0, s68, 0xe000
	s_nop 0
	global_load_lds_dwordx4 v182, s[60:61]
	s_waitcnt lgkmcnt(8)
	s_barrier
	s_waitcnt lgkmcnt(0)
	s_setprio 1
	v_mfma_f32_16x16x32_bf16 v[162:165], v[38:41], v[122:125], v[162:165]
	v_mfma_f32_16x16x32_bf16 v[154:157], v[54:57], v[122:125], v[154:157]
	v_mfma_f32_16x16x32_bf16 v[134:137], v[38:41], v[146:149], v[134:137]
	v_mfma_f32_16x16x32_bf16 v[126:129], v[54:57], v[146:149], v[126:129]
	v_mfma_f32_16x16x32_bf16 v[110:113], v[38:41], v[158:161], v[110:113]
	v_mfma_f32_16x16x32_bf16 v[106:109], v[54:57], v[158:161], v[106:109]
	v_mfma_f32_16x16x32_bf16 v[94:97], v[38:41], v[170:173], v[94:97]
	v_mfma_f32_16x16x32_bf16 v[90:93], v[54:57], v[170:173], v[90:93]
	v_mfma_f32_16x16x32_bf16 v[162:165], v[46:49], v[130:133], v[162:165]
	v_mfma_f32_16x16x32_bf16 v[154:157], v[62:65], v[130:133], v[154:157]
	v_mfma_f32_16x16x32_bf16 v[134:137], v[46:49], v[150:153], v[134:137]
	v_mfma_f32_16x16x32_bf16 v[126:129], v[62:65], v[150:153], v[126:129]
	v_mfma_f32_16x16x32_bf16 v[110:113], v[46:49], v[166:169], v[110:113]
	v_mfma_f32_16x16x32_bf16 v[106:109], v[62:65], v[166:169], v[106:109]
	v_mfma_f32_16x16x32_bf16 v[94:97], v[46:49], v[184:187], v[94:97]
	v_mfma_f32_16x16x32_bf16 v[90:93], v[62:65], v[184:187], v[90:93]
	s_setprio 0
	s_barrier
	s_add_i32 s23, 0, 0x14000
	s_add_i32 s22, s22, s67
	v_add_u32_e32 v210, s23, v204
	s_mov_b32 m0, s22
	ds_read_b128 v[188:191], v210
	ds_read_b128 v[192:195], v210 offset:1024
	ds_read_b128 v[206:209], v210 offset:2048
	ds_read_b128 v[210:213], v210 offset:3072
	global_load_lds_dwordx4 v0, s[62:63]
	s_add_i32 m0, s22, 0x2000
	s_nop 0
	global_load_lds_dwordx4 v178, s[62:63]
	s_barrier
	s_waitcnt lgkmcnt(0)
	s_setprio 1
	v_mfma_f32_16x16x32_bf16 v[142:145], v[188:191], v[122:125], v[142:145]
	v_mfma_f32_16x16x32_bf16 v[118:121], v[188:191], v[146:149], v[118:121]
	v_mfma_f32_16x16x32_bf16 v[114:117], v[206:209], v[146:149], v[114:117]
	v_mfma_f32_16x16x32_bf16 v[102:105], v[188:191], v[158:161], v[102:105]
	v_mfma_f32_16x16x32_bf16 v[98:101], v[206:209], v[158:161], v[98:101]
	v_mfma_f32_16x16x32_bf16 v[86:89], v[188:191], v[170:173], v[86:89]
	v_mfma_f32_16x16x32_bf16 v[82:85], v[206:209], v[170:173], v[82:85]
	v_mfma_f32_16x16x32_bf16 v[142:145], v[192:195], v[130:133], v[142:145]
	v_mfma_f32_16x16x32_bf16 v[122:125], v[206:209], v[122:125], v[138:141]
	v_mfma_f32_16x16x32_bf16 v[118:121], v[192:195], v[150:153], v[118:121]
	v_mfma_f32_16x16x32_bf16 v[114:117], v[210:213], v[150:153], v[114:117]
	v_mfma_f32_16x16x32_bf16 v[102:105], v[192:195], v[166:169], v[102:105]
	v_mfma_f32_16x16x32_bf16 v[98:101], v[210:213], v[166:169], v[98:101]
	v_mfma_f32_16x16x32_bf16 v[86:89], v[192:195], v[184:187], v[86:89]
	v_mfma_f32_16x16x32_bf16 v[82:85], v[210:213], v[184:187], v[82:85]
	v_mfma_f32_16x16x32_bf16 v[122:125], v[210:213], v[130:133], v[122:125]
	s_setprio 0
	s_mov_b32 m0, s68
	s_barrier
	ds_read_b128 v[130:133], v205 offset:16384
	ds_read_b128 v[138:141], v205 offset:17408
	ds_read_b128 v[146:149], v205 offset:18432
	ds_read_b128 v[150:153], v205 offset:19456
	ds_read_b128 v[158:161], v205 offset:20480
	ds_read_b128 v[166:169], v205 offset:21504
	ds_read_b128 v[170:173], v205 offset:22528
	ds_read_b128 v[184:187], v205 offset:23552
	global_load_lds_dwordx4 v174, s[64:65]
	s_mov_b32 m0, s69
	s_nop 0
	global_load_lds_dwordx4 v176, s[64:65]
	s_barrier
	s_waitcnt lgkmcnt(0)
	s_setprio 1
	v_mfma_f32_16x16x32_bf16 v[78:81], v[38:41], v[130:133], v[78:81]
	v_mfma_f32_16x16x32_bf16 v[74:77], v[54:57], v[130:133], v[74:77]
	v_mfma_f32_16x16x32_bf16 v[58:61], v[38:41], v[146:149], v[58:61]
	v_mfma_f32_16x16x32_bf16 v[50:53], v[54:57], v[146:149], v[50:53]
	v_mfma_f32_16x16x32_bf16 v[30:33], v[38:41], v[158:161], v[30:33]
	v_mfma_f32_16x16x32_bf16 v[26:29], v[54:57], v[158:161], v[26:29]
	v_mfma_f32_16x16x32_bf16 v[14:17], v[38:41], v[170:173], v[14:17]
	v_mfma_f32_16x16x32_bf16 v[10:13], v[54:57], v[170:173], v[10:13]
	v_mfma_f32_16x16x32_bf16 v[78:81], v[46:49], v[138:141], v[78:81]
	v_mfma_f32_16x16x32_bf16 v[74:77], v[62:65], v[138:141], v[74:77]
	v_mfma_f32_16x16x32_bf16 v[58:61], v[46:49], v[150:153], v[58:61]
	v_mfma_f32_16x16x32_bf16 v[50:53], v[62:65], v[150:153], v[50:53]
	v_mfma_f32_16x16x32_bf16 v[30:33], v[46:49], v[166:169], v[30:33]
	v_mfma_f32_16x16x32_bf16 v[26:29], v[62:65], v[166:169], v[26:29]
	v_mfma_f32_16x16x32_bf16 v[14:17], v[46:49], v[184:187], v[14:17]
	v_mfma_f32_16x16x32_bf16 v[10:13], v[62:65], v[184:187], v[10:13]
	s_setprio 0
	s_barrier
	s_add_u32 s60, s62, 0x20000
	s_addc_u32 s61, s63, 0
	s_add_i32 s22, s23, s67
	s_mov_b32 m0, s22
	s_nop 0
	global_load_lds_dwordx4 v0, s[60:61]
	s_add_i32 m0, s22, 0x2000
	s_nop 0
	global_load_lds_dwordx4 v178, s[60:61]
	s_waitcnt vmcnt(6)
	s_barrier
; #define PG8_STAGE(bufoff, gbase, voff) do { _Pragma("unroll") for (int _i = 0; _i < 2; ++_i) \
;         __builtin_amdgcn_global_load_lds((const unsigned*)((const char*)(gbase) + (voff)[_i]), (LAS unsigned*)(lds + (bufoff) + ldsw + _i * 8192), 16, 0, 0); } while (0)
; #define PG8_LDA(dst, b, h) do { _Pragma("unroll") for (int m = 0; m < 4; ++m) _Pragma("unroll") for (int k = 0; k < 2; ++k) dst[m][k] = *(const LAS bf16x8*)(lds + PG8_SA(b, h) + aoff + m * 2048 + k * 1024); } while (0)
; #define PG8_LDB(dst, b, h) do { _Pragma("unroll") for (int n = 0; n < 2; ++n) _Pragma("unroll") for (int k = 0; k < 2; ++k) dst[n][k] = *(const LAS bf16x8*)(lds + PG8_SB(b, h) + boff + n * 2048 + k * 1024); } while (0)
; #define PG8_MMA(ai, bj, At, Bt) do { __builtin_amdgcn_s_setprio(1); _Pragma("unroll") for (int m = 0; m < 4; ++m) _Pragma("unroll") for (int n = 0; n < 2; ++n) _Pragma("unroll") for (int k = 0; k < 2; ++k) \
;         acc[ai][bj][m][n] = __builtin_amdgcn_mfma_f32_16x16x32_bf16(Bt[n][k], At[m][k], acc[ai][bj][m][n], 0, 0, 0); __builtin_amdgcn_s_setprio(0); } while (0)
; #define PG8_WAIT_V(n) asm volatile("s_waitcnt vmcnt(" #n ")" ::: "memory")
; #define PG8_WAIT_L(n) asm volatile("s_waitcnt lgkmcnt(" #n ")" ::: "memory")
; #define PG8_BAR __builtin_amdgcn_s_barrier()
; #define PG8_SCHED __builtin_amdgcn_sched_barrier(0)
; template <class Epi>
; __device__ __forceinline__ void gemm_phase(LAS unsigned char* lds, const Gemm g, const StaticOrder& S, const Epi& E) {
;     ...
;             PG8_WAIT_V(6); PG8_BAR; PG8_MMA(1, 1, At, B1); PG8_BAR;
;             PG8_LDB(B0, 1, 0); PG8_SCHED; PG8_LDA(At, 1, 0); PG8_STAGE(PG8_SA(0, 1), a2 + hA, voffA);
;             PG8_WAIT_L(8); PG8_BAR; PG8_WAIT_L(0); PG8_MMA(0, 0, At, B0); PG8_BAR; PG8_SCHED;
;             PG8_LDB(B1, 1, 1); PG8_STAGE(PG8_SB(1, 0), b3, voffB);
;             PG8_BAR; PG8_WAIT_L(0); PG8_MMA(0, 1, At, B1); PG8_BAR;
;             PG8_LDA(At, 1, 1); PG8_STAGE(PG8_SA(1, 0), a3, voffA);
;             PG8_BAR; PG8_WAIT_L(0); PG8_MMA(1, 0, At, B0); PG8_BAR; PG8_SCHED;
	s_setprio 1
	v_mfma_f32_16x16x32_bf16 v[42:45], v[188:191], v[146:149], v[42:45]
	v_mfma_f32_16x16x32_bf16 v[34:37], v[206:209], v[146:149], v[34:37]
	v_mfma_f32_16x16x32_bf16 v[22:25], v[188:191], v[158:161], v[22:25]
	v_mfma_f32_16x16x32_bf16 v[18:21], v[206:209], v[158:161], v[18:21]
	v_mfma_f32_16x16x32_bf16 v[6:9], v[188:191], v[170:173], v[6:9]
	v_mfma_f32_16x16x32_bf16 v[2:5], v[206:209], v[170:173], v[2:5]
	v_mfma_f32_16x16x32_bf16 v[38:41], v[188:191], v[130:133], v[70:73]
	v_mfma_f32_16x16x32_bf16 v[46:49], v[206:209], v[130:133], v[66:69]
	v_mfma_f32_16x16x32_bf16 v[42:45], v[192:195], v[150:153], v[42:45]
	v_mfma_f32_16x16x32_bf16 v[34:37], v[210:213], v[150:153], v[34:37]
	v_mfma_f32_16x16x32_bf16 v[22:25], v[192:195], v[166:169], v[22:25]
	v_mfma_f32_16x16x32_bf16 v[18:21], v[210:213], v[166:169], v[18:21]
	v_mfma_f32_16x16x32_bf16 v[6:9], v[192:195], v[184:187], v[6:9]
	v_mfma_f32_16x16x32_bf16 v[2:5], v[210:213], v[184:187], v[2:5]
	v_mfma_f32_16x16x32_bf16 v[38:41], v[192:195], v[138:141], v[38:41]
	v_mfma_f32_16x16x32_bf16 v[46:49], v[210:213], v[138:141], v[46:49]
	s_setprio 0
	s_add_i32 s22, 0, 0x18000
	v_add_u32_e32 v70, s22, v204
	s_barrier
	ds_read_b128 v[54:57], v70
	ds_read_b128 v[62:65], v70 offset:1024
	ds_read_b128 v[66:69], v70 offset:2048
	ds_read_b128 v[70:73], v70 offset:3072
	s_add_u32 s60, s64, 0x110000
	s_addc_u32 s61, s65, 0
	s_mov_b32 m0, s70
	ds_read_b128 v[130:133], v205 offset:32768
	ds_read_b128 v[138:141], v205 offset:33792
	ds_read_b128 v[146:149], v205 offset:34816
	ds_read_b128 v[150:153], v205 offset:35840
	ds_read_b128 v[158:161], v205 offset:36864
	ds_read_b128 v[166:169], v205 offset:37888
	ds_read_b128 v[170:173], v205 offset:38912
	ds_read_b128 v[184:187], v205 offset:39936
	global_load_lds_dwordx4 v174, s[60:61]
	s_mov_b32 m0, s71
	s_nop 0
	global_load_lds_dwordx4 v176, s[60:61]
	s_waitcnt lgkmcnt(8)
	s_barrier
	s_waitcnt lgkmcnt(0)
	s_setprio 1
	v_mfma_f32_16x16x32_bf16 v[162:165], v[54:57], v[130:133], v[162:165]
	v_mfma_f32_16x16x32_bf16 v[154:157], v[66:69], v[130:133], v[154:157]
	v_mfma_f32_16x16x32_bf16 v[134:137], v[54:57], v[146:149], v[134:137]
	v_mfma_f32_16x16x32_bf16 v[126:129], v[66:69], v[146:149], v[126:129]
	v_mfma_f32_16x16x32_bf16 v[110:113], v[54:57], v[158:161], v[110:113]
	v_mfma_f32_16x16x32_bf16 v[106:109], v[66:69], v[158:161], v[106:109]
	v_mfma_f32_16x16x32_bf16 v[94:97], v[54:57], v[170:173], v[94:97]
	v_mfma_f32_16x16x32_bf16 v[90:93], v[66:69], v[170:173], v[90:93]
	v_mfma_f32_16x16x32_bf16 v[162:165], v[62:65], v[138:141], v[162:165]
	v_mfma_f32_16x16x32_bf16 v[154:157], v[70:73], v[138:141], v[154:157]
	v_mfma_f32_16x16x32_bf16 v[134:137], v[62:65], v[150:153], v[134:137]
	v_mfma_f32_16x16x32_bf16 v[126:129], v[70:73], v[150:153], v[126:129]
	v_mfma_f32_16x16x32_bf16 v[110:113], v[62:65], v[166:169], v[110:113]
	v_mfma_f32_16x16x32_bf16 v[106:109], v[70:73], v[166:169], v[106:109]
	v_mfma_f32_16x16x32_bf16 v[94:97], v[62:65], v[184:187], v[94:97]
	v_mfma_f32_16x16x32_bf16 v[90:93], v[70:73], v[184:187], v[90:93]
	s_setprio 0
	s_barrier
	s_add_i32 s23, 0, 0x1c000
	s_add_i32 s22, s22, s67
	v_add_u32_e32 v210, s23, v204
	s_mov_b32 m0, s22
	ds_read_b128 v[188:191], v210
	ds_read_b128 v[192:195], v210 offset:1024
	ds_read_b128 v[206:209], v210 offset:2048
	ds_read_b128 v[210:213], v210 offset:3072
	s_add_u32 s100, s62, 0x80
	s_addc_u32 s101, s63, 0
	global_load_lds_dwordx4 v0, s[100:101]
	s_add_i32 m0, s22, 0x2000
	s_nop 0
	global_load_lds_dwordx4 v178, s[100:101]
	s_barrier
	s_waitcnt lgkmcnt(0)
	s_setprio 1
	v_mfma_f32_16x16x32_bf16 v[142:145], v[188:191], v[130:133], v[142:145]
	v_mfma_f32_16x16x32_bf16 v[122:125], v[206:209], v[130:133], v[122:125]
	v_mfma_f32_16x16x32_bf16 v[118:121], v[188:191], v[146:149], v[118:121]
	v_mfma_f32_16x16x32_bf16 v[114:117], v[206:209], v[146:149], v[114:117]
	v_mfma_f32_16x16x32_bf16 v[102:105], v[188:191], v[158:161], v[102:105]
	v_mfma_f32_16x16x32_bf16 v[98:101], v[206:209], v[158:161], v[98:101]
	v_mfma_f32_16x16x32_bf16 v[86:89], v[188:191], v[170:173], v[86:89]
	v_mfma_f32_16x16x32_bf16 v[82:85], v[206:209], v[170:173], v[82:85]
	v_mfma_f32_16x16x32_bf16 v[142:145], v[192:195], v[138:141], v[142:145]
	v_mfma_f32_16x16x32_bf16 v[138:141], v[210:213], v[138:141], v[122:125]
	v_mfma_f32_16x16x32_bf16 v[118:121], v[192:195], v[150:153], v[118:121]
	v_mfma_f32_16x16x32_bf16 v[114:117], v[210:213], v[150:153], v[114:117]
	v_mfma_f32_16x16x32_bf16 v[102:105], v[192:195], v[166:169], v[102:105]
	v_mfma_f32_16x16x32_bf16 v[98:101], v[210:213], v[166:169], v[98:101]
	v_mfma_f32_16x16x32_bf16 v[86:89], v[192:195], v[184:187], v[86:89]
	v_mfma_f32_16x16x32_bf16 v[82:85], v[210:213], v[184:187], v[82:85]
	s_setprio 0
	s_mov_b32 m0, s75
	s_barrier
	ds_read_b128 v[122:125], v205 offset:49152
	ds_read_b128 v[130:133], v205 offset:50176
	ds_read_b128 v[146:149], v205 offset:51200
	ds_read_b128 v[150:153], v205 offset:52224
	ds_read_b128 v[158:161], v205 offset:53248
	ds_read_b128 v[166:169], v205 offset:54272
	ds_read_b128 v[170:173], v205 offset:55296
	ds_read_b128 v[184:187], v205 offset:56320
	s_add_u32 s100, s64, 0x80
	s_addc_u32 s101, s65, 0
	global_load_lds_dwordx4 v174, s[100:101]
	s_mov_b32 m0, s76
	s_nop 0
	global_load_lds_dwordx4 v176, s[100:101]
	s_barrier
; #define PG8_STAGE(bufoff, gbase, voff) do { _Pragma("unroll") for (int _i = 0; _i < 2; ++_i) \
;         __builtin_amdgcn_global_load_lds((const unsigned*)((const char*)(gbase) + (voff)[_i]), (LAS unsigned*)(lds + (bufoff) + ldsw + _i * 8192), 16, 0, 0); } while (0)
; #define PG8_MMA(ai, bj, At, Bt) do { __builtin_amdgcn_s_setprio(1); _Pragma("unroll") for (int m = 0; m < 4; ++m) _Pragma("unroll") for (int n = 0; n < 2; ++n) _Pragma("unroll") for (int k = 0; k < 2; ++k) \
;         acc[ai][bj][m][n] = __builtin_amdgcn_mfma_f32_16x16x32_bf16(Bt[n][k], At[m][k], acc[ai][bj][m][n], 0, 0, 0); __builtin_amdgcn_s_setprio(0); } while (0)
; #define PG8_WAIT_V(n) asm volatile("s_waitcnt vmcnt(" #n ")" ::: "memory")
; #define PG8_WAIT_L(n) asm volatile("s_waitcnt lgkmcnt(" #n ")" ::: "memory")
; #define PG8_BAR __builtin_amdgcn_s_barrier()
; #define PG8_SCHED __builtin_amdgcn_sched_barrier(0)
; template <class Epi>
; __device__ __forceinline__ void gemm_phase(LAS unsigned char* lds, const Gemm g, const StaticOrder& S, const Epi& E) {
;     ...
;             PG8_BAR; PG8_WAIT_L(0); PG8_MMA(1, 0, At, B0); PG8_BAR; PG8_SCHED;
;             PG8_STAGE(PG8_SB(1, 1), b3 + hB, voffB);
;             PG8_WAIT_V(6); PG8_BAR; PG8_MMA(1, 1, At, B1); PG8_BAR;
;         }
;     __device__ __forceinline__ void operator()(const Acc& acc, const Unit& u, int wr, int wc, int fr, int fq) const {
;         asm volatile("" : "+v"(fr), "+v"(fq));
;         const int row0 = u.pm * 256 + wr * 64 + fr, col0 = u.pn * 256 + wc * 32 + 8 * fq;
;         f32x4 bv[2][2];
; #pragma unroll
;         for (int bj = 0; bj < 2; ++bj)
; #pragma unroll
;             for (int n = 0; n < 2; ++n) bv[bj][n] = *(const f32x4*)(bias + col0 + bj * 128 + 4 * n);
; #pragma unroll
;         for (int ai = 0; ai < 2; ++ai) {
;             u32x4 av[4][2];
; #pragma unroll
;             for (int m = 0; m < 4; ++m)
; #pragma unroll
;                 for (int bj = 0; bj < 2; ++bj) av[m][bj] = *(const u32x4*)(proj + (size_t)(row0 + ai * 128 + m * 16) * NPROJ + col0 + bj * 128);
	s_waitcnt lgkmcnt(0)
	s_setprio 1
	v_mfma_f32_16x16x32_bf16 v[78:81], v[54:57], v[122:125], v[78:81]
	v_mfma_f32_16x16x32_bf16 v[74:77], v[66:69], v[122:125], v[74:77]
	v_mfma_f32_16x16x32_bf16 v[58:61], v[54:57], v[146:149], v[58:61]
	v_mfma_f32_16x16x32_bf16 v[50:53], v[66:69], v[146:149], v[50:53]
	v_mfma_f32_16x16x32_bf16 v[30:33], v[54:57], v[158:161], v[30:33]
	v_mfma_f32_16x16x32_bf16 v[26:29], v[66:69], v[158:161], v[26:29]
	v_mfma_f32_16x16x32_bf16 v[14:17], v[54:57], v[170:173], v[14:17]
	v_mfma_f32_16x16x32_bf16 v[10:13], v[66:69], v[170:173], v[10:13]
	v_mfma_f32_16x16x32_bf16 v[78:81], v[62:65], v[130:133], v[78:81]
	v_mfma_f32_16x16x32_bf16 v[74:77], v[70:73], v[130:133], v[74:77]
	v_mfma_f32_16x16x32_bf16 v[58:61], v[62:65], v[150:153], v[58:61]
	v_mfma_f32_16x16x32_bf16 v[50:53], v[70:73], v[150:153], v[50:53]
	v_mfma_f32_16x16x32_bf16 v[30:33], v[62:65], v[166:169], v[30:33]
	v_mfma_f32_16x16x32_bf16 v[26:29], v[70:73], v[166:169], v[26:29]
	v_mfma_f32_16x16x32_bf16 v[14:17], v[62:65], v[184:187], v[14:17]
	v_mfma_f32_16x16x32_bf16 v[10:13], v[70:73], v[184:187], v[10:13]
	s_setprio 0
	s_barrier
	s_add_u32 s60, s62, 0x20080
	s_addc_u32 s61, s63, 0
	s_add_i32 s22, s23, s67
	s_mov_b32 m0, s22
	s_nop 0
	global_load_lds_dwordx4 v0, s[60:61]
	s_add_i32 m0, s22, 0x2000
	s_nop 0
	global_load_lds_dwordx4 v178, s[60:61]
	s_waitcnt vmcnt(6)
	s_barrier
	s_setprio 1
	v_mfma_f32_16x16x32_bf16 v[38:41], v[188:191], v[122:125], v[38:41]
	v_mfma_f32_16x16x32_bf16 v[70:73], v[192:195], v[130:133], v[38:41]
	v_mfma_f32_16x16x32_bf16 v[38:41], v[206:209], v[122:125], v[46:49]
	v_mfma_f32_16x16x32_bf16 v[66:69], v[210:213], v[130:133], v[38:41]
	v_mfma_f32_16x16x32_bf16 v[38:41], v[188:191], v[146:149], v[42:45]
	v_mfma_f32_16x16x32_bf16 v[34:37], v[206:209], v[146:149], v[34:37]
	v_mfma_f32_16x16x32_bf16 v[22:25], v[188:191], v[158:161], v[22:25]
	v_mfma_f32_16x16x32_bf16 v[18:21], v[206:209], v[158:161], v[18:21]
	v_mfma_f32_16x16x32_bf16 v[6:9], v[188:191], v[170:173], v[6:9]
	v_mfma_f32_16x16x32_bf16 v[2:5], v[206:209], v[170:173], v[2:5]
	v_mfma_f32_16x16x32_bf16 v[42:45], v[192:195], v[150:153], v[38:41]
	v_mfma_f32_16x16x32_bf16 v[34:37], v[210:213], v[150:153], v[34:37]
	v_mfma_f32_16x16x32_bf16 v[22:25], v[192:195], v[166:169], v[22:25]
	v_mfma_f32_16x16x32_bf16 v[18:21], v[210:213], v[166:169], v[18:21]
	v_mfma_f32_16x16x32_bf16 v[6:9], v[192:195], v[184:187], v[6:9]
	v_mfma_f32_16x16x32_bf16 v[2:5], v[210:213], v[184:187], v[2:5]
	s_setprio 0
	s_add_i32 s97, s97, 2
	s_add_u32 s51, s51, 0x100
	s_addc_u32 s55, s55, 0
	s_cmp_gt_u32 s97, 5
	s_mov_b64 s[60:61], s[42:43]
	s_barrier
	s_cbranch_scc0 .LBB0_387
	s_lshl_b32 s23, s48, 8
	v_mov_b32_e32 v38, v203
	v_mov_b32_e32 v124, v202
	s_or_b32 s23, s23, s74
	s_lshl_b32 s22, s33, 8
	v_lshl_add_u32 v122, v38, 3, s23
	v_ashrrev_i32_e32 v123, 31, v122
	v_lshl_add_u64 v[46:47], v[122:123], 2, s[2:3]
	global_load_dwordx4 v[54:57], v[46:47], off offset:16
	global_load_dwordx4 v[62:65], v[46:47], off
	global_load_dwordx4 v[38:41], v[46:47], off offset:528
	s_nop 0
	global_load_dwordx4 v[46:49], v[46:47], off offset:512
	s_add_i32 s22, s22, s30
	v_lshlrev_b64 v[184:185], 1, v[122:123]
	v_add_u32_e32 v206, s22, v124
	v_lshl_add_u64 v[188:189], s[20:21], 0, v[184:185]
	v_mad_i64_i32 v[122:123], s[42:43], v206, s96, v[188:189]
	global_load_dwordx4 v[192:195], v[122:123], off
	global_load_dwordx4 v[170:173], v[122:123], off offset:256
	v_add_u32_e32 v209, 16, v206
	v_mad_i64_i32 v[122:123], s[42:43], v209, s96, v[188:189]
	global_load_dwordx4 v[166:169], v[122:123], off
	global_load_dwordx4 v[158:161], v[122:123], off offset:256
	v_add_u32_e32 v208, 32, v206
	v_mad_i64_i32 v[122:123], s[42:43], v208, s96, v[188:189]
	global_load_dwordx4 v[150:153], v[122:123], off
	global_load_dwordx4 v[146:149], v[122:123], off offset:256
	v_add_u32_e32 v207, 48, v206
	v_mad_i64_i32 v[122:123], s[42:43], v207, s96, v[188:189]
	global_load_dwordx4 v[130:133], v[122:123], off
	s_nop 0
	global_load_dwordx4 v[122:125], v[122:123], off offset:256
	v_mov_b64_e32 v[186:187], s[20:21]
	v_mad_i64_i32 v[190:191], s[42:43], v206, s96, v[186:187]
	v_lshl_add_u64 v[190:191], v[190:191], 0, v[184:185]
	s_and_b64 vcc, exec, s[40:41]
	s_mov_b32 s48, s54
	s_mov_b32 s33, s47
	s_mov_b64 s[62:63], s[58:59]
	s_mov_b64 s[60:61], s[56:57]
	s_waitcnt vmcnt(0)
; __device__ __forceinline__ u32x4 pack8(const f32x4 a, const f32x4 b) { u32x4 w; w.x = cvt_pk_bf16(a[0], a[1]); w.y = cvt_pk_bf16(a[2], a[3]); w.z = cvt_pk_bf16(b[0], b[1]); w.w = cvt_pk_bf16(b[2], b[3]); return w; }
; __device__ __forceinline__ void unpack8(const u32x4 w, f32x4& a, f32x4& b) { a = (f32x4){bflo(w.x), bfhi(w.x), bflo(w.y), bfhi(w.y)}; b = (f32x4){bflo(w.z), bfhi(w.z), bflo(w.w), bfhi(w.w)}; }
; __device__ __forceinline__ f32x4 sig4(const f32x4 v) { return (f32x4){sigmoidf_(v[0]), sigmoidf_(v[1]), sigmoidf_(v[2]), sigmoidf_(v[3])}; }
;     __device__ __forceinline__ void operator()(const Acc& acc, const Unit& u, int wr, int wc, int fr, int fq) const {
;     ...
;         for (int ai = 0; ai < 2; ++ai) {
;             u32x4 av[4][2];
; #pragma unroll
;             for (int m = 0; m < 4; ++m)
; #pragma unroll
;                 for (int bj = 0; bj < 2; ++bj) av[m][bj] = *(const u32x4*)(proj + (size_t)(row0 + ai * 128 + m * 16) * NPROJ + col0 + bj * 128);
; #pragma unroll
;             for (int m = 0; m < 4; ++m) { bf16_t* rowp = proj + (size_t)(row0 + ai * 128 + m * 16) * NPROJ + col0;
; #pragma unroll
;                 for (int bj = 0; bj < 2; ++bj) { f32x4 a0, a1; unpack8(av[m][bj], a0, a1);
;                     const f32x4 o0 = a0 * sig4(acc[ai][bj][m][0] + bv[bj][0]), o1 = a1 * sig4(acc[ai][bj][m][1] + bv[bj][1]);
;                     *(u32x4*)(rowp + C_GLU + bj * 128) = pack8(o0, o1); } } }
	v_pk_add_f32 v[156:157], v[156:157], v[56:57]
	v_pk_add_f32 v[164:165], v[164:165], v[64:65]
	v_pk_add_f32 v[162:163], v[162:163], v[62:63]
	v_pk_add_f32 v[154:155], v[154:155], v[54:55]
	v_mul_f32_e32 v162, 0xbfb8aa3b, v162
	v_mul_f32_e32 v163, 0xbfb8aa3b, v163
	v_mul_f32_e32 v164, 0xbfb8aa3b, v164
	v_mul_f32_e32 v165, 0xbfb8aa3b, v165
	v_mul_f32_e32 v154, 0xbfb8aa3b, v154
	v_mul_f32_e32 v155, 0xbfb8aa3b, v155
	v_mul_f32_e32 v156, 0xbfb8aa3b, v156
	v_mul_f32_e32 v157, 0xbfb8aa3b, v157
	v_exp_f32_e32 v162, v162
	v_exp_f32_e32 v163, v163
	v_exp_f32_e32 v164, v164
	v_exp_f32_e32 v165, v165
	v_exp_f32_e32 v154, v154
	v_exp_f32_e32 v155, v155
	v_exp_f32_e32 v156, v156
	v_exp_f32_e32 v157, v157
	v_pk_add_f32 v[144:145], v[144:145], v[48:49]
	v_pk_add_f32 v[142:143], v[142:143], v[46:47]
	v_pk_add_f32 v[140:141], v[140:141], v[40:41]
	v_pk_add_f32 v[138:139], v[138:139], v[38:39]
	v_mul_f32_e32 v142, 0xbfb8aa3b, v142
	v_mul_f32_e32 v143, 0xbfb8aa3b, v143
	v_mul_f32_e32 v144, 0xbfb8aa3b, v144
	v_mul_f32_e32 v145, 0xbfb8aa3b, v145
	v_mul_f32_e32 v138, 0xbfb8aa3b, v138
	v_mul_f32_e32 v139, 0xbfb8aa3b, v139
	v_mul_f32_e32 v140, 0xbfb8aa3b, v140
	v_mul_f32_e32 v141, 0xbfb8aa3b, v141
	v_exp_f32_e32 v142, v142
	v_exp_f32_e32 v143, v143
	v_exp_f32_e32 v144, v144
	v_exp_f32_e32 v145, v145
	v_exp_f32_e32 v138, v138
	v_exp_f32_e32 v139, v139
	v_exp_f32_e32 v140, v140
	v_exp_f32_e32 v141, v141
	v_add_f32_e32 v162, 1.0, v162
	v_add_f32_e32 v163, 1.0, v163
	v_add_f32_e32 v164, 1.0, v164
	v_add_f32_e32 v165, 1.0, v165
	v_add_f32_e32 v154, 1.0, v154
	v_add_f32_e32 v155, 1.0, v155
	v_add_f32_e32 v156, 1.0, v156
	v_add_f32_e32 v157, 1.0, v157
	v_pk_add_f32 v[136:137], v[136:137], v[64:65]
	v_pk_add_f32 v[134:135], v[134:135], v[62:63]
	v_pk_add_f32 v[128:129], v[128:129], v[56:57]
	v_pk_add_f32 v[126:127], v[126:127], v[54:55]
	v_rcp_f32_e32 v162, v162
	v_rcp_f32_e32 v163, v163
	v_rcp_f32_e32 v164, v164
	v_rcp_f32_e32 v165, v165
	v_rcp_f32_e32 v154, v154
	v_rcp_f32_e32 v155, v155
	v_rcp_f32_e32 v156, v156
	v_rcp_f32_e32 v157, v157
	v_mul_f32_e32 v134, 0xbfb8aa3b, v134
	v_mul_f32_e32 v135, 0xbfb8aa3b, v135
	v_mul_f32_e32 v136, 0xbfb8aa3b, v136
	v_mul_f32_e32 v137, 0xbfb8aa3b, v137
	v_mul_f32_e32 v126, 0xbfb8aa3b, v126
	v_mul_f32_e32 v127, 0xbfb8aa3b, v127
	v_mul_f32_e32 v128, 0xbfb8aa3b, v128
	v_mul_f32_e32 v129, 0xbfb8aa3b, v129
	v_exp_f32_e32 v134, v134
	v_exp_f32_e32 v135, v135
	v_exp_f32_e32 v136, v136
	v_exp_f32_e32 v137, v137
	v_exp_f32_e32 v126, v126
	v_exp_f32_e32 v127, v127
	v_exp_f32_e32 v128, v128
	v_exp_f32_e32 v129, v129
	v_add_f32_e32 v142, 1.0, v142
	v_add_f32_e32 v143, 1.0, v143
	v_add_f32_e32 v144, 1.0, v144
	v_add_f32_e32 v145, 1.0, v145
	v_add_f32_e32 v138, 1.0, v138
	v_add_f32_e32 v139, 1.0, v139
	v_add_f32_e32 v140, 1.0, v140
	v_add_f32_e32 v141, 1.0, v141
	v_pk_add_f32 v[120:121], v[120:121], v[48:49]
	v_pk_add_f32 v[118:119], v[118:119], v[46:47]
	v_pk_add_f32 v[116:117], v[116:117], v[40:41]
	v_pk_add_f32 v[114:115], v[114:115], v[38:39]
	v_lshlrev_b32_e32 v210, 16, v192
	v_and_b32_e32 v211, 0xffff0000, v192
	v_lshlrev_b32_e32 v212, 16, v193
	v_and_b32_e32 v213, 0xffff0000, v193
	v_lshlrev_b32_e32 v192, 16, v194
	v_and_b32_e32 v193, 0xffff0000, v194
	v_lshlrev_b32_e32 v194, 16, v195
	v_and_b32_e32 v195, 0xffff0000, v195
	v_rcp_f32_e32 v142, v142
	v_rcp_f32_e32 v143, v143
	v_rcp_f32_e32 v144, v144
	v_rcp_f32_e32 v145, v145
	v_rcp_f32_e32 v138, v138
	v_rcp_f32_e32 v139, v139
	v_rcp_f32_e32 v140, v140
	v_rcp_f32_e32 v141, v141
	v_mul_f32_e32 v118, 0xbfb8aa3b, v118
	v_mul_f32_e32 v119, 0xbfb8aa3b, v119
	v_mul_f32_e32 v120, 0xbfb8aa3b, v120
	v_mul_f32_e32 v121, 0xbfb8aa3b, v121
	v_mul_f32_e32 v114, 0xbfb8aa3b, v114
	v_mul_f32_e32 v115, 0xbfb8aa3b, v115
	v_mul_f32_e32 v116, 0xbfb8aa3b, v116
	v_mul_f32_e32 v117, 0xbfb8aa3b, v117
	v_pk_mul_f32 v[164:165], v[164:165], v[212:213]
	v_pk_mul_f32 v[162:163], v[162:163], v[210:211]
	v_pk_mul_f32 v[194:195], v[156:157], v[194:195]
	v_pk_mul_f32 v[156:157], v[154:155], v[192:193]
	v_exp_f32_e32 v118, v118
	v_exp_f32_e32 v119, v119
	v_exp_f32_e32 v120, v120
	v_exp_f32_e32 v121, v121
	v_exp_f32_e32 v114, v114
	v_exp_f32_e32 v115, v115
	v_exp_f32_e32 v116, v116
	v_exp_f32_e32 v117, v117
	v_cvt_pk_bf16_f32 v154, v162, v163
	v_cvt_pk_bf16_f32 v155, v164, v165
	v_cvt_pk_bf16_f32 v156, v156, v157
	v_cvt_pk_bf16_f32 v157, v194, v195
	v_add_f32_e32 v134, 1.0, v134
	v_add_f32_e32 v135, 1.0, v135
	v_add_f32_e32 v136, 1.0, v136
	v_add_f32_e32 v137, 1.0, v137
	v_add_f32_e32 v126, 1.0, v126
	v_add_f32_e32 v127, 1.0, v127
	v_add_f32_e32 v128, 1.0, v128
	v_add_f32_e32 v129, 1.0, v129
	v_pk_add_f32 v[112:113], v[112:113], v[64:65]
	v_pk_add_f32 v[110:111], v[110:111], v[62:63]
	v_pk_add_f32 v[108:109], v[108:109], v[56:57]
	v_pk_add_f32 v[106:107], v[106:107], v[54:55]
	global_store_dwordx4 v[190:191], v[154:157], off offset:1024
	v_lshlrev_b32_e32 v162, 16, v170
	v_and_b32_e32 v163, 0xffff0000, v170
	v_lshlrev_b32_e32 v164, 16, v171
	v_and_b32_e32 v165, 0xffff0000, v171
	v_lshlrev_b32_e32 v154, 16, v172
	v_and_b32_e32 v155, 0xffff0000, v172
	v_lshlrev_b32_e32 v156, 16, v173
	v_and_b32_e32 v157, 0xffff0000, v173
	v_rcp_f32_e32 v134, v134
	v_rcp_f32_e32 v135, v135
	v_rcp_f32_e32 v136, v136
	v_rcp_f32_e32 v137, v137
	v_rcp_f32_e32 v126, v126
	v_rcp_f32_e32 v127, v127
	v_rcp_f32_e32 v128, v128
	v_rcp_f32_e32 v129, v129
	v_mul_f32_e32 v110, 0xbfb8aa3b, v110
	v_mul_f32_e32 v111, 0xbfb8aa3b, v111
	v_mul_f32_e32 v112, 0xbfb8aa3b, v112
	v_mul_f32_e32 v113, 0xbfb8aa3b, v113
	v_mul_f32_e32 v106, 0xbfb8aa3b, v106
	v_mul_f32_e32 v107, 0xbfb8aa3b, v107
	v_mul_f32_e32 v108, 0xbfb8aa3b, v108
	v_mul_f32_e32 v109, 0xbfb8aa3b, v109
; __device__ __forceinline__ u32x4 pack8(const f32x4 a, const f32x4 b) { u32x4 w; w.x = cvt_pk_bf16(a[0], a[1]); w.y = cvt_pk_bf16(a[2], a[3]); w.z = cvt_pk_bf16(b[0], b[1]); w.w = cvt_pk_bf16(b[2], b[3]); return w; }
; __device__ __forceinline__ void unpack8(const u32x4 w, f32x4& a, f32x4& b) { a = (f32x4){bflo(w.x), bfhi(w.x), bflo(w.y), bfhi(w.y)}; b = (f32x4){bflo(w.z), bfhi(w.z), bflo(w.w), bfhi(w.w)}; }
; __device__ __forceinline__ f32x4 sig4(const f32x4 v) { return (f32x4){sigmoidf_(v[0]), sigmoidf_(v[1]), sigmoidf_(v[2]), sigmoidf_(v[3])}; }
;     __device__ __forceinline__ void operator()(const Acc& acc, const Unit& u, int wr, int wc, int fr, int fq) const {
;     ...
;         for (int ai = 0; ai < 2; ++ai) {
;             u32x4 av[4][2];
; #pragma unroll
;             for (int m = 0; m < 4; ++m)
; #pragma unroll
;                 for (int bj = 0; bj < 2; ++bj) av[m][bj] = *(const u32x4*)(proj + (size_t)(row0 + ai * 128 + m * 16) * NPROJ + col0 + bj * 128);
; #pragma unroll
;             for (int m = 0; m < 4; ++m) { bf16_t* rowp = proj + (size_t)(row0 + ai * 128 + m * 16) * NPROJ + col0;
; #pragma unroll
;                 for (int bj = 0; bj < 2; ++bj) { f32x4 a0, a1; unpack8(av[m][bj], a0, a1);
;                     const f32x4 o0 = a0 * sig4(acc[ai][bj][m][0] + bv[bj][0]), o1 = a1 * sig4(acc[ai][bj][m][1] + bv[bj][1]);
;                     *(u32x4*)(rowp + C_GLU + bj * 128) = pack8(o0, o1); } } }
	v_pk_mul_f32 v[144:145], v[144:145], v[164:165]
	v_pk_mul_f32 v[142:143], v[142:143], v[162:163]
	v_pk_mul_f32 v[156:157], v[140:141], v[156:157]
	v_pk_mul_f32 v[140:141], v[138:139], v[154:155]
	v_exp_f32_e32 v110, v110
	v_exp_f32_e32 v111, v111
	v_exp_f32_e32 v112, v112
	v_exp_f32_e32 v113, v113
	v_exp_f32_e32 v106, v106
	v_exp_f32_e32 v107, v107
	v_exp_f32_e32 v108, v108
	v_exp_f32_e32 v109, v109
	v_cvt_pk_bf16_f32 v138, v142, v143
	v_cvt_pk_bf16_f32 v139, v144, v145
	v_cvt_pk_bf16_f32 v140, v140, v141
	v_cvt_pk_bf16_f32 v141, v156, v157
	v_add_f32_e32 v118, 1.0, v118
	v_add_f32_e32 v119, 1.0, v119
	v_add_f32_e32 v120, 1.0, v120
	v_add_f32_e32 v121, 1.0, v121
	v_add_f32_e32 v114, 1.0, v114
	v_add_f32_e32 v115, 1.0, v115
	v_add_f32_e32 v116, 1.0, v116
	v_add_f32_e32 v117, 1.0, v117
	v_pk_add_f32 v[104:105], v[104:105], v[48:49]
	v_pk_add_f32 v[102:103], v[102:103], v[46:47]
	v_pk_add_f32 v[100:101], v[100:101], v[40:41]
	v_pk_add_f32 v[98:99], v[98:99], v[38:39]
	global_store_dwordx4 v[190:191], v[138:141], off offset:1280
	v_lshlrev_b32_e32 v142, 16, v167
	v_and_b32_e32 v143, 0xffff0000, v167
	v_lshlrev_b32_e32 v140, 16, v166
	v_and_b32_e32 v141, 0xffff0000, v166
	v_lshlrev_b32_e32 v144, 16, v168
	v_and_b32_e32 v145, 0xffff0000, v168
	v_lshlrev_b32_e32 v154, 16, v169
	v_and_b32_e32 v155, 0xffff0000, v169
	v_rcp_f32_e32 v118, v118
	v_rcp_f32_e32 v119, v119
	v_rcp_f32_e32 v120, v120
	v_rcp_f32_e32 v121, v121
	v_rcp_f32_e32 v114, v114
	v_rcp_f32_e32 v115, v115
	v_rcp_f32_e32 v116, v116
	v_rcp_f32_e32 v117, v117
	v_mul_f32_e32 v102, 0xbfb8aa3b, v102
	v_mul_f32_e32 v103, 0xbfb8aa3b, v103
	v_mul_f32_e32 v104, 0xbfb8aa3b, v104
	v_mul_f32_e32 v105, 0xbfb8aa3b, v105
	v_mul_f32_e32 v98, 0xbfb8aa3b, v98
	v_mul_f32_e32 v99, 0xbfb8aa3b, v99
	v_mul_f32_e32 v100, 0xbfb8aa3b, v100
	v_mul_f32_e32 v101, 0xbfb8aa3b, v101
	v_mad_i64_i32 v[138:139], s[42:43], v209, s96, v[186:187]
	v_pk_mul_f32 v[136:137], v[136:137], v[142:143]
	v_pk_mul_f32 v[134:135], v[134:135], v[140:141]
	v_pk_mul_f32 v[140:141], v[128:129], v[154:155]
	v_pk_mul_f32 v[128:129], v[126:127], v[144:145]
	v_exp_f32_e32 v102, v102
	v_exp_f32_e32 v103, v103
	v_exp_f32_e32 v104, v104
	v_exp_f32_e32 v105, v105
	v_exp_f32_e32 v98, v98
	v_exp_f32_e32 v99, v99
	v_exp_f32_e32 v100, v100
	v_exp_f32_e32 v101, v101
	v_lshl_add_u64 v[138:139], v[138:139], 0, v[184:185]
	v_cvt_pk_bf16_f32 v126, v134, v135
	v_cvt_pk_bf16_f32 v127, v136, v137
	v_cvt_pk_bf16_f32 v128, v128, v129
	v_cvt_pk_bf16_f32 v129, v140, v141
	v_add_f32_e32 v110, 1.0, v110
	v_add_f32_e32 v111, 1.0, v111
	v_add_f32_e32 v112, 1.0, v112
	v_add_f32_e32 v113, 1.0, v113
	v_add_f32_e32 v106, 1.0, v106
	v_add_f32_e32 v107, 1.0, v107
	v_add_f32_e32 v108, 1.0, v108
	v_add_f32_e32 v109, 1.0, v109
	v_pk_add_f32 v[96:97], v[96:97], v[64:65]
	v_pk_add_f32 v[94:95], v[94:95], v[62:63]
	v_pk_add_f32 v[92:93], v[92:93], v[56:57]
	v_pk_add_f32 v[90:91], v[90:91], v[54:55]
	global_store_dwordx4 v[138:139], v[126:129], off offset:1024
	v_lshlrev_b32_e32 v134, 16, v160
	v_and_b32_e32 v135, 0xffff0000, v160
	v_lshlrev_b32_e32 v126, 16, v158
	v_and_b32_e32 v127, 0xffff0000, v158
	v_lshlrev_b32_e32 v128, 16, v159
	v_and_b32_e32 v129, 0xffff0000, v159
	v_lshlrev_b32_e32 v136, 16, v161
	v_and_b32_e32 v137, 0xffff0000, v161
	v_rcp_f32_e32 v110, v110
	v_rcp_f32_e32 v111, v111
	v_rcp_f32_e32 v112, v112
	v_rcp_f32_e32 v113, v113
	v_rcp_f32_e32 v106, v106
	v_rcp_f32_e32 v107, v107
	v_rcp_f32_e32 v108, v108
	v_rcp_f32_e32 v109, v109
	v_mul_f32_e32 v94, 0xbfb8aa3b, v94
	v_mul_f32_e32 v95, 0xbfb8aa3b, v95
	v_mul_f32_e32 v96, 0xbfb8aa3b, v96
	v_mul_f32_e32 v97, 0xbfb8aa3b, v97
	v_mul_f32_e32 v90, 0xbfb8aa3b, v90
	v_mul_f32_e32 v91, 0xbfb8aa3b, v91
	v_mul_f32_e32 v92, 0xbfb8aa3b, v92
	v_mul_f32_e32 v93, 0xbfb8aa3b, v93
	v_pk_mul_f32 v[120:121], v[120:121], v[128:129]
	v_pk_mul_f32 v[118:119], v[118:119], v[126:127]
	v_pk_mul_f32 v[126:127], v[116:117], v[136:137]
	v_pk_mul_f32 v[116:117], v[114:115], v[134:135]
	v_exp_f32_e32 v94, v94
	v_exp_f32_e32 v95, v95
	v_exp_f32_e32 v96, v96
	v_exp_f32_e32 v97, v97
	v_exp_f32_e32 v90, v90
	v_exp_f32_e32 v91, v91
	v_exp_f32_e32 v92, v92
	v_exp_f32_e32 v93, v93
	v_cvt_pk_bf16_f32 v114, v118, v119
	v_cvt_pk_bf16_f32 v115, v120, v121
	v_cvt_pk_bf16_f32 v116, v116, v117
	v_cvt_pk_bf16_f32 v117, v126, v127
	v_add_f32_e32 v102, 1.0, v102
	v_add_f32_e32 v103, 1.0, v103
	v_add_f32_e32 v104, 1.0, v104
	v_add_f32_e32 v105, 1.0, v105
	v_add_f32_e32 v98, 1.0, v98
	v_add_f32_e32 v99, 1.0, v99
	v_add_f32_e32 v100, 1.0, v100
	v_add_f32_e32 v101, 1.0, v101
	v_pk_add_f32 v[88:89], v[88:89], v[48:49]
	v_pk_add_f32 v[86:87], v[86:87], v[46:47]
	v_pk_add_f32 v[84:85], v[84:85], v[40:41]
	v_pk_add_f32 v[82:83], v[82:83], v[38:39]
	global_store_dwordx4 v[138:139], v[114:117], off offset:1280
	v_lshlrev_b32_e32 v118, 16, v151
	v_and_b32_e32 v119, 0xffff0000, v151
	v_lshlrev_b32_e32 v116, 16, v150
	v_and_b32_e32 v117, 0xffff0000, v150
	v_lshlrev_b32_e32 v120, 16, v152
	v_and_b32_e32 v121, 0xffff0000, v152
	v_lshlrev_b32_e32 v126, 16, v153
	v_and_b32_e32 v127, 0xffff0000, v153
	v_rcp_f32_e32 v102, v102
	v_rcp_f32_e32 v103, v103
	v_rcp_f32_e32 v104, v104
	v_rcp_f32_e32 v105, v105
	v_rcp_f32_e32 v98, v98
	v_rcp_f32_e32 v99, v99
	v_rcp_f32_e32 v100, v100
	v_rcp_f32_e32 v101, v101
	v_mul_f32_e32 v86, 0xbfb8aa3b, v86
	v_mul_f32_e32 v87, 0xbfb8aa3b, v87
	v_mul_f32_e32 v88, 0xbfb8aa3b, v88
	v_mul_f32_e32 v89, 0xbfb8aa3b, v89
	v_mul_f32_e32 v82, 0xbfb8aa3b, v82
	v_mul_f32_e32 v83, 0xbfb8aa3b, v83
	v_mul_f32_e32 v84, 0xbfb8aa3b, v84
	v_mul_f32_e32 v85, 0xbfb8aa3b, v85
	v_mad_i64_i32 v[114:115], s[42:43], v208, s96, v[186:187]
	v_pk_mul_f32 v[112:113], v[112:113], v[118:119]
; __device__ __forceinline__ u32x4 pack8(const f32x4 a, const f32x4 b) { u32x4 w; w.x = cvt_pk_bf16(a[0], a[1]); w.y = cvt_pk_bf16(a[2], a[3]); w.z = cvt_pk_bf16(b[0], b[1]); w.w = cvt_pk_bf16(b[2], b[3]); return w; }
; __device__ __forceinline__ void unpack8(const u32x4 w, f32x4& a, f32x4& b) { a = (f32x4){bflo(w.x), bfhi(w.x), bflo(w.y), bfhi(w.y)}; b = (f32x4){bflo(w.z), bfhi(w.z), bflo(w.w), bfhi(w.w)}; }
; __device__ __forceinline__ f32x4 sig4(const f32x4 v) { return (f32x4){sigmoidf_(v[0]), sigmoidf_(v[1]), sigmoidf_(v[2]), sigmoidf_(v[3])}; }
;     __device__ __forceinline__ void operator()(const Acc& acc, const Unit& u, int wr, int wc, int fr, int fq) const {
;     ...
;         for (int ai = 0; ai < 2; ++ai) {
;             u32x4 av[4][2];
; #pragma unroll
;             for (int m = 0; m < 4; ++m)
; #pragma unroll
;                 for (int bj = 0; bj < 2; ++bj) av[m][bj] = *(const u32x4*)(proj + (size_t)(row0 + ai * 128 + m * 16) * NPROJ + col0 + bj * 128);
; #pragma unroll
;             for (int m = 0; m < 4; ++m) { bf16_t* rowp = proj + (size_t)(row0 + ai * 128 + m * 16) * NPROJ + col0;
; #pragma unroll
;                 for (int bj = 0; bj < 2; ++bj) { f32x4 a0, a1; unpack8(av[m][bj], a0, a1);
;                     const f32x4 o0 = a0 * sig4(acc[ai][bj][m][0] + bv[bj][0]), o1 = a1 * sig4(acc[ai][bj][m][1] + bv[bj][1]);
;                     *(u32x4*)(rowp + C_GLU + bj * 128) = pack8(o0, o1); } } }
	v_pk_mul_f32 v[110:111], v[110:111], v[116:117]
	v_pk_mul_f32 v[116:117], v[108:109], v[126:127]
	v_pk_mul_f32 v[108:109], v[106:107], v[120:121]
	v_exp_f32_e32 v86, v86
	v_exp_f32_e32 v87, v87
	v_exp_f32_e32 v88, v88
	v_exp_f32_e32 v89, v89
	v_exp_f32_e32 v82, v82
	v_exp_f32_e32 v83, v83
	v_exp_f32_e32 v84, v84
	v_exp_f32_e32 v85, v85
	v_lshl_add_u64 v[114:115], v[114:115], 0, v[184:185]
	v_cvt_pk_bf16_f32 v106, v110, v111
	v_cvt_pk_bf16_f32 v107, v112, v113
	v_cvt_pk_bf16_f32 v108, v108, v109
	v_cvt_pk_bf16_f32 v109, v116, v117
	v_add_f32_e32 v94, 1.0, v94
	v_add_f32_e32 v95, 1.0, v95
	v_add_f32_e32 v96, 1.0, v96
	v_add_f32_e32 v97, 1.0, v97
	v_add_f32_e32 v90, 1.0, v90
	v_add_f32_e32 v91, 1.0, v91
	v_add_f32_e32 v92, 1.0, v92
	v_add_f32_e32 v93, 1.0, v93
	global_store_dwordx4 v[114:115], v[106:109], off offset:1024
	v_lshlrev_b32_e32 v110, 16, v148
	v_and_b32_e32 v111, 0xffff0000, v148
	v_lshlrev_b32_e32 v106, 16, v146
	v_and_b32_e32 v107, 0xffff0000, v146
	v_lshlrev_b32_e32 v108, 16, v147
	v_and_b32_e32 v109, 0xffff0000, v147
	v_lshlrev_b32_e32 v112, 16, v149
	v_and_b32_e32 v113, 0xffff0000, v149
	v_rcp_f32_e32 v94, v94
	v_rcp_f32_e32 v95, v95
	v_rcp_f32_e32 v96, v96
	v_rcp_f32_e32 v97, v97
	v_rcp_f32_e32 v90, v90
	v_rcp_f32_e32 v91, v91
	v_rcp_f32_e32 v92, v92
	v_rcp_f32_e32 v93, v93
	v_pk_mul_f32 v[104:105], v[104:105], v[108:109]
	v_pk_mul_f32 v[102:103], v[102:103], v[106:107]
	v_pk_mul_f32 v[106:107], v[100:101], v[112:113]
	v_pk_mul_f32 v[100:101], v[98:99], v[110:111]
	v_cvt_pk_bf16_f32 v98, v102, v103
	v_cvt_pk_bf16_f32 v99, v104, v105
	v_cvt_pk_bf16_f32 v100, v100, v101
	v_cvt_pk_bf16_f32 v101, v106, v107
	v_add_f32_e32 v86, 1.0, v86
	v_add_f32_e32 v87, 1.0, v87
	v_add_f32_e32 v88, 1.0, v88
	v_add_f32_e32 v89, 1.0, v89
	v_add_f32_e32 v82, 1.0, v82
	v_add_f32_e32 v83, 1.0, v83
	v_add_f32_e32 v84, 1.0, v84
	v_add_f32_e32 v85, 1.0, v85
	global_store_dwordx4 v[114:115], v[98:101], off offset:1280
	v_lshlrev_b32_e32 v102, 16, v131
	v_and_b32_e32 v103, 0xffff0000, v131
	v_lshlrev_b32_e32 v100, 16, v130
	v_and_b32_e32 v101, 0xffff0000, v130
	v_lshlrev_b32_e32 v104, 16, v132
	v_and_b32_e32 v105, 0xffff0000, v132
	v_lshlrev_b32_e32 v106, 16, v133
	v_and_b32_e32 v107, 0xffff0000, v133
	v_rcp_f32_e32 v86, v86
	v_rcp_f32_e32 v87, v87
	v_rcp_f32_e32 v88, v88
	v_rcp_f32_e32 v89, v89
	v_rcp_f32_e32 v82, v82
	v_rcp_f32_e32 v83, v83
	v_rcp_f32_e32 v84, v84
	v_rcp_f32_e32 v85, v85
	v_mad_i64_i32 v[98:99], s[42:43], v207, s96, v[186:187]
	v_pk_mul_f32 v[96:97], v[96:97], v[102:103]
	v_pk_mul_f32 v[94:95], v[94:95], v[100:101]
	v_pk_mul_f32 v[100:101], v[92:93], v[106:107]
	v_pk_mul_f32 v[92:93], v[90:91], v[104:105]
	v_lshl_add_u64 v[98:99], v[98:99], 0, v[184:185]
	v_cvt_pk_bf16_f32 v90, v94, v95
	v_cvt_pk_bf16_f32 v91, v96, v97
	v_cvt_pk_bf16_f32 v92, v92, v93
	v_cvt_pk_bf16_f32 v93, v100, v101
	global_store_dwordx4 v[98:99], v[90:93], off offset:1024
	v_lshlrev_b32_e32 v94, 16, v124
	v_and_b32_e32 v95, 0xffff0000, v124
	v_lshlrev_b32_e32 v90, 16, v122
	v_and_b32_e32 v91, 0xffff0000, v122
	v_lshlrev_b32_e32 v92, 16, v123
	v_and_b32_e32 v93, 0xffff0000, v123
	v_lshlrev_b32_e32 v96, 16, v125
	v_and_b32_e32 v97, 0xffff0000, v125
	v_pk_mul_f32 v[88:89], v[88:89], v[92:93]
	v_pk_mul_f32 v[86:87], v[86:87], v[90:91]
	v_pk_mul_f32 v[90:91], v[84:85], v[96:97]
	v_pk_mul_f32 v[84:85], v[82:83], v[94:95]
	v_cvt_pk_bf16_f32 v82, v86, v87
	v_cvt_pk_bf16_f32 v83, v88, v89
	v_cvt_pk_bf16_f32 v84, v84, v85
	v_cvt_pk_bf16_f32 v85, v90, v91
	v_add_u32_e32 v110, 0x80, v206
	global_store_dwordx4 v[98:99], v[82:85], off offset:1280
	v_add_u32_e32 v122, 0x90, v206
	v_add_u32_e32 v113, 0xa0, v206
	v_mad_i64_i32 v[82:83], s[42:43], v110, s96, v[188:189]
	global_load_dwordx4 v[106:109], v[82:83], off
	global_load_dwordx4 v[114:117], v[82:83], off offset:256
	v_mad_i64_i32 v[82:83], s[42:43], v122, s96, v[188:189]
	global_load_dwordx4 v[102:105], v[82:83], off
	global_load_dwordx4 v[98:101], v[82:83], off offset:256
	v_mad_i64_i32 v[82:83], s[42:43], v113, s96, v[188:189]
	global_load_dwordx4 v[94:97], v[82:83], off
	global_load_dwordx4 v[90:93], v[82:83], off offset:256
	v_add_u32_e32 v112, 0xb0, v206
	v_mad_i64_i32 v[82:83], s[42:43], v112, s96, v[188:189]
	global_load_dwordx4 v[86:89], v[82:83], off
	s_nop 0
	global_load_dwordx4 v[82:85], v[82:83], off offset:256
	v_pk_add_f32 v[80:81], v[80:81], v[64:65]
	v_pk_add_f32 v[78:79], v[78:79], v[62:63]
	v_pk_add_f32 v[76:77], v[76:77], v[56:57]
	v_pk_add_f32 v[74:75], v[74:75], v[54:55]
	v_mul_f32_e32 v78, 0xbfb8aa3b, v78
	v_mul_f32_e32 v79, 0xbfb8aa3b, v79
	v_mul_f32_e32 v80, 0xbfb8aa3b, v80
	v_mul_f32_e32 v81, 0xbfb8aa3b, v81
	v_mul_f32_e32 v74, 0xbfb8aa3b, v74
	v_mul_f32_e32 v75, 0xbfb8aa3b, v75
	v_mul_f32_e32 v76, 0xbfb8aa3b, v76
	v_mul_f32_e32 v77, 0xbfb8aa3b, v77
	v_exp_f32_e32 v78, v78
	v_exp_f32_e32 v79, v79
	v_exp_f32_e32 v80, v80
	v_exp_f32_e32 v81, v81
	v_exp_f32_e32 v74, v74
	v_exp_f32_e32 v75, v75
	v_exp_f32_e32 v76, v76
	v_exp_f32_e32 v77, v77
	v_pk_add_f32 v[72:73], v[72:73], v[48:49]
	v_pk_add_f32 v[70:71], v[70:71], v[46:47]
	v_pk_add_f32 v[68:69], v[68:69], v[40:41]
	v_pk_add_f32 v[66:67], v[66:67], v[38:39]
	v_mul_f32_e32 v70, 0xbfb8aa3b, v70
	v_mul_f32_e32 v71, 0xbfb8aa3b, v71
	v_mul_f32_e32 v72, 0xbfb8aa3b, v72
	v_mul_f32_e32 v73, 0xbfb8aa3b, v73
	v_mul_f32_e32 v66, 0xbfb8aa3b, v66
	v_mul_f32_e32 v67, 0xbfb8aa3b, v67
	v_mul_f32_e32 v68, 0xbfb8aa3b, v68
	v_mul_f32_e32 v69, 0xbfb8aa3b, v69
	v_exp_f32_e32 v70, v70
	v_exp_f32_e32 v71, v71
	v_exp_f32_e32 v72, v72
	v_exp_f32_e32 v73, v73
	v_exp_f32_e32 v66, v66
	v_exp_f32_e32 v67, v67
	v_exp_f32_e32 v68, v68
	v_exp_f32_e32 v69, v69
	v_add_f32_e32 v78, 1.0, v78
; __device__ __forceinline__ u32x4 pack8(const f32x4 a, const f32x4 b) { u32x4 w; w.x = cvt_pk_bf16(a[0], a[1]); w.y = cvt_pk_bf16(a[2], a[3]); w.z = cvt_pk_bf16(b[0], b[1]); w.w = cvt_pk_bf16(b[2], b[3]); return w; }
; __device__ __forceinline__ void unpack8(const u32x4 w, f32x4& a, f32x4& b) { a = (f32x4){bflo(w.x), bfhi(w.x), bflo(w.y), bfhi(w.y)}; b = (f32x4){bflo(w.z), bfhi(w.z), bflo(w.w), bfhi(w.w)}; }
; __device__ __forceinline__ f32x4 sig4(const f32x4 v) { return (f32x4){sigmoidf_(v[0]), sigmoidf_(v[1]), sigmoidf_(v[2]), sigmoidf_(v[3])}; }
;     __device__ __forceinline__ void operator()(const Acc& acc, const Unit& u, int wr, int wc, int fr, int fq) const {
;     ...
;         for (int ai = 0; ai < 2; ++ai) {
;             u32x4 av[4][2];
; #pragma unroll
;             for (int m = 0; m < 4; ++m)
; #pragma unroll
;                 for (int bj = 0; bj < 2; ++bj) av[m][bj] = *(const u32x4*)(proj + (size_t)(row0 + ai * 128 + m * 16) * NPROJ + col0 + bj * 128);
; #pragma unroll
;             for (int m = 0; m < 4; ++m) { bf16_t* rowp = proj + (size_t)(row0 + ai * 128 + m * 16) * NPROJ + col0;
; #pragma unroll
;                 for (int bj = 0; bj < 2; ++bj) { f32x4 a0, a1; unpack8(av[m][bj], a0, a1);
;                     const f32x4 o0 = a0 * sig4(acc[ai][bj][m][0] + bv[bj][0]), o1 = a1 * sig4(acc[ai][bj][m][1] + bv[bj][1]);
;                     *(u32x4*)(rowp + C_GLU + bj * 128) = pack8(o0, o1); } } }
	v_add_f32_e32 v79, 1.0, v79
	v_add_f32_e32 v80, 1.0, v80
	v_add_f32_e32 v81, 1.0, v81
	v_add_f32_e32 v74, 1.0, v74
	v_add_f32_e32 v75, 1.0, v75
	v_add_f32_e32 v76, 1.0, v76
	v_add_f32_e32 v77, 1.0, v77
	v_pk_add_f32 v[60:61], v[60:61], v[64:65]
	v_pk_add_f32 v[58:59], v[58:59], v[62:63]
	v_pk_add_f32 v[52:53], v[52:53], v[56:57]
	v_pk_add_f32 v[50:51], v[50:51], v[54:55]
	v_rcp_f32_e32 v78, v78
	v_rcp_f32_e32 v79, v79
	v_rcp_f32_e32 v80, v80
	v_rcp_f32_e32 v81, v81
	v_rcp_f32_e32 v74, v74
	v_rcp_f32_e32 v75, v75
	v_rcp_f32_e32 v76, v76
	v_rcp_f32_e32 v77, v77
	v_mul_f32_e32 v58, 0xbfb8aa3b, v58
	v_mul_f32_e32 v59, 0xbfb8aa3b, v59
	v_mul_f32_e32 v60, 0xbfb8aa3b, v60
	v_mul_f32_e32 v61, 0xbfb8aa3b, v61
	v_mul_f32_e32 v50, 0xbfb8aa3b, v50
	v_mul_f32_e32 v51, 0xbfb8aa3b, v51
	v_mul_f32_e32 v52, 0xbfb8aa3b, v52
	v_mul_f32_e32 v53, 0xbfb8aa3b, v53
	v_exp_f32_e32 v58, v58
	v_exp_f32_e32 v59, v59
	v_exp_f32_e32 v60, v60
	v_exp_f32_e32 v61, v61
	v_exp_f32_e32 v50, v50
	v_exp_f32_e32 v51, v51
	v_exp_f32_e32 v52, v52
	v_exp_f32_e32 v53, v53
	v_add_f32_e32 v70, 1.0, v70
	v_add_f32_e32 v71, 1.0, v71
	v_add_f32_e32 v72, 1.0, v72
	v_add_f32_e32 v73, 1.0, v73
	v_add_f32_e32 v66, 1.0, v66
	v_add_f32_e32 v67, 1.0, v67
	v_add_f32_e32 v68, 1.0, v68
	v_add_f32_e32 v69, 1.0, v69
	v_pk_add_f32 v[44:45], v[44:45], v[48:49]
	v_pk_add_f32 v[42:43], v[42:43], v[46:47]
	v_pk_add_f32 v[36:37], v[36:37], v[40:41]
	v_pk_add_f32 v[34:35], v[34:35], v[38:39]
	s_waitcnt vmcnt(0)
	v_lshlrev_b32_e32 v118, 16, v106
	v_and_b32_e32 v119, 0xffff0000, v106
	v_lshlrev_b32_e32 v106, 16, v107
	v_and_b32_e32 v107, 0xffff0000, v107
	v_lshlrev_b32_e32 v120, 16, v108
	v_and_b32_e32 v121, 0xffff0000, v108
	v_lshlrev_b32_e32 v108, 16, v109
	v_and_b32_e32 v109, 0xffff0000, v109
	v_rcp_f32_e32 v70, v70
	v_rcp_f32_e32 v71, v71
	v_rcp_f32_e32 v72, v72
	v_rcp_f32_e32 v73, v73
	v_rcp_f32_e32 v66, v66
	v_rcp_f32_e32 v67, v67
	v_rcp_f32_e32 v68, v68
	v_rcp_f32_e32 v69, v69
	v_mul_f32_e32 v42, 0xbfb8aa3b, v42
	v_mul_f32_e32 v43, 0xbfb8aa3b, v43
	v_mul_f32_e32 v44, 0xbfb8aa3b, v44
	v_mul_f32_e32 v45, 0xbfb8aa3b, v45
	v_mul_f32_e32 v34, 0xbfb8aa3b, v34
	v_mul_f32_e32 v35, 0xbfb8aa3b, v35
	v_mul_f32_e32 v36, 0xbfb8aa3b, v36
	v_mul_f32_e32 v37, 0xbfb8aa3b, v37
	v_mad_i64_i32 v[110:111], s[42:43], v110, s96, v[186:187]
	v_pk_mul_f32 v[80:81], v[80:81], v[106:107]
	v_pk_mul_f32 v[78:79], v[78:79], v[118:119]
	v_pk_mul_f32 v[106:107], v[76:77], v[108:109]
	v_pk_mul_f32 v[76:77], v[74:75], v[120:121]
	v_exp_f32_e32 v42, v42
	v_exp_f32_e32 v43, v43
	v_exp_f32_e32 v44, v44
	v_exp_f32_e32 v45, v45
	v_exp_f32_e32 v34, v34
	v_exp_f32_e32 v35, v35
	v_exp_f32_e32 v36, v36
	v_exp_f32_e32 v37, v37
	v_lshl_add_u64 v[110:111], v[110:111], 0, v[184:185]
	v_cvt_pk_bf16_f32 v74, v78, v79
	v_cvt_pk_bf16_f32 v75, v80, v81
	v_cvt_pk_bf16_f32 v76, v76, v77
	v_cvt_pk_bf16_f32 v77, v106, v107
	v_add_f32_e32 v58, 1.0, v58
	v_add_f32_e32 v59, 1.0, v59
	v_add_f32_e32 v60, 1.0, v60
	v_add_f32_e32 v61, 1.0, v61
	v_add_f32_e32 v50, 1.0, v50
	v_add_f32_e32 v51, 1.0, v51
	v_add_f32_e32 v52, 1.0, v52
	v_add_f32_e32 v53, 1.0, v53
	v_pk_add_f32 v[32:33], v[32:33], v[64:65]
	v_pk_add_f32 v[30:31], v[30:31], v[62:63]
	v_pk_add_f32 v[28:29], v[28:29], v[56:57]
	v_pk_add_f32 v[26:27], v[26:27], v[54:55]
	global_store_dwordx4 v[110:111], v[74:77], off offset:1024
	v_lshlrev_b32_e32 v78, 16, v116
	v_and_b32_e32 v79, 0xffff0000, v116
	v_lshlrev_b32_e32 v74, 16, v114
	v_and_b32_e32 v75, 0xffff0000, v114
	v_lshlrev_b32_e32 v76, 16, v115
	v_and_b32_e32 v77, 0xffff0000, v115
	v_lshlrev_b32_e32 v80, 16, v117
	v_and_b32_e32 v81, 0xffff0000, v117
	v_rcp_f32_e32 v58, v58
	v_rcp_f32_e32 v59, v59
	v_rcp_f32_e32 v60, v60
	v_rcp_f32_e32 v61, v61
	v_rcp_f32_e32 v50, v50
	v_rcp_f32_e32 v51, v51
	v_rcp_f32_e32 v52, v52
	v_rcp_f32_e32 v53, v53
	v_mul_f32_e32 v30, 0xbfb8aa3b, v30
	v_mul_f32_e32 v31, 0xbfb8aa3b, v31
	v_mul_f32_e32 v32, 0xbfb8aa3b, v32
	v_mul_f32_e32 v33, 0xbfb8aa3b, v33
	v_mul_f32_e32 v26, 0xbfb8aa3b, v26
	v_mul_f32_e32 v27, 0xbfb8aa3b, v27
	v_mul_f32_e32 v28, 0xbfb8aa3b, v28
	v_mul_f32_e32 v29, 0xbfb8aa3b, v29
	v_pk_mul_f32 v[72:73], v[72:73], v[76:77]
	v_pk_mul_f32 v[70:71], v[70:71], v[74:75]
	v_pk_mul_f32 v[74:75], v[68:69], v[80:81]
	v_pk_mul_f32 v[68:69], v[66:67], v[78:79]
	v_exp_f32_e32 v30, v30
	v_exp_f32_e32 v31, v31
	v_exp_f32_e32 v32, v32
	v_exp_f32_e32 v33, v33
	v_exp_f32_e32 v26, v26
	v_exp_f32_e32 v27, v27
	v_exp_f32_e32 v28, v28
	v_exp_f32_e32 v29, v29
	v_cvt_pk_bf16_f32 v66, v70, v71
	v_cvt_pk_bf16_f32 v67, v72, v73
	v_cvt_pk_bf16_f32 v68, v68, v69
	v_cvt_pk_bf16_f32 v69, v74, v75
	v_add_f32_e32 v42, 1.0, v42
	v_add_f32_e32 v43, 1.0, v43
	v_add_f32_e32 v44, 1.0, v44
	v_add_f32_e32 v45, 1.0, v45
	v_add_f32_e32 v34, 1.0, v34
	v_add_f32_e32 v35, 1.0, v35
	v_add_f32_e32 v36, 1.0, v36
	v_add_f32_e32 v37, 1.0, v37
	v_pk_add_f32 v[24:25], v[24:25], v[48:49]
	v_pk_add_f32 v[22:23], v[22:23], v[46:47]
	v_pk_add_f32 v[20:21], v[20:21], v[40:41]
	v_pk_add_f32 v[18:19], v[18:19], v[38:39]
	global_store_dwordx4 v[110:111], v[66:69], off offset:1280
	v_lshlrev_b32_e32 v70, 16, v103
	v_and_b32_e32 v71, 0xffff0000, v103
	v_lshlrev_b32_e32 v68, 16, v102
	v_and_b32_e32 v69, 0xffff0000, v102
	v_lshlrev_b32_e32 v72, 16, v104
	v_and_b32_e32 v73, 0xffff0000, v104
	v_lshlrev_b32_e32 v74, 16, v105
	v_and_b32_e32 v75, 0xffff0000, v105
	v_rcp_f32_e32 v42, v42
	v_rcp_f32_e32 v43, v43
	v_rcp_f32_e32 v44, v44
	v_rcp_f32_e32 v45, v45
	v_rcp_f32_e32 v34, v34
	v_rcp_f32_e32 v35, v35
	v_rcp_f32_e32 v36, v36
	v_rcp_f32_e32 v37, v37
	v_mul_f32_e32 v22, 0xbfb8aa3b, v22
	v_mul_f32_e32 v23, 0xbfb8aa3b, v23
	v_mul_f32_e32 v24, 0xbfb8aa3b, v24
; __device__ __forceinline__ u32x4 pack8(const f32x4 a, const f32x4 b) { u32x4 w; w.x = cvt_pk_bf16(a[0], a[1]); w.y = cvt_pk_bf16(a[2], a[3]); w.z = cvt_pk_bf16(b[0], b[1]); w.w = cvt_pk_bf16(b[2], b[3]); return w; }
; __device__ __forceinline__ void unpack8(const u32x4 w, f32x4& a, f32x4& b) { a = (f32x4){bflo(w.x), bfhi(w.x), bflo(w.y), bfhi(w.y)}; b = (f32x4){bflo(w.z), bfhi(w.z), bflo(w.w), bfhi(w.w)}; }
; __device__ __forceinline__ f32x4 sig4(const f32x4 v) { return (f32x4){sigmoidf_(v[0]), sigmoidf_(v[1]), sigmoidf_(v[2]), sigmoidf_(v[3])}; }
;     __device__ __forceinline__ void operator()(const Acc& acc, const Unit& u, int wr, int wc, int fr, int fq) const {
;     ...
;         for (int ai = 0; ai < 2; ++ai) {
;             u32x4 av[4][2];
; #pragma unroll
;             for (int m = 0; m < 4; ++m)
; #pragma unroll
;                 for (int bj = 0; bj < 2; ++bj) av[m][bj] = *(const u32x4*)(proj + (size_t)(row0 + ai * 128 + m * 16) * NPROJ + col0 + bj * 128);
; #pragma unroll
;             for (int m = 0; m < 4; ++m) { bf16_t* rowp = proj + (size_t)(row0 + ai * 128 + m * 16) * NPROJ + col0;
; #pragma unroll
;                 for (int bj = 0; bj < 2; ++bj) { f32x4 a0, a1; unpack8(av[m][bj], a0, a1);
;                     const f32x4 o0 = a0 * sig4(acc[ai][bj][m][0] + bv[bj][0]), o1 = a1 * sig4(acc[ai][bj][m][1] + bv[bj][1]);
;                     *(u32x4*)(rowp + C_GLU + bj * 128) = pack8(o0, o1); } } }
	v_mul_f32_e32 v25, 0xbfb8aa3b, v25
	v_mul_f32_e32 v18, 0xbfb8aa3b, v18
	v_mul_f32_e32 v19, 0xbfb8aa3b, v19
	v_mul_f32_e32 v20, 0xbfb8aa3b, v20
	v_mul_f32_e32 v21, 0xbfb8aa3b, v21
	v_mad_i64_i32 v[66:67], s[42:43], v122, s96, v[186:187]
	v_pk_mul_f32 v[60:61], v[60:61], v[70:71]
	v_pk_mul_f32 v[58:59], v[58:59], v[68:69]
	v_pk_mul_f32 v[68:69], v[52:53], v[74:75]
	v_pk_mul_f32 v[52:53], v[50:51], v[72:73]
	v_exp_f32_e32 v22, v22
	v_exp_f32_e32 v23, v23
	v_exp_f32_e32 v24, v24
	v_exp_f32_e32 v25, v25
	v_exp_f32_e32 v18, v18
	v_exp_f32_e32 v19, v19
	v_exp_f32_e32 v20, v20
	v_exp_f32_e32 v21, v21
	v_lshl_add_u64 v[66:67], v[66:67], 0, v[184:185]
	v_cvt_pk_bf16_f32 v50, v58, v59
	v_cvt_pk_bf16_f32 v51, v60, v61
	v_cvt_pk_bf16_f32 v52, v52, v53
	v_cvt_pk_bf16_f32 v53, v68, v69
	v_add_f32_e32 v30, 1.0, v30
	v_add_f32_e32 v31, 1.0, v31
	v_add_f32_e32 v32, 1.0, v32
	v_add_f32_e32 v33, 1.0, v33
	v_add_f32_e32 v26, 1.0, v26
	v_add_f32_e32 v27, 1.0, v27
	v_add_f32_e32 v28, 1.0, v28
	v_add_f32_e32 v29, 1.0, v29
	v_pk_add_f32 v[16:17], v[16:17], v[64:65]
	v_pk_add_f32 v[14:15], v[14:15], v[62:63]
	v_pk_add_f32 v[12:13], v[12:13], v[56:57]
	v_pk_add_f32 v[10:11], v[10:11], v[54:55]
	global_store_dwordx4 v[66:67], v[50:53], off offset:1024
	v_lshlrev_b32_e32 v58, 16, v100
	v_and_b32_e32 v59, 0xffff0000, v100
	v_lshlrev_b32_e32 v50, 16, v98
	v_and_b32_e32 v51, 0xffff0000, v98
	v_lshlrev_b32_e32 v52, 16, v99
	v_and_b32_e32 v53, 0xffff0000, v99
	v_lshlrev_b32_e32 v60, 16, v101
	v_and_b32_e32 v61, 0xffff0000, v101
	v_rcp_f32_e32 v30, v30
	v_rcp_f32_e32 v31, v31
	v_rcp_f32_e32 v32, v32
	v_rcp_f32_e32 v33, v33
	v_rcp_f32_e32 v26, v26
	v_rcp_f32_e32 v27, v27
	v_rcp_f32_e32 v28, v28
	v_rcp_f32_e32 v29, v29
	v_mul_f32_e32 v14, 0xbfb8aa3b, v14
	v_mul_f32_e32 v15, 0xbfb8aa3b, v15
	v_mul_f32_e32 v16, 0xbfb8aa3b, v16
	v_mul_f32_e32 v17, 0xbfb8aa3b, v17
	v_mul_f32_e32 v10, 0xbfb8aa3b, v10
	v_mul_f32_e32 v11, 0xbfb8aa3b, v11
	v_mul_f32_e32 v12, 0xbfb8aa3b, v12
	v_mul_f32_e32 v13, 0xbfb8aa3b, v13
	v_pk_mul_f32 v[44:45], v[44:45], v[52:53]
	v_pk_mul_f32 v[42:43], v[42:43], v[50:51]
	v_pk_mul_f32 v[50:51], v[36:37], v[60:61]
	v_pk_mul_f32 v[36:37], v[34:35], v[58:59]
	v_exp_f32_e32 v14, v14
	v_exp_f32_e32 v15, v15
	v_exp_f32_e32 v16, v16
	v_exp_f32_e32 v17, v17
	v_exp_f32_e32 v10, v10
	v_exp_f32_e32 v11, v11
	v_exp_f32_e32 v12, v12
	v_exp_f32_e32 v13, v13
	v_cvt_pk_bf16_f32 v34, v42, v43
	v_cvt_pk_bf16_f32 v35, v44, v45
	v_cvt_pk_bf16_f32 v36, v36, v37
	v_cvt_pk_bf16_f32 v37, v50, v51
	v_add_f32_e32 v22, 1.0, v22
	v_add_f32_e32 v23, 1.0, v23
	v_add_f32_e32 v24, 1.0, v24
	v_add_f32_e32 v25, 1.0, v25
	v_add_f32_e32 v18, 1.0, v18
	v_add_f32_e32 v19, 1.0, v19
	v_add_f32_e32 v20, 1.0, v20
	v_add_f32_e32 v21, 1.0, v21
	v_pk_add_f32 v[8:9], v[8:9], v[48:49]
	v_pk_add_f32 v[6:7], v[6:7], v[46:47]
	v_pk_add_f32 v[4:5], v[4:5], v[40:41]
	v_pk_add_f32 v[2:3], v[2:3], v[38:39]
	global_store_dwordx4 v[66:67], v[34:37], off offset:1280
	v_lshlrev_b32_e32 v42, 16, v95
	v_and_b32_e32 v43, 0xffff0000, v95
	v_lshlrev_b32_e32 v36, 16, v94
	v_and_b32_e32 v37, 0xffff0000, v94
	v_lshlrev_b32_e32 v44, 16, v96
	v_and_b32_e32 v45, 0xffff0000, v96
	v_lshlrev_b32_e32 v50, 16, v97
	v_and_b32_e32 v51, 0xffff0000, v97
	v_rcp_f32_e32 v22, v22
	v_rcp_f32_e32 v23, v23
	v_rcp_f32_e32 v24, v24
	v_rcp_f32_e32 v25, v25
	v_rcp_f32_e32 v18, v18
	v_rcp_f32_e32 v19, v19
	v_rcp_f32_e32 v20, v20
	v_rcp_f32_e32 v21, v21
	v_mul_f32_e32 v6, 0xbfb8aa3b, v6
	v_mul_f32_e32 v7, 0xbfb8aa3b, v7
	v_mul_f32_e32 v8, 0xbfb8aa3b, v8
	v_mul_f32_e32 v9, 0xbfb8aa3b, v9
	v_mul_f32_e32 v2, 0xbfb8aa3b, v2
	v_mul_f32_e32 v3, 0xbfb8aa3b, v3
; #define PG8_WAIT_V(n) asm volatile("s_waitcnt vmcnt(" #n ")" ::: "memory")
; #define PG8_BAR __builtin_amdgcn_s_barrier()
; __device__ __forceinline__ u32x4 pack8(const f32x4 a, const f32x4 b) { u32x4 w; w.x = cvt_pk_bf16(a[0], a[1]); w.y = cvt_pk_bf16(a[2], a[3]); w.z = cvt_pk_bf16(b[0], b[1]); w.w = cvt_pk_bf16(b[2], b[3]); return w; }
; __device__ __forceinline__ void unpack8(const u32x4 w, f32x4& a, f32x4& b) { a = (f32x4){bflo(w.x), bfhi(w.x), bflo(w.y), bfhi(w.y)}; b = (f32x4){bflo(w.z), bfhi(w.z), bflo(w.w), bfhi(w.w)}; }
; __device__ __forceinline__ f32x4 sig4(const f32x4 v) { return (f32x4){sigmoidf_(v[0]), sigmoidf_(v[1]), sigmoidf_(v[2]), sigmoidf_(v[3])}; }
; template <class Epi>
; __device__ __forceinline__ void gemm_phase(LAS unsigned char* lds, const Gemm g, const StaticOrder& S, const Epi& E) {
;     ...
;     PG8_WAIT_V(0);
;     if (wr == 0) PG8_BAR;
;     PG8_BAR;
;     __device__ __forceinline__ void operator()(const Acc& acc, const Unit& u, int wr, int wc, int fr, int fq) const {
;     ...
;             for (int m = 0; m < 4; ++m) { bf16_t* rowp = proj + (size_t)(row0 + ai * 128 + m * 16) * NPROJ + col0;
; #pragma unroll
;                 for (int bj = 0; bj < 2; ++bj) { f32x4 a0, a1; unpack8(av[m][bj], a0, a1);
;                     const f32x4 o0 = a0 * sig4(acc[ai][bj][m][0] + bv[bj][0]), o1 = a1 * sig4(acc[ai][bj][m][1] + bv[bj][1]);
;                     *(u32x4*)(rowp + C_GLU + bj * 128) = pack8(o0, o1); } } }
	v_mul_f32_e32 v4, 0xbfb8aa3b, v4
	v_mul_f32_e32 v5, 0xbfb8aa3b, v5
	v_mad_i64_i32 v[34:35], s[42:43], v113, s96, v[186:187]
	v_pk_mul_f32 v[32:33], v[32:33], v[42:43]
	v_pk_mul_f32 v[30:31], v[30:31], v[36:37]
	v_pk_mul_f32 v[36:37], v[28:29], v[50:51]
	v_pk_mul_f32 v[28:29], v[26:27], v[44:45]
	v_exp_f32_e32 v6, v6
	v_exp_f32_e32 v7, v7
	v_exp_f32_e32 v8, v8
	v_exp_f32_e32 v9, v9
	v_exp_f32_e32 v2, v2
	v_exp_f32_e32 v3, v3
	v_exp_f32_e32 v4, v4
	v_exp_f32_e32 v5, v5
	v_lshl_add_u64 v[34:35], v[34:35], 0, v[184:185]
	v_cvt_pk_bf16_f32 v26, v30, v31
	v_cvt_pk_bf16_f32 v27, v32, v33
	v_cvt_pk_bf16_f32 v28, v28, v29
	v_cvt_pk_bf16_f32 v29, v36, v37
	v_add_f32_e32 v14, 1.0, v14
	v_add_f32_e32 v15, 1.0, v15
	v_add_f32_e32 v16, 1.0, v16
	v_add_f32_e32 v17, 1.0, v17
	v_add_f32_e32 v10, 1.0, v10
	v_add_f32_e32 v11, 1.0, v11
	v_add_f32_e32 v12, 1.0, v12
	v_add_f32_e32 v13, 1.0, v13
	global_store_dwordx4 v[34:35], v[26:29], off offset:1024
	v_lshlrev_b32_e32 v30, 16, v92
	v_and_b32_e32 v31, 0xffff0000, v92
	v_lshlrev_b32_e32 v26, 16, v90
	v_and_b32_e32 v27, 0xffff0000, v90
	v_lshlrev_b32_e32 v28, 16, v91
	v_and_b32_e32 v29, 0xffff0000, v91
	v_lshlrev_b32_e32 v32, 16, v93
	v_and_b32_e32 v33, 0xffff0000, v93
	v_rcp_f32_e32 v14, v14
	v_rcp_f32_e32 v15, v15
	v_rcp_f32_e32 v16, v16
	v_rcp_f32_e32 v17, v17
	v_rcp_f32_e32 v10, v10
	v_rcp_f32_e32 v11, v11
	v_rcp_f32_e32 v12, v12
	v_rcp_f32_e32 v13, v13
	v_pk_mul_f32 v[24:25], v[24:25], v[28:29]
	v_pk_mul_f32 v[22:23], v[22:23], v[26:27]
	v_pk_mul_f32 v[26:27], v[20:21], v[32:33]
	v_pk_mul_f32 v[20:21], v[18:19], v[30:31]
	v_cvt_pk_bf16_f32 v18, v22, v23
	v_cvt_pk_bf16_f32 v19, v24, v25
	v_cvt_pk_bf16_f32 v20, v20, v21
	v_cvt_pk_bf16_f32 v21, v26, v27
	v_add_f32_e32 v6, 1.0, v6
	v_add_f32_e32 v7, 1.0, v7
	v_add_f32_e32 v8, 1.0, v8
	v_add_f32_e32 v9, 1.0, v9
	v_add_f32_e32 v2, 1.0, v2
	v_add_f32_e32 v3, 1.0, v3
	v_add_f32_e32 v4, 1.0, v4
	v_add_f32_e32 v5, 1.0, v5
	global_store_dwordx4 v[34:35], v[18:21], off offset:1280
	v_lshlrev_b32_e32 v22, 16, v87
	v_and_b32_e32 v23, 0xffff0000, v87
	v_lshlrev_b32_e32 v20, 16, v86
	v_and_b32_e32 v21, 0xffff0000, v86
	v_lshlrev_b32_e32 v24, 16, v88
	v_and_b32_e32 v25, 0xffff0000, v88
	v_lshlrev_b32_e32 v26, 16, v89
	v_and_b32_e32 v27, 0xffff0000, v89
	v_rcp_f32_e32 v6, v6
	v_rcp_f32_e32 v7, v7
	v_rcp_f32_e32 v8, v8
	v_rcp_f32_e32 v9, v9
	v_rcp_f32_e32 v2, v2
	v_rcp_f32_e32 v3, v3
	v_rcp_f32_e32 v4, v4
	v_rcp_f32_e32 v5, v5
	v_mad_i64_i32 v[18:19], s[42:43], v112, s96, v[186:187]
	v_pk_mul_f32 v[16:17], v[16:17], v[22:23]
	v_pk_mul_f32 v[14:15], v[14:15], v[20:21]
	v_pk_mul_f32 v[20:21], v[12:13], v[26:27]
	v_pk_mul_f32 v[12:13], v[10:11], v[24:25]
	v_lshl_add_u64 v[18:19], v[18:19], 0, v[184:185]
	v_cvt_pk_bf16_f32 v10, v14, v15
	v_cvt_pk_bf16_f32 v11, v16, v17
	v_cvt_pk_bf16_f32 v12, v12, v13
	v_cvt_pk_bf16_f32 v13, v20, v21
	global_store_dwordx4 v[18:19], v[10:13], off offset:1024
	v_lshlrev_b32_e32 v14, 16, v84
	v_and_b32_e32 v15, 0xffff0000, v84
	v_lshlrev_b32_e32 v10, 16, v82
	v_and_b32_e32 v11, 0xffff0000, v82
	v_lshlrev_b32_e32 v12, 16, v83
	v_and_b32_e32 v13, 0xffff0000, v83
	v_lshlrev_b32_e32 v16, 16, v85
	v_and_b32_e32 v17, 0xffff0000, v85
	v_pk_mul_f32 v[8:9], v[8:9], v[12:13]
	v_pk_mul_f32 v[6:7], v[6:7], v[10:11]
	v_pk_mul_f32 v[10:11], v[4:5], v[16:17]
	v_pk_mul_f32 v[4:5], v[2:3], v[14:15]
	v_cvt_pk_bf16_f32 v2, v6, v7
	v_cvt_pk_bf16_f32 v3, v8, v9
	v_cvt_pk_bf16_f32 v4, v4, v5
	v_cvt_pk_bf16_f32 v5, v10, v11
	global_store_dwordx4 v[18:19], v[2:5], off offset:1280
	s_cbranch_vccz .LBB0_378
	s_waitcnt vmcnt(0)
	s_cmpk_gt_u32 s29, 0xff
	s_cbranch_scc1 .LBB0_391
	s_barrier

; #define PG8_STAGE(bufoff, gbase, voff) do { _Pragma("unroll") for (int _i = 0; _i < 2; ++_i) \
;         __builtin_amdgcn_global_load_lds((const unsigned*)((const char*)(gbase) + (voff)[_i]), (LAS unsigned*)(lds + (bufoff) + ldsw + _i * 8192), 16, 0, 0); } while (0)
; #define PG8_LDA(dst, b, h) do { _Pragma("unroll") for (int m = 0; m < 4; ++m) _Pragma("unroll") for (int k = 0; k < 2; ++k) dst[m][k] = *(const LAS bf16x8*)(lds + PG8_SA(b, h) + aoff + m * 2048 + k * 1024); } while (0)
; #define PG8_LDB(dst, b, h) do { _Pragma("unroll") for (int n = 0; n < 2; ++n) _Pragma("unroll") for (int k = 0; k < 2; ++k) dst[n][k] = *(const LAS bf16x8*)(lds + PG8_SB(b, h) + boff + n * 2048 + k * 1024); } while (0)
; #define PG8_MMA(ai, bj, At, Bt) do { __builtin_amdgcn_s_setprio(1); _Pragma("unroll") for (int m = 0; m < 4; ++m) _Pragma("unroll") for (int n = 0; n < 2; ++n) _Pragma("unroll") for (int k = 0; k < 2; ++k) \
;         acc[ai][bj][m][n] = __builtin_amdgcn_mfma_f32_16x16x32_bf16(Bt[n][k], At[m][k], acc[ai][bj][m][n], 0, 0, 0); __builtin_amdgcn_s_setprio(0); } while (0)
; #define PG8_WAIT_V(n) asm volatile("s_waitcnt vmcnt(" #n ")" ::: "memory")
; #define PG8_WAIT_L(n) asm volatile("s_waitcnt lgkmcnt(" #n ")" ::: "memory")
; #define PG8_BAR __builtin_amdgcn_s_barrier()
; template <class Epi>
; __device__ __forceinline__ void gemm_phase(LAS unsigned char* lds, const Gemm g, const StaticOrder& S, const Epi& E) {
;     ...
;         for (int t = 0; t < nt; t += 2) {
;             const bool last = (t == nt - 2);
;             const char* a1 = cA + (size_t)(t + 1) * kstep;
;             const char* a2 = last ? nA : cA + (size_t)(t + 2) * kstep; const char* b2 = last ? nB : cB + (size_t)(t + 2) * kstep;
;             const char* a3 = a2 + kstep; const char* b3 = b2 + kstep;
;             PG8_LDB(B0, 0, 0); PG8_SCHED; PG8_LDA(At, 0, 0); PG8_STAGE(PG8_SA(1, 1), a1 + hA, voffA);
;             PG8_WAIT_L(8); PG8_BAR; PG8_WAIT_L(0); PG8_MMA(0, 0, At, B0); PG8_BAR; PG8_SCHED;
;             PG8_LDB(B1, 0, 1); PG8_STAGE(PG8_SB(0, 0), b2, voffB);
;             PG8_BAR; PG8_WAIT_L(0); PG8_MMA(0, 1, At, B1); PG8_BAR;
;             PG8_LDA(At, 0, 1); PG8_STAGE(PG8_SA(0, 0), a2, voffA);
;             PG8_BAR; PG8_WAIT_L(0); PG8_MMA(1, 0, At, B0); PG8_BAR; PG8_SCHED;
;             PG8_STAGE(PG8_SB(0, 1), b2 + hB, voffB);
;             PG8_WAIT_V(6); PG8_BAR; PG8_MMA(1, 1, At, B1); PG8_BAR;
.LBB0_623:
	s_add_u32 s48, s46, 0xfffc0080
	s_addc_u32 s49, s47, -1
	s_add_i32 s67, 0, 0x10000
	v_add_u32_e32 v151, s67, v143
	ds_read_b128 v[156:159], v151
	ds_read_b128 v[160:163], v151 offset:1024
	ds_read_b128 v[164:167], v151 offset:2048
	ds_read_b128 v[168:171], v151 offset:3072
	s_cmp_eq_u32 s66, 12
	s_cselect_b32 s51, s23, s49
	s_cselect_b32 s50, s62, s48
	s_cselect_b32 s49, s15, s65
	s_cselect_b32 s48, s63, s64
	s_add_i32 m0, s53, 0xc000
	ds_read_b128 v[172:175], v149
	ds_read_b128 v[176:179], v149 offset:1024
	ds_read_b128 v[180:183], v149 offset:2048
	ds_read_b128 v[184:187], v149 offset:3072
	ds_read_b128 v[188:191], v149 offset:4096
	ds_read_b128 v[192:195], v149 offset:5120
	ds_read_b128 v[202:205], v149 offset:6144
	ds_read_b128 v[206:209], v149 offset:7168
	global_load_lds_dwordx4 v144, s[46:47]
	s_add_i32 m0, s53, 0xe000
	s_nop 0
	global_load_lds_dwordx4 v146, s[46:47]
	s_waitcnt lgkmcnt(8)
	s_barrier
	s_waitcnt lgkmcnt(0)
	s_setprio 1
	v_mfma_f32_16x16x32_bf16 v[126:129], v[156:159], v[172:175], v[126:129]
	v_mfma_f32_16x16x32_bf16 v[122:125], v[164:167], v[172:175], v[122:125]
	v_mfma_f32_16x16x32_bf16 v[118:121], v[156:159], v[180:183], v[118:121]
	v_mfma_f32_16x16x32_bf16 v[110:113], v[164:167], v[180:183], v[110:113]
	v_mfma_f32_16x16x32_bf16 v[102:105], v[156:159], v[188:191], v[102:105]
	v_mfma_f32_16x16x32_bf16 v[94:97], v[164:167], v[188:191], v[94:97]
	v_mfma_f32_16x16x32_bf16 v[86:89], v[156:159], v[202:205], v[86:89]
	v_mfma_f32_16x16x32_bf16 v[78:81], v[164:167], v[202:205], v[78:81]
	v_mfma_f32_16x16x32_bf16 v[126:129], v[160:163], v[176:179], v[126:129]
	v_mfma_f32_16x16x32_bf16 v[122:125], v[168:171], v[176:179], v[122:125]
	v_mfma_f32_16x16x32_bf16 v[118:121], v[160:163], v[184:187], v[118:121]
	v_mfma_f32_16x16x32_bf16 v[110:113], v[168:171], v[184:187], v[110:113]
	v_mfma_f32_16x16x32_bf16 v[102:105], v[160:163], v[192:195], v[102:105]
	v_mfma_f32_16x16x32_bf16 v[94:97], v[168:171], v[192:195], v[94:97]
	v_mfma_f32_16x16x32_bf16 v[86:89], v[160:163], v[206:209], v[86:89]
	v_mfma_f32_16x16x32_bf16 v[78:81], v[168:171], v[206:209], v[78:81]
	s_setprio 0
	s_barrier
	s_add_i32 s70, 0, 0x14000
	s_add_i32 s67, s67, s33
	v_add_u32_e32 v151, s70, v143
	s_mov_b32 m0, s67
	ds_read_b128 v[210:213], v151
	ds_read_b128 v[214:217], v151 offset:1024
	ds_read_b128 v[218:221], v151 offset:2048
	ds_read_b128 v[222:225], v151 offset:3072
	global_load_lds_dwordx4 v0, s[48:49]
	s_add_i32 m0, s67, 0x2000
	s_nop 0
	global_load_lds_dwordx4 v134, s[48:49]
	s_barrier
	s_waitcnt lgkmcnt(0)
	s_setprio 1
	v_mfma_f32_16x16x32_bf16 v[114:117], v[210:213], v[172:175], v[114:117]
	v_mfma_f32_16x16x32_bf16 v[106:109], v[218:221], v[172:175], v[106:109]
	v_mfma_f32_16x16x32_bf16 v[98:101], v[210:213], v[180:183], v[98:101]
	v_mfma_f32_16x16x32_bf16 v[90:93], v[218:221], v[180:183], v[90:93]
	v_mfma_f32_16x16x32_bf16 v[82:85], v[210:213], v[188:191], v[82:85]
	v_mfma_f32_16x16x32_bf16 v[74:77], v[218:221], v[188:191], v[74:77]
	v_mfma_f32_16x16x32_bf16 v[70:73], v[210:213], v[202:205], v[70:73]
	v_mfma_f32_16x16x32_bf16 v[66:69], v[218:221], v[202:205], v[66:69]
	v_mfma_f32_16x16x32_bf16 v[114:117], v[214:217], v[176:179], v[114:117]
	v_mfma_f32_16x16x32_bf16 v[106:109], v[222:225], v[176:179], v[106:109]
	v_mfma_f32_16x16x32_bf16 v[98:101], v[214:217], v[184:187], v[98:101]
	v_mfma_f32_16x16x32_bf16 v[90:93], v[222:225], v[184:187], v[90:93]
	v_mfma_f32_16x16x32_bf16 v[82:85], v[214:217], v[192:195], v[82:85]
	v_mfma_f32_16x16x32_bf16 v[74:77], v[222:225], v[192:195], v[74:77]
	v_mfma_f32_16x16x32_bf16 v[70:73], v[214:217], v[206:209], v[70:73]
	v_mfma_f32_16x16x32_bf16 v[66:69], v[222:225], v[206:209], v[66:69]
	s_setprio 0
	s_mov_b32 m0, s53
	s_barrier
	ds_read_b128 v[172:175], v149 offset:16384
	ds_read_b128 v[176:179], v149 offset:17408
	ds_read_b128 v[180:183], v149 offset:18432
	ds_read_b128 v[184:187], v149 offset:19456
	ds_read_b128 v[188:191], v149 offset:20480
	ds_read_b128 v[192:195], v149 offset:21504
	ds_read_b128 v[202:205], v149 offset:22528
	ds_read_b128 v[206:209], v149 offset:23552
	global_load_lds_dwordx4 v130, s[50:51]
	s_mov_b32 m0, s54
	s_nop 0
	global_load_lds_dwordx4 v132, s[50:51]
	s_barrier
	s_waitcnt lgkmcnt(0)
	s_setprio 1
	v_mfma_f32_16x16x32_bf16 v[62:65], v[156:159], v[172:175], v[62:65]
	v_mfma_f32_16x16x32_bf16 v[58:61], v[164:167], v[172:175], v[58:61]
	v_mfma_f32_16x16x32_bf16 v[54:57], v[156:159], v[180:183], v[54:57]
	v_mfma_f32_16x16x32_bf16 v[46:49], v[164:167], v[180:183], v[46:49]
	v_mfma_f32_16x16x32_bf16 v[38:41], v[156:159], v[188:191], v[38:41]
	v_mfma_f32_16x16x32_bf16 v[30:33], v[164:167], v[188:191], v[30:33]
	v_mfma_f32_16x16x32_bf16 v[22:25], v[156:159], v[202:205], v[22:25]
	v_mfma_f32_16x16x32_bf16 v[14:17], v[164:167], v[202:205], v[14:17]
	v_mfma_f32_16x16x32_bf16 v[62:65], v[160:163], v[176:179], v[62:65]
	v_mfma_f32_16x16x32_bf16 v[58:61], v[168:171], v[176:179], v[58:61]
	v_mfma_f32_16x16x32_bf16 v[54:57], v[160:163], v[184:187], v[54:57]
	v_mfma_f32_16x16x32_bf16 v[46:49], v[168:171], v[184:187], v[46:49]
	v_mfma_f32_16x16x32_bf16 v[38:41], v[160:163], v[192:195], v[38:41]
	v_mfma_f32_16x16x32_bf16 v[30:33], v[168:171], v[192:195], v[30:33]
	v_mfma_f32_16x16x32_bf16 v[22:25], v[160:163], v[206:209], v[22:25]
	v_mfma_f32_16x16x32_bf16 v[14:17], v[168:171], v[206:209], v[14:17]
	s_setprio 0
	s_barrier
	s_add_u32 s68, s48, 0x40000
	s_addc_u32 s69, s49, 0
	s_add_i32 s67, s70, s33
	s_mov_b32 m0, s67
	s_nop 0
	global_load_lds_dwordx4 v0, s[68:69]
	s_add_i32 m0, s67, 0x2000
	s_nop 0
	global_load_lds_dwordx4 v134, s[68:69]
	s_waitcnt vmcnt(6)
	s_barrier
; #define PG8_STAGE(bufoff, gbase, voff) do { _Pragma("unroll") for (int _i = 0; _i < 2; ++_i) \
;         __builtin_amdgcn_global_load_lds((const unsigned*)((const char*)(gbase) + (voff)[_i]), (LAS unsigned*)(lds + (bufoff) + ldsw + _i * 8192), 16, 0, 0); } while (0)
; #define PG8_LDA(dst, b, h) do { _Pragma("unroll") for (int m = 0; m < 4; ++m) _Pragma("unroll") for (int k = 0; k < 2; ++k) dst[m][k] = *(const LAS bf16x8*)(lds + PG8_SA(b, h) + aoff + m * 2048 + k * 1024); } while (0)
; #define PG8_LDB(dst, b, h) do { _Pragma("unroll") for (int n = 0; n < 2; ++n) _Pragma("unroll") for (int k = 0; k < 2; ++k) dst[n][k] = *(const LAS bf16x8*)(lds + PG8_SB(b, h) + boff + n * 2048 + k * 1024); } while (0)
; #define PG8_MMA(ai, bj, At, Bt) do { __builtin_amdgcn_s_setprio(1); _Pragma("unroll") for (int m = 0; m < 4; ++m) _Pragma("unroll") for (int n = 0; n < 2; ++n) _Pragma("unroll") for (int k = 0; k < 2; ++k) \
;         acc[ai][bj][m][n] = __builtin_amdgcn_mfma_f32_16x16x32_bf16(Bt[n][k], At[m][k], acc[ai][bj][m][n], 0, 0, 0); __builtin_amdgcn_s_setprio(0); } while (0)
; #define PG8_WAIT_V(n) asm volatile("s_waitcnt vmcnt(" #n ")" ::: "memory")
; #define PG8_WAIT_L(n) asm volatile("s_waitcnt lgkmcnt(" #n ")" ::: "memory")
; #define PG8_BAR __builtin_amdgcn_s_barrier()
; #define PG8_SCHED __builtin_amdgcn_sched_barrier(0)
; template <class Epi>
; __device__ __forceinline__ void gemm_phase(LAS unsigned char* lds, const Gemm g, const StaticOrder& S, const Epi& E) {
;     ...
;             PG8_WAIT_V(6); PG8_BAR; PG8_MMA(1, 1, At, B1); PG8_BAR;
;             PG8_LDB(B0, 1, 0); PG8_SCHED; PG8_LDA(At, 1, 0); PG8_STAGE(PG8_SA(0, 1), a2 + hA, voffA);
;             PG8_WAIT_L(8); PG8_BAR; PG8_WAIT_L(0); PG8_MMA(0, 0, At, B0); PG8_BAR; PG8_SCHED;
;             PG8_LDB(B1, 1, 1); PG8_STAGE(PG8_SB(1, 0), b3, voffB);
;             PG8_BAR; PG8_WAIT_L(0); PG8_MMA(0, 1, At, B1); PG8_BAR;
;             PG8_LDA(At, 1, 1); PG8_STAGE(PG8_SA(1, 0), a3, voffA);
;             PG8_BAR; PG8_WAIT_L(0); PG8_MMA(1, 0, At, B0); PG8_BAR; PG8_SCHED;
	s_setprio 1
	v_mfma_f32_16x16x32_bf16 v[50:53], v[210:213], v[172:175], v[50:53]
	v_mfma_f32_16x16x32_bf16 v[42:45], v[218:221], v[172:175], v[42:45]
	v_mfma_f32_16x16x32_bf16 v[34:37], v[210:213], v[180:183], v[34:37]
	v_mfma_f32_16x16x32_bf16 v[26:29], v[218:221], v[180:183], v[26:29]
	v_mfma_f32_16x16x32_bf16 v[18:21], v[210:213], v[188:191], v[18:21]
	v_mfma_f32_16x16x32_bf16 v[10:13], v[218:221], v[188:191], v[10:13]
	v_mfma_f32_16x16x32_bf16 v[6:9], v[210:213], v[202:205], v[6:9]
	v_mfma_f32_16x16x32_bf16 v[2:5], v[218:221], v[202:205], v[2:5]
	v_mfma_f32_16x16x32_bf16 v[50:53], v[214:217], v[176:179], v[50:53]
	v_mfma_f32_16x16x32_bf16 v[42:45], v[222:225], v[176:179], v[42:45]
	v_mfma_f32_16x16x32_bf16 v[34:37], v[214:217], v[184:187], v[34:37]
	v_mfma_f32_16x16x32_bf16 v[26:29], v[222:225], v[184:187], v[26:29]
	v_mfma_f32_16x16x32_bf16 v[18:21], v[214:217], v[192:195], v[18:21]
	v_mfma_f32_16x16x32_bf16 v[10:13], v[222:225], v[192:195], v[10:13]
	v_mfma_f32_16x16x32_bf16 v[6:9], v[214:217], v[206:209], v[6:9]
	v_mfma_f32_16x16x32_bf16 v[2:5], v[222:225], v[206:209], v[2:5]
	s_setprio 0
	s_add_i32 s67, 0, 0x18000
	v_add_u32_e32 v151, s67, v143
	s_barrier
	ds_read_b128 v[156:159], v151
	ds_read_b128 v[160:163], v151 offset:1024
	ds_read_b128 v[164:167], v151 offset:2048
	ds_read_b128 v[168:171], v151 offset:3072
	s_add_u32 s68, s50, 0x40000
	s_addc_u32 s69, s51, 0
	s_mov_b32 m0, s55
	ds_read_b128 v[172:175], v149 offset:32768
	ds_read_b128 v[176:179], v149 offset:33792
	ds_read_b128 v[180:183], v149 offset:34816
	ds_read_b128 v[184:187], v149 offset:35840
	ds_read_b128 v[188:191], v149 offset:36864
	ds_read_b128 v[192:195], v149 offset:37888
	ds_read_b128 v[202:205], v149 offset:38912
	ds_read_b128 v[206:209], v149 offset:39936
	global_load_lds_dwordx4 v130, s[68:69]
	s_mov_b32 m0, s56
	s_nop 0
	global_load_lds_dwordx4 v132, s[68:69]
	s_waitcnt lgkmcnt(8)
	s_barrier
	s_waitcnt lgkmcnt(0)
	s_setprio 1
	v_mfma_f32_16x16x32_bf16 v[126:129], v[156:159], v[172:175], v[126:129]
	v_mfma_f32_16x16x32_bf16 v[122:125], v[164:167], v[172:175], v[122:125]
	v_mfma_f32_16x16x32_bf16 v[118:121], v[156:159], v[180:183], v[118:121]
	v_mfma_f32_16x16x32_bf16 v[110:113], v[164:167], v[180:183], v[110:113]
	v_mfma_f32_16x16x32_bf16 v[102:105], v[156:159], v[188:191], v[102:105]
	v_mfma_f32_16x16x32_bf16 v[94:97], v[164:167], v[188:191], v[94:97]
	v_mfma_f32_16x16x32_bf16 v[86:89], v[156:159], v[202:205], v[86:89]
	v_mfma_f32_16x16x32_bf16 v[78:81], v[164:167], v[202:205], v[78:81]
	v_mfma_f32_16x16x32_bf16 v[126:129], v[160:163], v[176:179], v[126:129]
	v_mfma_f32_16x16x32_bf16 v[122:125], v[168:171], v[176:179], v[122:125]
	v_mfma_f32_16x16x32_bf16 v[118:121], v[160:163], v[184:187], v[118:121]
	v_mfma_f32_16x16x32_bf16 v[110:113], v[168:171], v[184:187], v[110:113]
	v_mfma_f32_16x16x32_bf16 v[102:105], v[160:163], v[192:195], v[102:105]
	v_mfma_f32_16x16x32_bf16 v[94:97], v[168:171], v[192:195], v[94:97]
	v_mfma_f32_16x16x32_bf16 v[86:89], v[160:163], v[206:209], v[86:89]
	v_mfma_f32_16x16x32_bf16 v[78:81], v[168:171], v[206:209], v[78:81]
	s_setprio 0
	s_barrier
	s_add_i32 s100, 0, 0x1c000
	s_add_i32 s101, s67, s33
	v_add_u32_e32 v151, s100, v143
	s_add_u32 s68, s48, 0x80
	s_addc_u32 s69, s49, 0
	s_mov_b32 m0, s101
	ds_read_b128 v[210:213], v151
	ds_read_b128 v[214:217], v151 offset:1024
	ds_read_b128 v[218:221], v151 offset:2048
	ds_read_b128 v[222:225], v151 offset:3072
	global_load_lds_dwordx4 v0, s[68:69]
	s_add_i32 m0, s101, 0x2000
	s_nop 0
	global_load_lds_dwordx4 v134, s[68:69]
	s_barrier
	s_waitcnt lgkmcnt(0)
	s_setprio 1
	v_mfma_f32_16x16x32_bf16 v[114:117], v[210:213], v[172:175], v[114:117]
	v_mfma_f32_16x16x32_bf16 v[106:109], v[218:221], v[172:175], v[106:109]
	v_mfma_f32_16x16x32_bf16 v[98:101], v[210:213], v[180:183], v[98:101]
	v_mfma_f32_16x16x32_bf16 v[90:93], v[218:221], v[180:183], v[90:93]
	v_mfma_f32_16x16x32_bf16 v[82:85], v[210:213], v[188:191], v[82:85]
	v_mfma_f32_16x16x32_bf16 v[74:77], v[218:221], v[188:191], v[74:77]
	v_mfma_f32_16x16x32_bf16 v[70:73], v[210:213], v[202:205], v[70:73]
	v_mfma_f32_16x16x32_bf16 v[66:69], v[218:221], v[202:205], v[66:69]
	v_mfma_f32_16x16x32_bf16 v[114:117], v[214:217], v[176:179], v[114:117]
	v_mfma_f32_16x16x32_bf16 v[106:109], v[222:225], v[176:179], v[106:109]
	v_mfma_f32_16x16x32_bf16 v[98:101], v[214:217], v[184:187], v[98:101]
	v_mfma_f32_16x16x32_bf16 v[90:93], v[222:225], v[184:187], v[90:93]
	v_mfma_f32_16x16x32_bf16 v[82:85], v[214:217], v[192:195], v[82:85]
	v_mfma_f32_16x16x32_bf16 v[74:77], v[222:225], v[192:195], v[74:77]
	v_mfma_f32_16x16x32_bf16 v[70:73], v[214:217], v[206:209], v[70:73]
	v_mfma_f32_16x16x32_bf16 v[66:69], v[222:225], v[206:209], v[66:69]
	s_setprio 0
	s_mov_b32 m0, s58
	s_add_u32 s68, s50, 0x80
	s_addc_u32 s69, s51, 0
	s_barrier
	ds_read_b128 v[172:175], v149 offset:49152
	ds_read_b128 v[176:179], v149 offset:50176
	ds_read_b128 v[180:183], v149 offset:51200
	ds_read_b128 v[184:187], v149 offset:52224
	ds_read_b128 v[188:191], v149 offset:53248
	ds_read_b128 v[192:195], v149 offset:54272
	ds_read_b128 v[202:205], v149 offset:55296
	ds_read_b128 v[206:209], v149 offset:56320
	global_load_lds_dwordx4 v130, s[68:69]
	s_mov_b32 m0, s59
	s_nop 0
	global_load_lds_dwordx4 v132, s[68:69]
	s_barrier
; #define PG8_STAGE(bufoff, gbase, voff) do { _Pragma("unroll") for (int _i = 0; _i < 2; ++_i) \
;         __builtin_amdgcn_global_load_lds((const unsigned*)((const char*)(gbase) + (voff)[_i]), (LAS unsigned*)(lds + (bufoff) + ldsw + _i * 8192), 16, 0, 0); } while (0)
; #define PG8_MMA(ai, bj, At, Bt) do { __builtin_amdgcn_s_setprio(1); _Pragma("unroll") for (int m = 0; m < 4; ++m) _Pragma("unroll") for (int n = 0; n < 2; ++n) _Pragma("unroll") for (int k = 0; k < 2; ++k) \
;         acc[ai][bj][m][n] = __builtin_amdgcn_mfma_f32_16x16x32_bf16(Bt[n][k], At[m][k], acc[ai][bj][m][n], 0, 0, 0); __builtin_amdgcn_s_setprio(0); } while (0)
; #define PG8_WAIT_V(n) asm volatile("s_waitcnt vmcnt(" #n ")" ::: "memory")
; #define PG8_WAIT_L(n) asm volatile("s_waitcnt lgkmcnt(" #n ")" ::: "memory")
; #define PG8_BAR __builtin_amdgcn_s_barrier()
; #define PG8_SCHED __builtin_amdgcn_sched_barrier(0)
; __device__ __forceinline__ u32x4 pack8(const f32x4 a, const f32x4 b) { u32x4 w; w.x = cvt_pk_bf16(a[0], a[1]); w.y = cvt_pk_bf16(a[2], a[3]); w.z = cvt_pk_bf16(b[0], b[1]); w.w = cvt_pk_bf16(b[2], b[3]); return w; }
; template <class Epi>
; __device__ __forceinline__ void gemm_phase(LAS unsigned char* lds, const Gemm g, const StaticOrder& S, const Epi& E) {
;     ...
;             PG8_BAR; PG8_WAIT_L(0); PG8_MMA(1, 0, At, B0); PG8_BAR; PG8_SCHED;
;             PG8_STAGE(PG8_SB(1, 1), b3 + hB, voffB);
;             PG8_WAIT_V(6); PG8_BAR; PG8_MMA(1, 1, At, B1); PG8_BAR;
;         }
;     __device__ __forceinline__ void operator()(const Acc& acc, const Unit& u, int wr, int wc, int fr, int fq, const RsPre& pr) const {
;         asm volatile("" : "+v"(fr), "+v"(fq));
;         const int row0 = u.pm * 256 + wr * 64 + fr, col0 = u.pn * 256 + wc * 32 + 8 * fq;
;         const float (&rs)[2][4] = pr.rs;
; #pragma unroll
;         for (int ai = 0; ai < 2; ++ai)
; #pragma unroll
;             for (int m = 0; m < 4; ++m) { bf16_t* rowp = O + (size_t)(row0 + ai * 128 + m * 16) * ldc + col0;
; #pragma unroll
;                 for (int bj = 0; bj < 2; ++bj) *(u32x4*)(rowp + bj * 128) = pack8(acc[ai][bj][m][0] * rs[ai][m], acc[ai][bj][m][1] * rs[ai][m]); }
	s_waitcnt lgkmcnt(0)
	s_setprio 1
	v_mfma_f32_16x16x32_bf16 v[62:65], v[156:159], v[172:175], v[62:65]
	v_mfma_f32_16x16x32_bf16 v[58:61], v[164:167], v[172:175], v[58:61]
	v_mfma_f32_16x16x32_bf16 v[54:57], v[156:159], v[180:183], v[54:57]
	v_mfma_f32_16x16x32_bf16 v[46:49], v[164:167], v[180:183], v[46:49]
	v_mfma_f32_16x16x32_bf16 v[38:41], v[156:159], v[188:191], v[38:41]
	v_mfma_f32_16x16x32_bf16 v[30:33], v[164:167], v[188:191], v[30:33]
	v_mfma_f32_16x16x32_bf16 v[22:25], v[156:159], v[202:205], v[22:25]
	v_mfma_f32_16x16x32_bf16 v[14:17], v[164:167], v[202:205], v[14:17]
	v_mfma_f32_16x16x32_bf16 v[62:65], v[160:163], v[176:179], v[62:65]
	v_mfma_f32_16x16x32_bf16 v[58:61], v[168:171], v[176:179], v[58:61]
	v_mfma_f32_16x16x32_bf16 v[54:57], v[160:163], v[184:187], v[54:57]
	v_mfma_f32_16x16x32_bf16 v[46:49], v[168:171], v[184:187], v[46:49]
	v_mfma_f32_16x16x32_bf16 v[38:41], v[160:163], v[192:195], v[38:41]
	v_mfma_f32_16x16x32_bf16 v[30:33], v[168:171], v[192:195], v[30:33]
	v_mfma_f32_16x16x32_bf16 v[22:25], v[160:163], v[206:209], v[22:25]
	v_mfma_f32_16x16x32_bf16 v[14:17], v[168:171], v[206:209], v[14:17]
	s_setprio 0
	s_barrier
	s_add_u32 s48, s48, 0x40080
	s_addc_u32 s49, s49, 0
	s_add_i32 s100, s100, s33
	s_mov_b32 m0, s100
	s_nop 0
	global_load_lds_dwordx4 v0, s[48:49]
	s_add_i32 m0, s100, 0x2000
	s_nop 0
	global_load_lds_dwordx4 v134, s[48:49]
	s_waitcnt vmcnt(6)
	s_barrier
	s_setprio 1
	v_mfma_f32_16x16x32_bf16 v[50:53], v[210:213], v[172:175], v[50:53]
	v_mfma_f32_16x16x32_bf16 v[42:45], v[218:221], v[172:175], v[42:45]
	v_mfma_f32_16x16x32_bf16 v[34:37], v[210:213], v[180:183], v[34:37]
	v_mfma_f32_16x16x32_bf16 v[26:29], v[218:221], v[180:183], v[26:29]
	v_mfma_f32_16x16x32_bf16 v[18:21], v[210:213], v[188:191], v[18:21]
	v_mfma_f32_16x16x32_bf16 v[10:13], v[218:221], v[188:191], v[10:13]
	v_mfma_f32_16x16x32_bf16 v[6:9], v[210:213], v[202:205], v[6:9]
	v_mfma_f32_16x16x32_bf16 v[2:5], v[218:221], v[202:205], v[2:5]
	v_mfma_f32_16x16x32_bf16 v[50:53], v[214:217], v[176:179], v[50:53]
	v_mfma_f32_16x16x32_bf16 v[42:45], v[222:225], v[176:179], v[42:45]
	v_mfma_f32_16x16x32_bf16 v[34:37], v[214:217], v[184:187], v[34:37]
	v_mfma_f32_16x16x32_bf16 v[26:29], v[222:225], v[184:187], v[26:29]
	v_mfma_f32_16x16x32_bf16 v[18:21], v[214:217], v[192:195], v[18:21]
	v_mfma_f32_16x16x32_bf16 v[10:13], v[222:225], v[192:195], v[10:13]
	v_mfma_f32_16x16x32_bf16 v[6:9], v[214:217], v[206:209], v[6:9]
	v_mfma_f32_16x16x32_bf16 v[2:5], v[222:225], v[206:209], v[2:5]
	s_setprio 0
	s_add_i32 s66, s66, 2
	s_add_u32 s46, s46, 0x100
	s_addc_u32 s47, s47, 0
	s_add_u32 s64, s64, 0x100
	s_addc_u32 s65, s65, 0
	s_cmp_gt_u32 s66, 13
	s_barrier
	s_cbranch_scc0 .LBB0_623
	v_mov_b32_e32 v151, v137
	v_mov_b32_e32 v153, v139
	s_lshl_b32 s15, s44, 8
	s_add_i32 s15, s15, s52
	v_add_u32_e32 v151, s15, v151
	s_lshl_b32 s15, s45, 8
	s_or_b32 s15, s15, s57
	v_lshl_add_u32 v158, v153, 3, s15
	v_lshlrev_b32_e32 v158, 1, v158
	v_mad_u32_u24 v160, v151, s96, v158
	s_waitcnt vmcnt(0)
	v_pk_mul_f32 v[128:129], v[154:155], v[128:129] op_sel_hi:[0,1]
	v_pk_mul_f32 v[126:127], v[154:155], v[126:127] op_sel_hi:[0,1]
	v_pk_mul_f32 v[162:163], v[154:155], v[124:125] op_sel_hi:[0,1]
	v_pk_mul_f32 v[124:125], v[154:155], v[122:123] op_sel_hi:[0,1]
	v_cvt_pk_bf16_f32 v122, v126, v127
	v_cvt_pk_bf16_f32 v123, v128, v129
	v_cvt_pk_bf16_f32 v124, v124, v125
	v_cvt_pk_bf16_f32 v125, v162, v163
	global_store_dwordx4 v160, v[122:125], s[20:21]
	v_pk_mul_f32 v[116:117], v[154:155], v[116:117] op_sel_hi:[0,1]
	v_pk_mul_f32 v[114:115], v[154:155], v[114:115] op_sel_hi:[0,1]
	v_pk_mul_f32 v[122:123], v[154:155], v[108:109] op_sel_hi:[0,1]
	v_pk_mul_f32 v[108:109], v[154:155], v[106:107] op_sel_hi:[0,1]
	v_cvt_pk_bf16_f32 v106, v114, v115
	v_cvt_pk_bf16_f32 v107, v116, v117
	v_cvt_pk_bf16_f32 v108, v108, v109
	v_cvt_pk_bf16_f32 v109, v122, v123
	global_store_dwordx4 v160, v[106:109], s[20:21] offset:256
	v_pk_mul_f32 v[112:113], v[152:153], v[112:113] op_sel_hi:[0,1]
	v_pk_mul_f32 v[110:111], v[152:153], v[110:111] op_sel_hi:[0,1]
	v_add_u32_e32 v114, 0x22000, v160
	v_pk_mul_f32 v[108:109], v[152:153], v[120:121] op_sel_hi:[0,1]
	v_pk_mul_f32 v[106:107], v[152:153], v[118:119] op_sel_hi:[0,1]
	v_cvt_pk_bf16_f32 v106, v106, v107
	v_cvt_pk_bf16_f32 v107, v108, v109
	v_cvt_pk_bf16_f32 v108, v110, v111
	v_cvt_pk_bf16_f32 v109, v112, v113
	global_store_dwordx4 v114, v[106:109], s[20:21]
	v_pk_mul_f32 v[100:101], v[152:153], v[100:101] op_sel_hi:[0,1]
	v_pk_mul_f32 v[98:99], v[152:153], v[98:99] op_sel_hi:[0,1]
	v_pk_mul_f32 v[106:107], v[152:153], v[92:93] op_sel_hi:[0,1]
	v_pk_mul_f32 v[92:93], v[152:153], v[90:91] op_sel_hi:[0,1]
	v_cvt_pk_bf16_f32 v90, v98, v99
	v_cvt_pk_bf16_f32 v91, v100, v101
	v_cvt_pk_bf16_f32 v92, v92, v93
	v_cvt_pk_bf16_f32 v93, v106, v107
	global_store_dwordx4 v114, v[90:93], s[20:21] offset:256
	v_pk_mul_f32 v[96:97], v[150:151], v[96:97] op_sel_hi:[0,1]
	v_pk_mul_f32 v[94:95], v[150:151], v[94:95] op_sel_hi:[0,1]
	v_add_u32_e32 v98, 0x44000, v160
	v_pk_mul_f32 v[92:93], v[150:151], v[104:105] op_sel_hi:[0,1]
	v_pk_mul_f32 v[90:91], v[150:151], v[102:103] op_sel_hi:[0,1]
	v_cvt_pk_bf16_f32 v90, v90, v91
	v_cvt_pk_bf16_f32 v91, v92, v93
	v_cvt_pk_bf16_f32 v92, v94, v95
	v_cvt_pk_bf16_f32 v93, v96, v97
	global_store_dwordx4 v98, v[90:93], s[20:21]
	v_pk_mul_f32 v[84:85], v[150:151], v[84:85] op_sel_hi:[0,1]
; __device__ __forceinline__ u32x4 pack8(const f32x4 a, const f32x4 b) { u32x4 w; w.x = cvt_pk_bf16(a[0], a[1]); w.y = cvt_pk_bf16(a[2], a[3]); w.z = cvt_pk_bf16(b[0], b[1]); w.w = cvt_pk_bf16(b[2], b[3]); return w; }
;     __device__ __forceinline__ void pre(RsPre& r, const Unit& u, int wr, int fr) const {
; #pragma unroll
;         for (int ai = 0; ai < 2; ++ai)
; #pragma unroll
;             for (int m = 0; m < 4; ++m) r.rs[ai][m] = rsv[u.pm * 256 + wr * 64 + fr + ai * 128 + m * 16]; }
;     __device__ __forceinline__ void operator()(const Acc& acc, const Unit& u, int wr, int wc, int fr, int fq, const RsPre& pr) const {
;     ...
;         for (int ai = 0; ai < 2; ++ai)
; #pragma unroll
;             for (int m = 0; m < 4; ++m) { bf16_t* rowp = O + (size_t)(row0 + ai * 128 + m * 16) * ldc + col0;
; #pragma unroll
;                 for (int bj = 0; bj < 2; ++bj) *(u32x4*)(rowp + bj * 128) = pack8(acc[ai][bj][m][0] * rs[ai][m], acc[ai][bj][m][1] * rs[ai][m]); }
	v_pk_mul_f32 v[82:83], v[150:151], v[82:83] op_sel_hi:[0,1]
	v_pk_mul_f32 v[90:91], v[150:151], v[76:77] op_sel_hi:[0,1]
	v_pk_mul_f32 v[76:77], v[150:151], v[74:75] op_sel_hi:[0,1]
	v_cvt_pk_bf16_f32 v74, v82, v83
	v_cvt_pk_bf16_f32 v75, v84, v85
	v_cvt_pk_bf16_f32 v76, v76, v77
	v_cvt_pk_bf16_f32 v77, v90, v91
	global_store_dwordx4 v98, v[74:77], s[20:21] offset:256
	v_pk_mul_f32 v[80:81], v[148:149], v[80:81] op_sel_hi:[0,1]
	v_pk_mul_f32 v[78:79], v[148:149], v[78:79] op_sel_hi:[0,1]
	v_add_u32_e32 v82, 0x66000, v160
	v_pk_mul_f32 v[76:77], v[148:149], v[88:89] op_sel_hi:[0,1]
	v_pk_mul_f32 v[74:75], v[148:149], v[86:87] op_sel_hi:[0,1]
	v_cvt_pk_bf16_f32 v74, v74, v75
	v_cvt_pk_bf16_f32 v75, v76, v77
	v_cvt_pk_bf16_f32 v76, v78, v79
	v_cvt_pk_bf16_f32 v77, v80, v81
	global_store_dwordx4 v82, v[74:77], s[20:21]
	v_pk_mul_f32 v[72:73], v[148:149], v[72:73] op_sel_hi:[0,1]
	v_pk_mul_f32 v[70:71], v[148:149], v[70:71] op_sel_hi:[0,1]
	v_pk_mul_f32 v[74:75], v[148:149], v[68:69] op_sel_hi:[0,1]
	v_pk_mul_f32 v[68:69], v[148:149], v[66:67] op_sel_hi:[0,1]
	v_cvt_pk_bf16_f32 v66, v70, v71
	v_cvt_pk_bf16_f32 v67, v72, v73
	v_cvt_pk_bf16_f32 v68, v68, v69
	v_cvt_pk_bf16_f32 v69, v74, v75
	global_store_dwordx4 v82, v[66:69], s[20:21] offset:256
	v_pk_mul_f32 v[64:65], v[142:143], v[64:65] op_sel_hi:[0,1]
	v_pk_mul_f32 v[62:63], v[142:143], v[62:63] op_sel_hi:[0,1]
	v_pk_mul_f32 v[68:69], v[142:143], v[60:61] op_sel_hi:[0,1]
	v_pk_mul_f32 v[60:61], v[142:143], v[58:59] op_sel_hi:[0,1]
	v_add_u32_e32 v66, 0x110000, v160
	v_cvt_pk_bf16_f32 v58, v62, v63
	v_cvt_pk_bf16_f32 v59, v64, v65
	v_cvt_pk_bf16_f32 v60, v60, v61
	v_cvt_pk_bf16_f32 v61, v68, v69
	global_store_dwordx4 v66, v[58:61], s[20:21]
	v_pk_mul_f32 v[52:53], v[142:143], v[52:53] op_sel_hi:[0,1]
	v_pk_mul_f32 v[50:51], v[142:143], v[50:51] op_sel_hi:[0,1]
	v_pk_mul_f32 v[58:59], v[142:143], v[44:45] op_sel_hi:[0,1]
	v_pk_mul_f32 v[44:45], v[142:143], v[42:43] op_sel_hi:[0,1]
	v_cvt_pk_bf16_f32 v42, v50, v51
	v_cvt_pk_bf16_f32 v43, v52, v53
	v_cvt_pk_bf16_f32 v44, v44, v45
	v_cvt_pk_bf16_f32 v45, v58, v59
	global_store_dwordx4 v66, v[42:45], s[20:21] offset:256
	v_pk_mul_f32 v[48:49], v[140:141], v[48:49] op_sel_hi:[0,1]
	v_pk_mul_f32 v[46:47], v[140:141], v[46:47] op_sel_hi:[0,1]
	v_add_u32_e32 v50, 0x132000, v160
	v_pk_mul_f32 v[44:45], v[140:141], v[56:57] op_sel_hi:[0,1]
	v_pk_mul_f32 v[42:43], v[140:141], v[54:55] op_sel_hi:[0,1]
	v_cvt_pk_bf16_f32 v42, v42, v43
	v_cvt_pk_bf16_f32 v43, v44, v45
	v_cvt_pk_bf16_f32 v44, v46, v47
	v_cvt_pk_bf16_f32 v45, v48, v49
	global_store_dwordx4 v50, v[42:45], s[20:21]
	v_pk_mul_f32 v[36:37], v[140:141], v[36:37] op_sel_hi:[0,1]
	v_pk_mul_f32 v[34:35], v[140:141], v[34:35] op_sel_hi:[0,1]
	v_pk_mul_f32 v[42:43], v[140:141], v[28:29] op_sel_hi:[0,1]
	v_pk_mul_f32 v[28:29], v[140:141], v[26:27] op_sel_hi:[0,1]
	v_cvt_pk_bf16_f32 v26, v34, v35
	v_cvt_pk_bf16_f32 v27, v36, v37
	v_cvt_pk_bf16_f32 v28, v28, v29
	v_cvt_pk_bf16_f32 v29, v42, v43
	global_store_dwordx4 v50, v[26:29], s[20:21] offset:256
	v_pk_mul_f32 v[32:33], v[138:139], v[32:33] op_sel_hi:[0,1]
	v_pk_mul_f32 v[30:31], v[138:139], v[30:31] op_sel_hi:[0,1]
	v_add_u32_e32 v34, 0x154000, v160
	v_pk_mul_f32 v[28:29], v[138:139], v[40:41] op_sel_hi:[0,1]
	v_pk_mul_f32 v[26:27], v[138:139], v[38:39] op_sel_hi:[0,1]
	v_cvt_pk_bf16_f32 v26, v26, v27
	v_cvt_pk_bf16_f32 v27, v28, v29
	v_cvt_pk_bf16_f32 v28, v30, v31
	v_cvt_pk_bf16_f32 v29, v32, v33
	global_store_dwordx4 v34, v[26:29], s[20:21]
	v_pk_mul_f32 v[20:21], v[138:139], v[20:21] op_sel_hi:[0,1]
	v_pk_mul_f32 v[18:19], v[138:139], v[18:19] op_sel_hi:[0,1]
	v_pk_mul_f32 v[26:27], v[138:139], v[12:13] op_sel_hi:[0,1]
	v_pk_mul_f32 v[12:13], v[138:139], v[10:11] op_sel_hi:[0,1]
	v_cvt_pk_bf16_f32 v10, v18, v19
	v_cvt_pk_bf16_f32 v11, v20, v21
	v_cvt_pk_bf16_f32 v12, v12, v13
	v_cvt_pk_bf16_f32 v13, v26, v27
	global_store_dwordx4 v34, v[10:13], s[20:21] offset:256
	v_pk_mul_f32 v[16:17], v[136:137], v[16:17] op_sel_hi:[0,1]
	v_pk_mul_f32 v[14:15], v[136:137], v[14:15] op_sel_hi:[0,1]
	v_add_u32_e32 v18, 0x176000, v160
	v_pk_mul_f32 v[12:13], v[136:137], v[24:25] op_sel_hi:[0,1]
	v_pk_mul_f32 v[10:11], v[136:137], v[22:23] op_sel_hi:[0,1]
	v_cvt_pk_bf16_f32 v10, v10, v11
	v_cvt_pk_bf16_f32 v11, v12, v13
	v_cvt_pk_bf16_f32 v12, v14, v15
	v_cvt_pk_bf16_f32 v13, v16, v17
	global_store_dwordx4 v18, v[10:13], s[20:21]
	v_pk_mul_f32 v[8:9], v[136:137], v[8:9] op_sel_hi:[0,1]
	v_pk_mul_f32 v[6:7], v[136:137], v[6:7] op_sel_hi:[0,1]
	v_pk_mul_f32 v[10:11], v[136:137], v[4:5] op_sel_hi:[0,1]
	v_pk_mul_f32 v[4:5], v[136:137], v[2:3] op_sel_hi:[0,1]
	v_cvt_pk_bf16_f32 v2, v6, v7
	v_cvt_pk_bf16_f32 v3, v8, v9
	v_cvt_pk_bf16_f32 v4, v4, v5
	v_cvt_pk_bf16_f32 v5, v10, v11
	s_mov_b64 s[44:45], -1
	s_and_b64 vcc, vcc, exec
	global_store_dwordx4 v18, v[2:5], s[20:21] offset:256
	s_cbranch_vccz .LBB0_615
	s_nop 0
	v_lshl_add_u32 v2, s22, 8, v141
	v_ashrrev_i32_e32 v3, 31, v2
	v_lshl_add_u64 v[2:3], v[2:3], 2, s[10:11]
	global_load_dword v154, v[2:3], off
	global_load_dword v152, v[2:3], off offset:64
	global_load_dword v150, v[2:3], off offset:128
	global_load_dword v148, v[2:3], off offset:192
	global_load_dword v142, v[2:3], off offset:512
	global_load_dword v140, v[2:3], off offset:576
	global_load_dword v138, v[2:3], off offset:640
	global_load_dword v136, v[2:3], off offset:704
	s_mov_b64 s[44:45], 0
	s_branch .LBB0_615
